# scan chunk fully unrolled (16 steps, immediate LDS offsets, no per-step address updates or loop control) on top of tail-fix version
# speedup vs baseline: 1.0175x; 1.0038x over previous
; #define SB __builtin_amdgcn_sched_barrier(0)
; #define CMP(G, c8) { CMP1(G, 0, 2 * (c8)) CMP1(G, 1, 2 * (c8) + 1) }
; __device__ __forceinline__ void phase_scan(const Args& a, unsigned char* lds) {
;     ...
;                 if (it >= 1 && it <= nch) {
;                     const int c = it - 1, buf = c & 1;
;                     const float* vb = vec + (size_t)((buf * 2 + hd) * 16) * 384 + cb;
;                     float* yb = ybuf + ((buf * 2 + hd) * 16) * 64;
;     ...
;                     f32x4 KA[8];
; #pragma unroll
;                     for (int j = 0; j < 8; ++j) KA[j] = *(const f32x4*)(vb + 256 + 4 * j);
; #pragma nounroll
;                     for (int s = 0; s < 16; ++s) {
;                         const float* vs = vb + s * 384;
;                         const float vi = vs[128 - cb + srow];
;                         f32x4 G0[8], G1[8], G2[8];
;                         LDG(G0, 0) SB;
;                         LDG(G1, 1) SB;
;                         f32x2 c0 = {0.f, 0.f}, c1 = {0.f, 0.f};
; #pragma unroll
;                         for (int j = 0; j < 8; ++j) { c0 += S2[2 * j] * (f32x2){KA[j][0], KA[j][1]}; c1 += S2[2 * j + 1] * (f32x2){KA[j][2], KA[j][3]}; }
;                         float cs = (c0.x + c0.y) + (c1.x + c1.y);
;                         cs += dpp_f(cs, 0);
;                         const float sa = -cs;
;                         const f32x2 sa2 = {sa, sa}, v2 = {vi, vi};
;                         f32x2 y0 = {0.f, 0.f}, y1 = {0.f, 0.f};
;                         SB; LDG(G2, 2) SB; CMP(G0, 0) SB;
;                         LDG(G0, 3) SB; CMP(G1, 1) SB;
;                         CMP(G2, 2) SB;
; #pragma unroll
;                         for (int j = 0; j < 8; ++j) KA[j] = *(const f32x4*)(vs + 384 + 256 + 4 * j);
;                         SB; CMP(G0, 3) SB;
;                         float ys = (y0.x + y0.y) + (y1.x + y1.y);
;                         ys += dpp_f(ys, 0);
;                         if ((lane & 1) == 0) yb[s * 64 + srow] = ys;
;                     }
.LBB0_647:
.LBB0_648:
	s_andn2_saveexec_b64 s[54:55], s[54:55]
	s_cbranch_execz .LBB0_655
	s_add_i32 s56, s71, -1
	s_cmp_ge_u32 s56, s69
	s_cbranch_scc1 .LBB0_654
	s_lshl_b32 s56, s71, 1
	s_waitcnt vmcnt(0)
	v_bitop3_b32 v121, s56, 2, v67 bitop3:0x26
	v_and_b32_e32 v232, 3, v168
	v_lshlrev_b32_e32 v232, 6, v232
	v_mad_u32_u24 v232, v121, s66, v232
	v_lshrrev_b32_e32 v233, 2, v168
	v_and_b32_e32 v234, 1, v179
	v_lshlrev_b32_e32 v234, 7, v234
	v_lshl_add_u32 v234, v233, 3, v234
	v_mad_u32_u24 v233, v121, s66, v234
	v_lshl_add_u32 v234, v121, 12, v234
	v_add_u32_e32 v234, 0x18000, v234
	ds_read_b128 v[32:35], v232 offset:1024
	ds_read_b128 v[36:39], v232 offset:1040
	ds_read_b128 v[40:43], v232 offset:1056
	ds_read_b128 v[44:47], v232 offset:1072
	ds_read_b128 v[88:91], v232 offset:1280
	ds_read_b128 v[92:95], v232 offset:1296
	ds_read_b128 v[96:99], v232 offset:1312
	ds_read_b128 v[100:103], v232 offset:1328
	ds_read_b128 v[104:107], v232 offset:256
	ds_read_b128 v[108:111], v232 offset:272
	ds_read_b128 v[112:115], v232 offset:288
	ds_read_b128 v[116:119], v232 offset:304
	ds_read_b128 v[180:183], v232 offset:768
	ds_read_b128 v[184:187], v232 offset:784
	ds_read_b128 v[188:191], v232 offset:800
	ds_read_b128 v[192:195], v232 offset:816
	ds_read_b64 v[120:121], v233 offset:512
	s_waitcnt lgkmcnt(0)
	s_waitcnt lgkmcnt(13)
	v_pk_mul_f32 v[196:197], v[0:1], v[32:33]
	v_pk_mul_f32 v[200:201], v[16:17], v[32:33]
	v_pk_mul_f32 v[204:205], v[0:1], v[48:49]
	v_pk_mul_f32 v[208:209], v[16:17], v[48:49]
	v_pk_fma_f32 v[196:197], v[2:3], v[34:35], v[196:197]
	v_pk_fma_f32 v[200:201], v[18:19], v[34:35], v[200:201]
	v_pk_fma_f32 v[204:205], v[2:3], v[50:51], v[204:205]
	v_pk_fma_f32 v[208:209], v[18:19], v[50:51], v[208:209]
	ds_read_b128 v[32:35], v232 offset:2560
	ds_read_b128 v[48:51], v232 offset:0
	v_pk_fma_f32 v[196:197], v[4:5], v[36:37], v[196:197]
	v_pk_fma_f32 v[200:201], v[20:21], v[36:37], v[200:201]
	v_pk_fma_f32 v[204:205], v[4:5], v[52:53], v[204:205]
	v_pk_fma_f32 v[208:209], v[20:21], v[52:53], v[208:209]
	v_pk_fma_f32 v[196:197], v[6:7], v[38:39], v[196:197]
	v_pk_fma_f32 v[200:201], v[22:23], v[38:39], v[200:201]
	v_pk_fma_f32 v[204:205], v[6:7], v[54:55], v[204:205]
	v_pk_fma_f32 v[208:209], v[22:23], v[54:55], v[208:209]
	ds_read_b128 v[36:39], v232 offset:2576
	ds_read_b128 v[52:55], v232 offset:16
	v_pk_fma_f32 v[196:197], v[8:9], v[40:41], v[196:197]
	v_pk_fma_f32 v[200:201], v[24:25], v[40:41], v[200:201]
	v_pk_fma_f32 v[204:205], v[8:9], v[56:57], v[204:205]
	v_pk_fma_f32 v[208:209], v[24:25], v[56:57], v[208:209]
	v_pk_fma_f32 v[196:197], v[10:11], v[42:43], v[196:197]
	v_pk_fma_f32 v[200:201], v[26:27], v[42:43], v[200:201]
	v_pk_fma_f32 v[204:205], v[10:11], v[58:59], v[204:205]
	v_pk_fma_f32 v[208:209], v[26:27], v[58:59], v[208:209]
	ds_read_b128 v[40:43], v232 offset:2592
	ds_read_b128 v[56:59], v232 offset:32
	v_pk_fma_f32 v[196:197], v[12:13], v[44:45], v[196:197]
	v_pk_fma_f32 v[200:201], v[28:29], v[44:45], v[200:201]
	v_pk_fma_f32 v[204:205], v[12:13], v[60:61], v[204:205]
	v_pk_fma_f32 v[208:209], v[28:29], v[60:61], v[208:209]
	v_pk_fma_f32 v[196:197], v[14:15], v[46:47], v[196:197]
	v_pk_fma_f32 v[200:201], v[30:31], v[46:47], v[200:201]
	v_pk_fma_f32 v[204:205], v[14:15], v[62:63], v[204:205]
	v_pk_fma_f32 v[208:209], v[30:31], v[62:63], v[208:209]
	ds_read_b128 v[44:47], v232 offset:2608
	ds_read_b128 v[60:63], v232 offset:48
	v_add_f32_e32 v212, v196, v197
	v_add_f32_e32 v213, v200, v201
	v_add_f32_e32 v214, v204, v205
	v_add_f32_e32 v215, v208, v209
	v_add_f32_dpp v212, v212, v212 quad_perm:[1,0,3,2] row_mask:0xf bank_mask:0xf
	v_add_f32_dpp v213, v213, v213 quad_perm:[1,0,3,2] row_mask:0xf bank_mask:0xf
	v_add_f32_dpp v214, v214, v214 quad_perm:[1,0,3,2] row_mask:0xf bank_mask:0xf
	v_add_f32_dpp v215, v215, v215 quad_perm:[1,0,3,2] row_mask:0xf bank_mask:0xf
	v_add_f32_dpp v212, v212, v212 quad_perm:[2,3,0,1] row_mask:0xf bank_mask:0xf
	v_add_f32_dpp v213, v213, v213 quad_perm:[2,3,0,1] row_mask:0xf bank_mask:0xf
	v_add_f32_dpp v214, v214, v214 quad_perm:[2,3,0,1] row_mask:0xf bank_mask:0xf
	v_add_f32_dpp v215, v215, v215 quad_perm:[2,3,0,1] row_mask:0xf bank_mask:0xf
	s_waitcnt lgkmcnt(8)
	ds_read_b64 v[122:123], v233 offset:2048
	v_pk_mul_f32 v[216:217], v[88:89], v[212:213] op_sel_hi:[1,0] neg_lo:[0,1] neg_hi:[0,1]
	v_pk_mul_f32 v[218:219], v[90:91], v[212:213] op_sel_hi:[1,0] neg_lo:[0,1] neg_hi:[0,1]
	v_pk_mul_f32 v[220:221], v[88:89], v[212:213] op_sel:[0,1] op_sel_hi:[1,1] neg_lo:[0,1] neg_hi:[0,1]
	v_pk_mul_f32 v[222:223], v[90:91], v[212:213] op_sel:[0,1] op_sel_hi:[1,1] neg_lo:[0,1] neg_hi:[0,1]
	v_pk_fma_f32 v[216:217], v[104:105], v[120:121], v[216:217] op_sel_hi:[1,0,1]
	v_pk_fma_f32 v[218:219], v[106:107], v[120:121], v[218:219] op_sel_hi:[1,0,1]
	v_pk_fma_f32 v[220:221], v[104:105], v[120:121], v[220:221] op_sel:[0,1,0] op_sel_hi:[1,1,1]
	v_pk_fma_f32 v[222:223], v[106:107], v[120:121], v[222:223] op_sel:[0,1,0] op_sel_hi:[1,1,1]
	v_pk_fma_f32 v[0:1], v[0:1], v[180:181], v[216:217]
	v_pk_fma_f32 v[2:3], v[2:3], v[182:183], v[218:219]
	v_pk_fma_f32 v[16:17], v[16:17], v[180:181], v[220:221]
	v_pk_fma_f32 v[18:19], v[18:19], v[182:183], v[222:223]
	ds_read_b128 v[88:91], v232 offset:2816
	ds_read_b128 v[104:107], v232 offset:1792
	ds_read_b128 v[180:183], v232 offset:2304
	v_pk_mul_f32 v[224:225], v[92:93], v[212:213] op_sel_hi:[1,0] neg_lo:[0,1] neg_hi:[0,1]
	v_pk_mul_f32 v[226:227], v[94:95], v[212:213] op_sel_hi:[1,0] neg_lo:[0,1] neg_hi:[0,1]
	v_pk_mul_f32 v[228:229], v[92:93], v[212:213] op_sel:[0,1] op_sel_hi:[1,1] neg_lo:[0,1] neg_hi:[0,1]
; #define SB __builtin_amdgcn_sched_barrier(0)
; #define CMP(G, c8) { CMP1(G, 0, 2 * (c8)) CMP1(G, 1, 2 * (c8) + 1) }
; __device__ __forceinline__ void phase_scan(const Args& a, unsigned char* lds) {
;     ...
;                     f32x4 KA[8];
; #pragma unroll
;                     for (int j = 0; j < 8; ++j) KA[j] = *(const f32x4*)(vb + 256 + 4 * j);
; #pragma nounroll
;                     for (int s = 0; s < 16; ++s) {
;                         const float* vs = vb + s * 384;
;                         const float vi = vs[128 - cb + srow];
;                         f32x4 G0[8], G1[8], G2[8];
;                         LDG(G0, 0) SB;
;                         LDG(G1, 1) SB;
;                         f32x2 c0 = {0.f, 0.f}, c1 = {0.f, 0.f};
; #pragma unroll
;                         for (int j = 0; j < 8; ++j) { c0 += S2[2 * j] * (f32x2){KA[j][0], KA[j][1]}; c1 += S2[2 * j + 1] * (f32x2){KA[j][2], KA[j][3]}; }
;                         float cs = (c0.x + c0.y) + (c1.x + c1.y);
;                         cs += dpp_f(cs, 0);
;                         const float sa = -cs;
;                         const f32x2 sa2 = {sa, sa}, v2 = {vi, vi};
;                         f32x2 y0 = {0.f, 0.f}, y1 = {0.f, 0.f};
;                         SB; LDG(G2, 2) SB; CMP(G0, 0) SB;
;                         LDG(G0, 3) SB; CMP(G1, 1) SB;
;                         CMP(G2, 2) SB;
; #pragma unroll
;                         for (int j = 0; j < 8; ++j) KA[j] = *(const f32x4*)(vs + 384 + 256 + 4 * j);
;                         SB; CMP(G0, 3) SB;
;                         float ys = (y0.x + y0.y) + (y1.x + y1.y);
;                         ys += dpp_f(ys, 0);
;                         if ((lane & 1) == 0) yb[s * 64 + srow] = ys;
;                     }
	v_pk_mul_f32 v[230:231], v[94:95], v[212:213] op_sel:[0,1] op_sel_hi:[1,1] neg_lo:[0,1] neg_hi:[0,1]
	v_pk_fma_f32 v[224:225], v[108:109], v[120:121], v[224:225] op_sel_hi:[1,0,1]
	v_pk_fma_f32 v[226:227], v[110:111], v[120:121], v[226:227] op_sel_hi:[1,0,1]
	v_pk_fma_f32 v[228:229], v[108:109], v[120:121], v[228:229] op_sel:[0,1,0] op_sel_hi:[1,1,1]
	v_pk_fma_f32 v[230:231], v[110:111], v[120:121], v[230:231] op_sel:[0,1,0] op_sel_hi:[1,1,1]
	v_pk_fma_f32 v[4:5], v[4:5], v[184:185], v[224:225]
	v_pk_fma_f32 v[6:7], v[6:7], v[186:187], v[226:227]
	v_pk_fma_f32 v[20:21], v[20:21], v[184:185], v[228:229]
	v_pk_fma_f32 v[22:23], v[22:23], v[186:187], v[230:231]
	ds_read_b128 v[92:95], v232 offset:2832
	ds_read_b128 v[108:111], v232 offset:1808
	ds_read_b128 v[184:187], v232 offset:2320
	v_pk_mul_f32 v[216:217], v[96:97], v[212:213] op_sel_hi:[1,0] neg_lo:[0,1] neg_hi:[0,1]
	v_pk_mul_f32 v[218:219], v[98:99], v[212:213] op_sel_hi:[1,0] neg_lo:[0,1] neg_hi:[0,1]
	v_pk_mul_f32 v[220:221], v[96:97], v[212:213] op_sel:[0,1] op_sel_hi:[1,1] neg_lo:[0,1] neg_hi:[0,1]
	v_pk_mul_f32 v[222:223], v[98:99], v[212:213] op_sel:[0,1] op_sel_hi:[1,1] neg_lo:[0,1] neg_hi:[0,1]
	v_pk_fma_f32 v[216:217], v[112:113], v[120:121], v[216:217] op_sel_hi:[1,0,1]
	v_pk_fma_f32 v[218:219], v[114:115], v[120:121], v[218:219] op_sel_hi:[1,0,1]
	v_pk_fma_f32 v[220:221], v[112:113], v[120:121], v[220:221] op_sel:[0,1,0] op_sel_hi:[1,1,1]
	v_pk_fma_f32 v[222:223], v[114:115], v[120:121], v[222:223] op_sel:[0,1,0] op_sel_hi:[1,1,1]
	v_pk_fma_f32 v[8:9], v[8:9], v[188:189], v[216:217]
	v_pk_fma_f32 v[10:11], v[10:11], v[190:191], v[218:219]
	v_pk_fma_f32 v[24:25], v[24:25], v[188:189], v[220:221]
	v_pk_fma_f32 v[26:27], v[26:27], v[190:191], v[222:223]
	ds_read_b128 v[96:99], v232 offset:2848
	ds_read_b128 v[112:115], v232 offset:1824
	ds_read_b128 v[188:191], v232 offset:2336
	v_pk_mul_f32 v[224:225], v[100:101], v[212:213] op_sel_hi:[1,0] neg_lo:[0,1] neg_hi:[0,1]
	v_pk_mul_f32 v[226:227], v[102:103], v[212:213] op_sel_hi:[1,0] neg_lo:[0,1] neg_hi:[0,1]
	v_pk_mul_f32 v[228:229], v[100:101], v[212:213] op_sel:[0,1] op_sel_hi:[1,1] neg_lo:[0,1] neg_hi:[0,1]
	v_pk_mul_f32 v[230:231], v[102:103], v[212:213] op_sel:[0,1] op_sel_hi:[1,1] neg_lo:[0,1] neg_hi:[0,1]
	v_pk_fma_f32 v[224:225], v[116:117], v[120:121], v[224:225] op_sel_hi:[1,0,1]
	v_pk_fma_f32 v[226:227], v[118:119], v[120:121], v[226:227] op_sel_hi:[1,0,1]
	v_pk_fma_f32 v[228:229], v[116:117], v[120:121], v[228:229] op_sel:[0,1,0] op_sel_hi:[1,1,1]
	v_pk_fma_f32 v[230:231], v[118:119], v[120:121], v[230:231] op_sel:[0,1,0] op_sel_hi:[1,1,1]
	v_pk_fma_f32 v[12:13], v[12:13], v[192:193], v[224:225]
	v_pk_fma_f32 v[14:15], v[14:15], v[194:195], v[226:227]
	v_pk_fma_f32 v[28:29], v[28:29], v[192:193], v[228:229]
	v_pk_fma_f32 v[30:31], v[30:31], v[194:195], v[230:231]
	ds_read_b128 v[100:103], v232 offset:2864
	ds_read_b128 v[116:119], v232 offset:1840
	ds_read_b128 v[192:195], v232 offset:2352
	s_waitcnt lgkmcnt(13)
	v_pk_mul_f32 v[196:197], v[0:1], v[32:33]
	v_pk_mul_f32 v[200:201], v[16:17], v[32:33]
	v_pk_mul_f32 v[204:205], v[0:1], v[48:49]
	v_pk_mul_f32 v[208:209], v[16:17], v[48:49]
	v_pk_fma_f32 v[196:197], v[2:3], v[34:35], v[196:197]
	v_pk_fma_f32 v[200:201], v[18:19], v[34:35], v[200:201]
	v_pk_fma_f32 v[204:205], v[2:3], v[50:51], v[204:205]
	v_pk_fma_f32 v[208:209], v[18:19], v[50:51], v[208:209]
	ds_read_b128 v[32:35], v232 offset:4096
	ds_read_b128 v[48:51], v232 offset:1536
	v_pk_fma_f32 v[196:197], v[4:5], v[36:37], v[196:197]
	v_pk_fma_f32 v[200:201], v[20:21], v[36:37], v[200:201]
	v_pk_fma_f32 v[204:205], v[4:5], v[52:53], v[204:205]
	v_pk_fma_f32 v[208:209], v[20:21], v[52:53], v[208:209]
	v_pk_fma_f32 v[196:197], v[6:7], v[38:39], v[196:197]
	v_pk_fma_f32 v[200:201], v[22:23], v[38:39], v[200:201]
	v_pk_fma_f32 v[204:205], v[6:7], v[54:55], v[204:205]
	v_pk_fma_f32 v[208:209], v[22:23], v[54:55], v[208:209]
	ds_read_b128 v[36:39], v232 offset:4112
	ds_read_b128 v[52:55], v232 offset:1552
	v_pk_fma_f32 v[196:197], v[8:9], v[40:41], v[196:197]
	v_pk_fma_f32 v[200:201], v[24:25], v[40:41], v[200:201]
	v_pk_fma_f32 v[204:205], v[8:9], v[56:57], v[204:205]
	v_pk_fma_f32 v[208:209], v[24:25], v[56:57], v[208:209]
	v_pk_fma_f32 v[196:197], v[10:11], v[42:43], v[196:197]
	v_pk_fma_f32 v[200:201], v[26:27], v[42:43], v[200:201]
	v_pk_fma_f32 v[204:205], v[10:11], v[58:59], v[204:205]
	v_pk_fma_f32 v[208:209], v[26:27], v[58:59], v[208:209]
	ds_read_b128 v[40:43], v232 offset:4128
	ds_read_b128 v[56:59], v232 offset:1568
	v_pk_fma_f32 v[196:197], v[12:13], v[44:45], v[196:197]
	v_pk_fma_f32 v[200:201], v[28:29], v[44:45], v[200:201]
	v_pk_fma_f32 v[204:205], v[12:13], v[60:61], v[204:205]
	v_pk_fma_f32 v[208:209], v[28:29], v[60:61], v[208:209]
	v_pk_fma_f32 v[196:197], v[14:15], v[46:47], v[196:197]
	v_pk_fma_f32 v[200:201], v[30:31], v[46:47], v[200:201]
	v_pk_fma_f32 v[204:205], v[14:15], v[62:63], v[204:205]
	v_pk_fma_f32 v[208:209], v[30:31], v[62:63], v[208:209]
	ds_read_b128 v[44:47], v232 offset:4144
	ds_read_b128 v[60:63], v232 offset:1584
	v_add_f32_e32 v212, v196, v197
	v_add_f32_e32 v213, v200, v201
	v_add_f32_e32 v214, v204, v205
	v_add_f32_e32 v215, v208, v209
	v_add_f32_dpp v212, v212, v212 quad_perm:[1,0,3,2] row_mask:0xf bank_mask:0xf
	v_add_f32_dpp v213, v213, v213 quad_perm:[1,0,3,2] row_mask:0xf bank_mask:0xf
	v_add_f32_dpp v214, v214, v214 quad_perm:[1,0,3,2] row_mask:0xf bank_mask:0xf
	v_add_f32_dpp v215, v215, v215 quad_perm:[1,0,3,2] row_mask:0xf bank_mask:0xf
	v_add_f32_dpp v212, v212, v212 quad_perm:[2,3,0,1] row_mask:0xf bank_mask:0xf
	v_add_f32_dpp v213, v213, v213 quad_perm:[2,3,0,1] row_mask:0xf bank_mask:0xf
	v_add_f32_dpp v214, v214, v214 quad_perm:[2,3,0,1] row_mask:0xf bank_mask:0xf
	v_add_f32_dpp v215, v215, v215 quad_perm:[2,3,0,1] row_mask:0xf bank_mask:0xf
	ds_write_b64 v234, v[214:215] offset:0
	s_waitcnt lgkmcnt(8)
; #define SB __builtin_amdgcn_sched_barrier(0)
; #define CMP(G, c8) { CMP1(G, 0, 2 * (c8)) CMP1(G, 1, 2 * (c8) + 1) }
; __device__ __forceinline__ void phase_scan(const Args& a, unsigned char* lds) {
;     ...
;                     f32x4 KA[8];
; #pragma unroll
;                     for (int j = 0; j < 8; ++j) KA[j] = *(const f32x4*)(vb + 256 + 4 * j);
; #pragma nounroll
;                     for (int s = 0; s < 16; ++s) {
;                         const float* vs = vb + s * 384;
;                         const float vi = vs[128 - cb + srow];
;                         f32x4 G0[8], G1[8], G2[8];
;                         LDG(G0, 0) SB;
;                         LDG(G1, 1) SB;
;                         f32x2 c0 = {0.f, 0.f}, c1 = {0.f, 0.f};
; #pragma unroll
;                         for (int j = 0; j < 8; ++j) { c0 += S2[2 * j] * (f32x2){KA[j][0], KA[j][1]}; c1 += S2[2 * j + 1] * (f32x2){KA[j][2], KA[j][3]}; }
;                         float cs = (c0.x + c0.y) + (c1.x + c1.y);
;                         cs += dpp_f(cs, 0);
;                         const float sa = -cs;
;                         const f32x2 sa2 = {sa, sa}, v2 = {vi, vi};
;                         f32x2 y0 = {0.f, 0.f}, y1 = {0.f, 0.f};
;                         SB; LDG(G2, 2) SB; CMP(G0, 0) SB;
;                         LDG(G0, 3) SB; CMP(G1, 1) SB;
;                         CMP(G2, 2) SB;
; #pragma unroll
;                         for (int j = 0; j < 8; ++j) KA[j] = *(const f32x4*)(vs + 384 + 256 + 4 * j);
;                         SB; CMP(G0, 3) SB;
;                         float ys = (y0.x + y0.y) + (y1.x + y1.y);
;                         ys += dpp_f(ys, 0);
;                         if ((lane & 1) == 0) yb[s * 64 + srow] = ys;
;                     }
	ds_read_b64 v[120:121], v233 offset:3584
	v_pk_mul_f32 v[216:217], v[88:89], v[212:213] op_sel_hi:[1,0] neg_lo:[0,1] neg_hi:[0,1]
	v_pk_mul_f32 v[218:219], v[90:91], v[212:213] op_sel_hi:[1,0] neg_lo:[0,1] neg_hi:[0,1]
	v_pk_mul_f32 v[220:221], v[88:89], v[212:213] op_sel:[0,1] op_sel_hi:[1,1] neg_lo:[0,1] neg_hi:[0,1]
	v_pk_mul_f32 v[222:223], v[90:91], v[212:213] op_sel:[0,1] op_sel_hi:[1,1] neg_lo:[0,1] neg_hi:[0,1]
	v_pk_fma_f32 v[216:217], v[104:105], v[122:123], v[216:217] op_sel_hi:[1,0,1]
	v_pk_fma_f32 v[218:219], v[106:107], v[122:123], v[218:219] op_sel_hi:[1,0,1]
	v_pk_fma_f32 v[220:221], v[104:105], v[122:123], v[220:221] op_sel:[0,1,0] op_sel_hi:[1,1,1]
	v_pk_fma_f32 v[222:223], v[106:107], v[122:123], v[222:223] op_sel:[0,1,0] op_sel_hi:[1,1,1]
	v_pk_fma_f32 v[0:1], v[0:1], v[180:181], v[216:217]
	v_pk_fma_f32 v[2:3], v[2:3], v[182:183], v[218:219]
	v_pk_fma_f32 v[16:17], v[16:17], v[180:181], v[220:221]
	v_pk_fma_f32 v[18:19], v[18:19], v[182:183], v[222:223]
	ds_read_b128 v[88:91], v232 offset:4352
	ds_read_b128 v[104:107], v232 offset:3328
	ds_read_b128 v[180:183], v232 offset:3840
	v_pk_mul_f32 v[224:225], v[92:93], v[212:213] op_sel_hi:[1,0] neg_lo:[0,1] neg_hi:[0,1]
	v_pk_mul_f32 v[226:227], v[94:95], v[212:213] op_sel_hi:[1,0] neg_lo:[0,1] neg_hi:[0,1]
	v_pk_mul_f32 v[228:229], v[92:93], v[212:213] op_sel:[0,1] op_sel_hi:[1,1] neg_lo:[0,1] neg_hi:[0,1]
	v_pk_mul_f32 v[230:231], v[94:95], v[212:213] op_sel:[0,1] op_sel_hi:[1,1] neg_lo:[0,1] neg_hi:[0,1]
	v_pk_fma_f32 v[224:225], v[108:109], v[122:123], v[224:225] op_sel_hi:[1,0,1]
	v_pk_fma_f32 v[226:227], v[110:111], v[122:123], v[226:227] op_sel_hi:[1,0,1]
	v_pk_fma_f32 v[228:229], v[108:109], v[122:123], v[228:229] op_sel:[0,1,0] op_sel_hi:[1,1,1]
	v_pk_fma_f32 v[230:231], v[110:111], v[122:123], v[230:231] op_sel:[0,1,0] op_sel_hi:[1,1,1]
	v_pk_fma_f32 v[4:5], v[4:5], v[184:185], v[224:225]
	v_pk_fma_f32 v[6:7], v[6:7], v[186:187], v[226:227]
	v_pk_fma_f32 v[20:21], v[20:21], v[184:185], v[228:229]
	v_pk_fma_f32 v[22:23], v[22:23], v[186:187], v[230:231]
	ds_read_b128 v[92:95], v232 offset:4368
	ds_read_b128 v[108:111], v232 offset:3344
	ds_read_b128 v[184:187], v232 offset:3856
	v_pk_mul_f32 v[216:217], v[96:97], v[212:213] op_sel_hi:[1,0] neg_lo:[0,1] neg_hi:[0,1]
	v_pk_mul_f32 v[218:219], v[98:99], v[212:213] op_sel_hi:[1,0] neg_lo:[0,1] neg_hi:[0,1]
	v_pk_mul_f32 v[220:221], v[96:97], v[212:213] op_sel:[0,1] op_sel_hi:[1,1] neg_lo:[0,1] neg_hi:[0,1]
	v_pk_mul_f32 v[222:223], v[98:99], v[212:213] op_sel:[0,1] op_sel_hi:[1,1] neg_lo:[0,1] neg_hi:[0,1]
	v_pk_fma_f32 v[216:217], v[112:113], v[122:123], v[216:217] op_sel_hi:[1,0,1]
	v_pk_fma_f32 v[218:219], v[114:115], v[122:123], v[218:219] op_sel_hi:[1,0,1]
	v_pk_fma_f32 v[220:221], v[112:113], v[122:123], v[220:221] op_sel:[0,1,0] op_sel_hi:[1,1,1]
	v_pk_fma_f32 v[222:223], v[114:115], v[122:123], v[222:223] op_sel:[0,1,0] op_sel_hi:[1,1,1]
	v_pk_fma_f32 v[8:9], v[8:9], v[188:189], v[216:217]
	v_pk_fma_f32 v[10:11], v[10:11], v[190:191], v[218:219]
	v_pk_fma_f32 v[24:25], v[24:25], v[188:189], v[220:221]
	v_pk_fma_f32 v[26:27], v[26:27], v[190:191], v[222:223]
	ds_read_b128 v[96:99], v232 offset:4384
	ds_read_b128 v[112:115], v232 offset:3360
	ds_read_b128 v[188:191], v232 offset:3872
	v_pk_mul_f32 v[224:225], v[100:101], v[212:213] op_sel_hi:[1,0] neg_lo:[0,1] neg_hi:[0,1]
	v_pk_mul_f32 v[226:227], v[102:103], v[212:213] op_sel_hi:[1,0] neg_lo:[0,1] neg_hi:[0,1]
	v_pk_mul_f32 v[228:229], v[100:101], v[212:213] op_sel:[0,1] op_sel_hi:[1,1] neg_lo:[0,1] neg_hi:[0,1]
	v_pk_mul_f32 v[230:231], v[102:103], v[212:213] op_sel:[0,1] op_sel_hi:[1,1] neg_lo:[0,1] neg_hi:[0,1]
	v_pk_fma_f32 v[224:225], v[116:117], v[122:123], v[224:225] op_sel_hi:[1,0,1]
	v_pk_fma_f32 v[226:227], v[118:119], v[122:123], v[226:227] op_sel_hi:[1,0,1]
	v_pk_fma_f32 v[228:229], v[116:117], v[122:123], v[228:229] op_sel:[0,1,0] op_sel_hi:[1,1,1]
	v_pk_fma_f32 v[230:231], v[118:119], v[122:123], v[230:231] op_sel:[0,1,0] op_sel_hi:[1,1,1]
	v_pk_fma_f32 v[12:13], v[12:13], v[192:193], v[224:225]
	v_pk_fma_f32 v[14:15], v[14:15], v[194:195], v[226:227]
	v_pk_fma_f32 v[28:29], v[28:29], v[192:193], v[228:229]
	v_pk_fma_f32 v[30:31], v[30:31], v[194:195], v[230:231]
	ds_read_b128 v[100:103], v232 offset:4400
	ds_read_b128 v[116:119], v232 offset:3376
	ds_read_b128 v[192:195], v232 offset:3888
	s_waitcnt lgkmcnt(13)
; #define SB __builtin_amdgcn_sched_barrier(0)
; #define CMP(G, c8) { CMP1(G, 0, 2 * (c8)) CMP1(G, 1, 2 * (c8) + 1) }
; __device__ __forceinline__ void phase_scan(const Args& a, unsigned char* lds) {
;     ...
;                     f32x4 KA[8];
; #pragma unroll
;                     for (int j = 0; j < 8; ++j) KA[j] = *(const f32x4*)(vb + 256 + 4 * j);
; #pragma nounroll
;                     for (int s = 0; s < 16; ++s) {
;                         const float* vs = vb + s * 384;
;                         const float vi = vs[128 - cb + srow];
;                         f32x4 G0[8], G1[8], G2[8];
;                         LDG(G0, 0) SB;
;                         LDG(G1, 1) SB;
;                         f32x2 c0 = {0.f, 0.f}, c1 = {0.f, 0.f};
; #pragma unroll
;                         for (int j = 0; j < 8; ++j) { c0 += S2[2 * j] * (f32x2){KA[j][0], KA[j][1]}; c1 += S2[2 * j + 1] * (f32x2){KA[j][2], KA[j][3]}; }
;                         float cs = (c0.x + c0.y) + (c1.x + c1.y);
;                         cs += dpp_f(cs, 0);
;                         const float sa = -cs;
;                         const f32x2 sa2 = {sa, sa}, v2 = {vi, vi};
;                         f32x2 y0 = {0.f, 0.f}, y1 = {0.f, 0.f};
;                         SB; LDG(G2, 2) SB; CMP(G0, 0) SB;
;                         LDG(G0, 3) SB; CMP(G1, 1) SB;
;                         CMP(G2, 2) SB;
; #pragma unroll
;                         for (int j = 0; j < 8; ++j) KA[j] = *(const f32x4*)(vs + 384 + 256 + 4 * j);
;                         SB; CMP(G0, 3) SB;
;                         float ys = (y0.x + y0.y) + (y1.x + y1.y);
;                         ys += dpp_f(ys, 0);
;                         if ((lane & 1) == 0) yb[s * 64 + srow] = ys;
;                     }
	v_pk_mul_f32 v[196:197], v[0:1], v[32:33]
	v_pk_mul_f32 v[200:201], v[16:17], v[32:33]
	v_pk_mul_f32 v[204:205], v[0:1], v[48:49]
	v_pk_mul_f32 v[208:209], v[16:17], v[48:49]
	v_pk_fma_f32 v[196:197], v[2:3], v[34:35], v[196:197]
	v_pk_fma_f32 v[200:201], v[18:19], v[34:35], v[200:201]
	v_pk_fma_f32 v[204:205], v[2:3], v[50:51], v[204:205]
	v_pk_fma_f32 v[208:209], v[18:19], v[50:51], v[208:209]
	ds_read_b128 v[32:35], v232 offset:5632
	ds_read_b128 v[48:51], v232 offset:3072
	v_pk_fma_f32 v[196:197], v[4:5], v[36:37], v[196:197]
	v_pk_fma_f32 v[200:201], v[20:21], v[36:37], v[200:201]
	v_pk_fma_f32 v[204:205], v[4:5], v[52:53], v[204:205]
	v_pk_fma_f32 v[208:209], v[20:21], v[52:53], v[208:209]
	v_pk_fma_f32 v[196:197], v[6:7], v[38:39], v[196:197]
	v_pk_fma_f32 v[200:201], v[22:23], v[38:39], v[200:201]
	v_pk_fma_f32 v[204:205], v[6:7], v[54:55], v[204:205]
	v_pk_fma_f32 v[208:209], v[22:23], v[54:55], v[208:209]
	ds_read_b128 v[36:39], v232 offset:5648
	ds_read_b128 v[52:55], v232 offset:3088
	v_pk_fma_f32 v[196:197], v[8:9], v[40:41], v[196:197]
	v_pk_fma_f32 v[200:201], v[24:25], v[40:41], v[200:201]
	v_pk_fma_f32 v[204:205], v[8:9], v[56:57], v[204:205]
	v_pk_fma_f32 v[208:209], v[24:25], v[56:57], v[208:209]
	v_pk_fma_f32 v[196:197], v[10:11], v[42:43], v[196:197]
	v_pk_fma_f32 v[200:201], v[26:27], v[42:43], v[200:201]
	v_pk_fma_f32 v[204:205], v[10:11], v[58:59], v[204:205]
	v_pk_fma_f32 v[208:209], v[26:27], v[58:59], v[208:209]
	ds_read_b128 v[40:43], v232 offset:5664
	ds_read_b128 v[56:59], v232 offset:3104
	v_pk_fma_f32 v[196:197], v[12:13], v[44:45], v[196:197]
	v_pk_fma_f32 v[200:201], v[28:29], v[44:45], v[200:201]
	v_pk_fma_f32 v[204:205], v[12:13], v[60:61], v[204:205]
	v_pk_fma_f32 v[208:209], v[28:29], v[60:61], v[208:209]
	v_pk_fma_f32 v[196:197], v[14:15], v[46:47], v[196:197]
	v_pk_fma_f32 v[200:201], v[30:31], v[46:47], v[200:201]
	v_pk_fma_f32 v[204:205], v[14:15], v[62:63], v[204:205]
	v_pk_fma_f32 v[208:209], v[30:31], v[62:63], v[208:209]
	ds_read_b128 v[44:47], v232 offset:5680
	ds_read_b128 v[60:63], v232 offset:3120
	v_add_f32_e32 v212, v196, v197
	v_add_f32_e32 v213, v200, v201
	v_add_f32_e32 v214, v204, v205
	v_add_f32_e32 v215, v208, v209
	v_add_f32_dpp v212, v212, v212 quad_perm:[1,0,3,2] row_mask:0xf bank_mask:0xf
	v_add_f32_dpp v213, v213, v213 quad_perm:[1,0,3,2] row_mask:0xf bank_mask:0xf
	v_add_f32_dpp v214, v214, v214 quad_perm:[1,0,3,2] row_mask:0xf bank_mask:0xf
	v_add_f32_dpp v215, v215, v215 quad_perm:[1,0,3,2] row_mask:0xf bank_mask:0xf
	v_add_f32_dpp v212, v212, v212 quad_perm:[2,3,0,1] row_mask:0xf bank_mask:0xf
	v_add_f32_dpp v213, v213, v213 quad_perm:[2,3,0,1] row_mask:0xf bank_mask:0xf
	v_add_f32_dpp v214, v214, v214 quad_perm:[2,3,0,1] row_mask:0xf bank_mask:0xf
	v_add_f32_dpp v215, v215, v215 quad_perm:[2,3,0,1] row_mask:0xf bank_mask:0xf
	ds_write_b64 v234, v[214:215] offset:256
	s_waitcnt lgkmcnt(8)
	ds_read_b64 v[122:123], v233 offset:5120
	v_pk_mul_f32 v[216:217], v[88:89], v[212:213] op_sel_hi:[1,0] neg_lo:[0,1] neg_hi:[0,1]
	v_pk_mul_f32 v[218:219], v[90:91], v[212:213] op_sel_hi:[1,0] neg_lo:[0,1] neg_hi:[0,1]
	v_pk_mul_f32 v[220:221], v[88:89], v[212:213] op_sel:[0,1] op_sel_hi:[1,1] neg_lo:[0,1] neg_hi:[0,1]
	v_pk_mul_f32 v[222:223], v[90:91], v[212:213] op_sel:[0,1] op_sel_hi:[1,1] neg_lo:[0,1] neg_hi:[0,1]
	v_pk_fma_f32 v[216:217], v[104:105], v[120:121], v[216:217] op_sel_hi:[1,0,1]
	v_pk_fma_f32 v[218:219], v[106:107], v[120:121], v[218:219] op_sel_hi:[1,0,1]
	v_pk_fma_f32 v[220:221], v[104:105], v[120:121], v[220:221] op_sel:[0,1,0] op_sel_hi:[1,1,1]
	v_pk_fma_f32 v[222:223], v[106:107], v[120:121], v[222:223] op_sel:[0,1,0] op_sel_hi:[1,1,1]
	v_pk_fma_f32 v[0:1], v[0:1], v[180:181], v[216:217]
	v_pk_fma_f32 v[2:3], v[2:3], v[182:183], v[218:219]
	v_pk_fma_f32 v[16:17], v[16:17], v[180:181], v[220:221]
	v_pk_fma_f32 v[18:19], v[18:19], v[182:183], v[222:223]
	ds_read_b128 v[88:91], v232 offset:5888
	ds_read_b128 v[104:107], v232 offset:4864
	ds_read_b128 v[180:183], v232 offset:5376
	v_pk_mul_f32 v[224:225], v[92:93], v[212:213] op_sel_hi:[1,0] neg_lo:[0,1] neg_hi:[0,1]
	v_pk_mul_f32 v[226:227], v[94:95], v[212:213] op_sel_hi:[1,0] neg_lo:[0,1] neg_hi:[0,1]
	v_pk_mul_f32 v[228:229], v[92:93], v[212:213] op_sel:[0,1] op_sel_hi:[1,1] neg_lo:[0,1] neg_hi:[0,1]
	v_pk_mul_f32 v[230:231], v[94:95], v[212:213] op_sel:[0,1] op_sel_hi:[1,1] neg_lo:[0,1] neg_hi:[0,1]
	v_pk_fma_f32 v[224:225], v[108:109], v[120:121], v[224:225] op_sel_hi:[1,0,1]
	v_pk_fma_f32 v[226:227], v[110:111], v[120:121], v[226:227] op_sel_hi:[1,0,1]
	v_pk_fma_f32 v[228:229], v[108:109], v[120:121], v[228:229] op_sel:[0,1,0] op_sel_hi:[1,1,1]
	v_pk_fma_f32 v[230:231], v[110:111], v[120:121], v[230:231] op_sel:[0,1,0] op_sel_hi:[1,1,1]
	v_pk_fma_f32 v[4:5], v[4:5], v[184:185], v[224:225]
	v_pk_fma_f32 v[6:7], v[6:7], v[186:187], v[226:227]
	v_pk_fma_f32 v[20:21], v[20:21], v[184:185], v[228:229]
	v_pk_fma_f32 v[22:23], v[22:23], v[186:187], v[230:231]
	ds_read_b128 v[92:95], v232 offset:5904
	ds_read_b128 v[108:111], v232 offset:4880
	ds_read_b128 v[184:187], v232 offset:5392
	v_pk_mul_f32 v[216:217], v[96:97], v[212:213] op_sel_hi:[1,0] neg_lo:[0,1] neg_hi:[0,1]
	v_pk_mul_f32 v[218:219], v[98:99], v[212:213] op_sel_hi:[1,0] neg_lo:[0,1] neg_hi:[0,1]
	v_pk_mul_f32 v[220:221], v[96:97], v[212:213] op_sel:[0,1] op_sel_hi:[1,1] neg_lo:[0,1] neg_hi:[0,1]
	v_pk_mul_f32 v[222:223], v[98:99], v[212:213] op_sel:[0,1] op_sel_hi:[1,1] neg_lo:[0,1] neg_hi:[0,1]
	v_pk_fma_f32 v[216:217], v[112:113], v[120:121], v[216:217] op_sel_hi:[1,0,1]
	v_pk_fma_f32 v[218:219], v[114:115], v[120:121], v[218:219] op_sel_hi:[1,0,1]
; #define SB __builtin_amdgcn_sched_barrier(0)
; #define CMP(G, c8) { CMP1(G, 0, 2 * (c8)) CMP1(G, 1, 2 * (c8) + 1) }
; __device__ __forceinline__ void phase_scan(const Args& a, unsigned char* lds) {
;     ...
;                     f32x4 KA[8];
; #pragma unroll
;                     for (int j = 0; j < 8; ++j) KA[j] = *(const f32x4*)(vb + 256 + 4 * j);
; #pragma nounroll
;                     for (int s = 0; s < 16; ++s) {
;                         const float* vs = vb + s * 384;
;                         const float vi = vs[128 - cb + srow];
;                         f32x4 G0[8], G1[8], G2[8];
;                         LDG(G0, 0) SB;
;                         LDG(G1, 1) SB;
;                         f32x2 c0 = {0.f, 0.f}, c1 = {0.f, 0.f};
; #pragma unroll
;                         for (int j = 0; j < 8; ++j) { c0 += S2[2 * j] * (f32x2){KA[j][0], KA[j][1]}; c1 += S2[2 * j + 1] * (f32x2){KA[j][2], KA[j][3]}; }
;                         float cs = (c0.x + c0.y) + (c1.x + c1.y);
;                         cs += dpp_f(cs, 0);
;                         const float sa = -cs;
;                         const f32x2 sa2 = {sa, sa}, v2 = {vi, vi};
;                         f32x2 y0 = {0.f, 0.f}, y1 = {0.f, 0.f};
;                         SB; LDG(G2, 2) SB; CMP(G0, 0) SB;
;                         LDG(G0, 3) SB; CMP(G1, 1) SB;
;                         CMP(G2, 2) SB;
; #pragma unroll
;                         for (int j = 0; j < 8; ++j) KA[j] = *(const f32x4*)(vs + 384 + 256 + 4 * j);
;                         SB; CMP(G0, 3) SB;
;                         float ys = (y0.x + y0.y) + (y1.x + y1.y);
;                         ys += dpp_f(ys, 0);
;                         if ((lane & 1) == 0) yb[s * 64 + srow] = ys;
;                     }
	v_pk_fma_f32 v[220:221], v[112:113], v[120:121], v[220:221] op_sel:[0,1,0] op_sel_hi:[1,1,1]
	v_pk_fma_f32 v[222:223], v[114:115], v[120:121], v[222:223] op_sel:[0,1,0] op_sel_hi:[1,1,1]
	v_pk_fma_f32 v[8:9], v[8:9], v[188:189], v[216:217]
	v_pk_fma_f32 v[10:11], v[10:11], v[190:191], v[218:219]
	v_pk_fma_f32 v[24:25], v[24:25], v[188:189], v[220:221]
	v_pk_fma_f32 v[26:27], v[26:27], v[190:191], v[222:223]
	ds_read_b128 v[96:99], v232 offset:5920
	ds_read_b128 v[112:115], v232 offset:4896
	ds_read_b128 v[188:191], v232 offset:5408
	v_pk_mul_f32 v[224:225], v[100:101], v[212:213] op_sel_hi:[1,0] neg_lo:[0,1] neg_hi:[0,1]
	v_pk_mul_f32 v[226:227], v[102:103], v[212:213] op_sel_hi:[1,0] neg_lo:[0,1] neg_hi:[0,1]
	v_pk_mul_f32 v[228:229], v[100:101], v[212:213] op_sel:[0,1] op_sel_hi:[1,1] neg_lo:[0,1] neg_hi:[0,1]
	v_pk_mul_f32 v[230:231], v[102:103], v[212:213] op_sel:[0,1] op_sel_hi:[1,1] neg_lo:[0,1] neg_hi:[0,1]
	v_pk_fma_f32 v[224:225], v[116:117], v[120:121], v[224:225] op_sel_hi:[1,0,1]
	v_pk_fma_f32 v[226:227], v[118:119], v[120:121], v[226:227] op_sel_hi:[1,0,1]
	v_pk_fma_f32 v[228:229], v[116:117], v[120:121], v[228:229] op_sel:[0,1,0] op_sel_hi:[1,1,1]
	v_pk_fma_f32 v[230:231], v[118:119], v[120:121], v[230:231] op_sel:[0,1,0] op_sel_hi:[1,1,1]
	v_pk_fma_f32 v[12:13], v[12:13], v[192:193], v[224:225]
	v_pk_fma_f32 v[14:15], v[14:15], v[194:195], v[226:227]
	v_pk_fma_f32 v[28:29], v[28:29], v[192:193], v[228:229]
	v_pk_fma_f32 v[30:31], v[30:31], v[194:195], v[230:231]
	ds_read_b128 v[100:103], v232 offset:5936
	ds_read_b128 v[116:119], v232 offset:4912
	ds_read_b128 v[192:195], v232 offset:5424
	s_waitcnt lgkmcnt(13)
	v_pk_mul_f32 v[196:197], v[0:1], v[32:33]
	v_pk_mul_f32 v[200:201], v[16:17], v[32:33]
	v_pk_mul_f32 v[204:205], v[0:1], v[48:49]
	v_pk_mul_f32 v[208:209], v[16:17], v[48:49]
	v_pk_fma_f32 v[196:197], v[2:3], v[34:35], v[196:197]
	v_pk_fma_f32 v[200:201], v[18:19], v[34:35], v[200:201]
	v_pk_fma_f32 v[204:205], v[2:3], v[50:51], v[204:205]
	v_pk_fma_f32 v[208:209], v[18:19], v[50:51], v[208:209]
	ds_read_b128 v[32:35], v232 offset:7168
	ds_read_b128 v[48:51], v232 offset:4608
	v_pk_fma_f32 v[196:197], v[4:5], v[36:37], v[196:197]
	v_pk_fma_f32 v[200:201], v[20:21], v[36:37], v[200:201]
	v_pk_fma_f32 v[204:205], v[4:5], v[52:53], v[204:205]
	v_pk_fma_f32 v[208:209], v[20:21], v[52:53], v[208:209]
	v_pk_fma_f32 v[196:197], v[6:7], v[38:39], v[196:197]
	v_pk_fma_f32 v[200:201], v[22:23], v[38:39], v[200:201]
	v_pk_fma_f32 v[204:205], v[6:7], v[54:55], v[204:205]
	v_pk_fma_f32 v[208:209], v[22:23], v[54:55], v[208:209]
	ds_read_b128 v[36:39], v232 offset:7184
	ds_read_b128 v[52:55], v232 offset:4624
	v_pk_fma_f32 v[196:197], v[8:9], v[40:41], v[196:197]
	v_pk_fma_f32 v[200:201], v[24:25], v[40:41], v[200:201]
	v_pk_fma_f32 v[204:205], v[8:9], v[56:57], v[204:205]
	v_pk_fma_f32 v[208:209], v[24:25], v[56:57], v[208:209]
	v_pk_fma_f32 v[196:197], v[10:11], v[42:43], v[196:197]
	v_pk_fma_f32 v[200:201], v[26:27], v[42:43], v[200:201]
	v_pk_fma_f32 v[204:205], v[10:11], v[58:59], v[204:205]
	v_pk_fma_f32 v[208:209], v[26:27], v[58:59], v[208:209]
	ds_read_b128 v[40:43], v232 offset:7200
	ds_read_b128 v[56:59], v232 offset:4640
	v_pk_fma_f32 v[196:197], v[12:13], v[44:45], v[196:197]
	v_pk_fma_f32 v[200:201], v[28:29], v[44:45], v[200:201]
	v_pk_fma_f32 v[204:205], v[12:13], v[60:61], v[204:205]
	v_pk_fma_f32 v[208:209], v[28:29], v[60:61], v[208:209]
	v_pk_fma_f32 v[196:197], v[14:15], v[46:47], v[196:197]
	v_pk_fma_f32 v[200:201], v[30:31], v[46:47], v[200:201]
	v_pk_fma_f32 v[204:205], v[14:15], v[62:63], v[204:205]
	v_pk_fma_f32 v[208:209], v[30:31], v[62:63], v[208:209]
	ds_read_b128 v[44:47], v232 offset:7216
	ds_read_b128 v[60:63], v232 offset:4656
	v_add_f32_e32 v212, v196, v197
	v_add_f32_e32 v213, v200, v201
	v_add_f32_e32 v214, v204, v205
	v_add_f32_e32 v215, v208, v209
	v_add_f32_dpp v212, v212, v212 quad_perm:[1,0,3,2] row_mask:0xf bank_mask:0xf
	v_add_f32_dpp v213, v213, v213 quad_perm:[1,0,3,2] row_mask:0xf bank_mask:0xf
	v_add_f32_dpp v214, v214, v214 quad_perm:[1,0,3,2] row_mask:0xf bank_mask:0xf
	v_add_f32_dpp v215, v215, v215 quad_perm:[1,0,3,2] row_mask:0xf bank_mask:0xf
	v_add_f32_dpp v212, v212, v212 quad_perm:[2,3,0,1] row_mask:0xf bank_mask:0xf
	v_add_f32_dpp v213, v213, v213 quad_perm:[2,3,0,1] row_mask:0xf bank_mask:0xf
	v_add_f32_dpp v214, v214, v214 quad_perm:[2,3,0,1] row_mask:0xf bank_mask:0xf
	v_add_f32_dpp v215, v215, v215 quad_perm:[2,3,0,1] row_mask:0xf bank_mask:0xf
	ds_write_b64 v234, v[214:215] offset:512
	s_waitcnt lgkmcnt(8)
; #define SB __builtin_amdgcn_sched_barrier(0)
; #define CMP(G, c8) { CMP1(G, 0, 2 * (c8)) CMP1(G, 1, 2 * (c8) + 1) }
; __device__ __forceinline__ void phase_scan(const Args& a, unsigned char* lds) {
;     ...
;                     f32x4 KA[8];
; #pragma unroll
;                     for (int j = 0; j < 8; ++j) KA[j] = *(const f32x4*)(vb + 256 + 4 * j);
; #pragma nounroll
;                     for (int s = 0; s < 16; ++s) {
;                         const float* vs = vb + s * 384;
;                         const float vi = vs[128 - cb + srow];
;                         f32x4 G0[8], G1[8], G2[8];
;                         LDG(G0, 0) SB;
;                         LDG(G1, 1) SB;
;                         f32x2 c0 = {0.f, 0.f}, c1 = {0.f, 0.f};
; #pragma unroll
;                         for (int j = 0; j < 8; ++j) { c0 += S2[2 * j] * (f32x2){KA[j][0], KA[j][1]}; c1 += S2[2 * j + 1] * (f32x2){KA[j][2], KA[j][3]}; }
;                         float cs = (c0.x + c0.y) + (c1.x + c1.y);
;                         cs += dpp_f(cs, 0);
;                         const float sa = -cs;
;                         const f32x2 sa2 = {sa, sa}, v2 = {vi, vi};
;                         f32x2 y0 = {0.f, 0.f}, y1 = {0.f, 0.f};
;                         SB; LDG(G2, 2) SB; CMP(G0, 0) SB;
;                         LDG(G0, 3) SB; CMP(G1, 1) SB;
;                         CMP(G2, 2) SB;
; #pragma unroll
;                         for (int j = 0; j < 8; ++j) KA[j] = *(const f32x4*)(vs + 384 + 256 + 4 * j);
;                         SB; CMP(G0, 3) SB;
;                         float ys = (y0.x + y0.y) + (y1.x + y1.y);
;                         ys += dpp_f(ys, 0);
;                         if ((lane & 1) == 0) yb[s * 64 + srow] = ys;
;                     }
	ds_read_b64 v[120:121], v233 offset:6656
	v_pk_mul_f32 v[216:217], v[88:89], v[212:213] op_sel_hi:[1,0] neg_lo:[0,1] neg_hi:[0,1]
	v_pk_mul_f32 v[218:219], v[90:91], v[212:213] op_sel_hi:[1,0] neg_lo:[0,1] neg_hi:[0,1]
	v_pk_mul_f32 v[220:221], v[88:89], v[212:213] op_sel:[0,1] op_sel_hi:[1,1] neg_lo:[0,1] neg_hi:[0,1]
	v_pk_mul_f32 v[222:223], v[90:91], v[212:213] op_sel:[0,1] op_sel_hi:[1,1] neg_lo:[0,1] neg_hi:[0,1]
	v_pk_fma_f32 v[216:217], v[104:105], v[122:123], v[216:217] op_sel_hi:[1,0,1]
	v_pk_fma_f32 v[218:219], v[106:107], v[122:123], v[218:219] op_sel_hi:[1,0,1]
	v_pk_fma_f32 v[220:221], v[104:105], v[122:123], v[220:221] op_sel:[0,1,0] op_sel_hi:[1,1,1]
	v_pk_fma_f32 v[222:223], v[106:107], v[122:123], v[222:223] op_sel:[0,1,0] op_sel_hi:[1,1,1]
	v_pk_fma_f32 v[0:1], v[0:1], v[180:181], v[216:217]
	v_pk_fma_f32 v[2:3], v[2:3], v[182:183], v[218:219]
	v_pk_fma_f32 v[16:17], v[16:17], v[180:181], v[220:221]
	v_pk_fma_f32 v[18:19], v[18:19], v[182:183], v[222:223]
	ds_read_b128 v[88:91], v232 offset:7424
	ds_read_b128 v[104:107], v232 offset:6400
	ds_read_b128 v[180:183], v232 offset:6912
	v_pk_mul_f32 v[224:225], v[92:93], v[212:213] op_sel_hi:[1,0] neg_lo:[0,1] neg_hi:[0,1]
	v_pk_mul_f32 v[226:227], v[94:95], v[212:213] op_sel_hi:[1,0] neg_lo:[0,1] neg_hi:[0,1]
	v_pk_mul_f32 v[228:229], v[92:93], v[212:213] op_sel:[0,1] op_sel_hi:[1,1] neg_lo:[0,1] neg_hi:[0,1]
	v_pk_mul_f32 v[230:231], v[94:95], v[212:213] op_sel:[0,1] op_sel_hi:[1,1] neg_lo:[0,1] neg_hi:[0,1]
	v_pk_fma_f32 v[224:225], v[108:109], v[122:123], v[224:225] op_sel_hi:[1,0,1]
	v_pk_fma_f32 v[226:227], v[110:111], v[122:123], v[226:227] op_sel_hi:[1,0,1]
	v_pk_fma_f32 v[228:229], v[108:109], v[122:123], v[228:229] op_sel:[0,1,0] op_sel_hi:[1,1,1]
	v_pk_fma_f32 v[230:231], v[110:111], v[122:123], v[230:231] op_sel:[0,1,0] op_sel_hi:[1,1,1]
	v_pk_fma_f32 v[4:5], v[4:5], v[184:185], v[224:225]
	v_pk_fma_f32 v[6:7], v[6:7], v[186:187], v[226:227]
	v_pk_fma_f32 v[20:21], v[20:21], v[184:185], v[228:229]
	v_pk_fma_f32 v[22:23], v[22:23], v[186:187], v[230:231]
	ds_read_b128 v[92:95], v232 offset:7440
	ds_read_b128 v[108:111], v232 offset:6416
	ds_read_b128 v[184:187], v232 offset:6928
	v_pk_mul_f32 v[216:217], v[96:97], v[212:213] op_sel_hi:[1,0] neg_lo:[0,1] neg_hi:[0,1]
	v_pk_mul_f32 v[218:219], v[98:99], v[212:213] op_sel_hi:[1,0] neg_lo:[0,1] neg_hi:[0,1]
	v_pk_mul_f32 v[220:221], v[96:97], v[212:213] op_sel:[0,1] op_sel_hi:[1,1] neg_lo:[0,1] neg_hi:[0,1]
	v_pk_mul_f32 v[222:223], v[98:99], v[212:213] op_sel:[0,1] op_sel_hi:[1,1] neg_lo:[0,1] neg_hi:[0,1]
	v_pk_fma_f32 v[216:217], v[112:113], v[122:123], v[216:217] op_sel_hi:[1,0,1]
	v_pk_fma_f32 v[218:219], v[114:115], v[122:123], v[218:219] op_sel_hi:[1,0,1]
	v_pk_fma_f32 v[220:221], v[112:113], v[122:123], v[220:221] op_sel:[0,1,0] op_sel_hi:[1,1,1]
	v_pk_fma_f32 v[222:223], v[114:115], v[122:123], v[222:223] op_sel:[0,1,0] op_sel_hi:[1,1,1]
	v_pk_fma_f32 v[8:9], v[8:9], v[188:189], v[216:217]
	v_pk_fma_f32 v[10:11], v[10:11], v[190:191], v[218:219]
	v_pk_fma_f32 v[24:25], v[24:25], v[188:189], v[220:221]
	v_pk_fma_f32 v[26:27], v[26:27], v[190:191], v[222:223]
	ds_read_b128 v[96:99], v232 offset:7456
	ds_read_b128 v[112:115], v232 offset:6432
	ds_read_b128 v[188:191], v232 offset:6944
	v_pk_mul_f32 v[224:225], v[100:101], v[212:213] op_sel_hi:[1,0] neg_lo:[0,1] neg_hi:[0,1]
	v_pk_mul_f32 v[226:227], v[102:103], v[212:213] op_sel_hi:[1,0] neg_lo:[0,1] neg_hi:[0,1]
	v_pk_mul_f32 v[228:229], v[100:101], v[212:213] op_sel:[0,1] op_sel_hi:[1,1] neg_lo:[0,1] neg_hi:[0,1]
	v_pk_mul_f32 v[230:231], v[102:103], v[212:213] op_sel:[0,1] op_sel_hi:[1,1] neg_lo:[0,1] neg_hi:[0,1]
	v_pk_fma_f32 v[224:225], v[116:117], v[122:123], v[224:225] op_sel_hi:[1,0,1]
	v_pk_fma_f32 v[226:227], v[118:119], v[122:123], v[226:227] op_sel_hi:[1,0,1]
	v_pk_fma_f32 v[228:229], v[116:117], v[122:123], v[228:229] op_sel:[0,1,0] op_sel_hi:[1,1,1]
	v_pk_fma_f32 v[230:231], v[118:119], v[122:123], v[230:231] op_sel:[0,1,0] op_sel_hi:[1,1,1]
	v_pk_fma_f32 v[12:13], v[12:13], v[192:193], v[224:225]
	v_pk_fma_f32 v[14:15], v[14:15], v[194:195], v[226:227]
	v_pk_fma_f32 v[28:29], v[28:29], v[192:193], v[228:229]
	v_pk_fma_f32 v[30:31], v[30:31], v[194:195], v[230:231]
	ds_read_b128 v[100:103], v232 offset:7472
	ds_read_b128 v[116:119], v232 offset:6448
	ds_read_b128 v[192:195], v232 offset:6960
	s_waitcnt lgkmcnt(13)
; #define SB __builtin_amdgcn_sched_barrier(0)
; #define CMP(G, c8) { CMP1(G, 0, 2 * (c8)) CMP1(G, 1, 2 * (c8) + 1) }
; __device__ __forceinline__ void phase_scan(const Args& a, unsigned char* lds) {
;     ...
;                     for (int s = 0; s < 16; ++s) {
;                         const float* vs = vb + s * 384;
;                         const float vi = vs[128 - cb + srow];
;                         f32x4 G0[8], G1[8], G2[8];
;                         LDG(G0, 0) SB;
;                         LDG(G1, 1) SB;
;                         f32x2 c0 = {0.f, 0.f}, c1 = {0.f, 0.f};
; #pragma unroll
;                         for (int j = 0; j < 8; ++j) { c0 += S2[2 * j] * (f32x2){KA[j][0], KA[j][1]}; c1 += S2[2 * j + 1] * (f32x2){KA[j][2], KA[j][3]}; }
;                         float cs = (c0.x + c0.y) + (c1.x + c1.y);
;                         cs += dpp_f(cs, 0);
;                         const float sa = -cs;
;                         const f32x2 sa2 = {sa, sa}, v2 = {vi, vi};
;                         f32x2 y0 = {0.f, 0.f}, y1 = {0.f, 0.f};
;                         SB; LDG(G2, 2) SB; CMP(G0, 0) SB;
;                         LDG(G0, 3) SB; CMP(G1, 1) SB;
;                         CMP(G2, 2) SB;
; #pragma unroll
;                         for (int j = 0; j < 8; ++j) KA[j] = *(const f32x4*)(vs + 384 + 256 + 4 * j);
;                         SB; CMP(G0, 3) SB;
;                         float ys = (y0.x + y0.y) + (y1.x + y1.y);
;                         ys += dpp_f(ys, 0);
;                         if ((lane & 1) == 0) yb[s * 64 + srow] = ys;
	v_pk_mul_f32 v[196:197], v[0:1], v[32:33]
	v_pk_mul_f32 v[200:201], v[16:17], v[32:33]
	v_pk_mul_f32 v[204:205], v[0:1], v[48:49]
	v_pk_mul_f32 v[208:209], v[16:17], v[48:49]
	v_pk_fma_f32 v[196:197], v[2:3], v[34:35], v[196:197]
	v_pk_fma_f32 v[200:201], v[18:19], v[34:35], v[200:201]
	v_pk_fma_f32 v[204:205], v[2:3], v[50:51], v[204:205]
	v_pk_fma_f32 v[208:209], v[18:19], v[50:51], v[208:209]
	ds_read_b128 v[32:35], v232 offset:8704
	ds_read_b128 v[48:51], v232 offset:6144
	v_pk_fma_f32 v[196:197], v[4:5], v[36:37], v[196:197]
	v_pk_fma_f32 v[200:201], v[20:21], v[36:37], v[200:201]
	v_pk_fma_f32 v[204:205], v[4:5], v[52:53], v[204:205]
	v_pk_fma_f32 v[208:209], v[20:21], v[52:53], v[208:209]
	v_pk_fma_f32 v[196:197], v[6:7], v[38:39], v[196:197]
	v_pk_fma_f32 v[200:201], v[22:23], v[38:39], v[200:201]
	v_pk_fma_f32 v[204:205], v[6:7], v[54:55], v[204:205]
	v_pk_fma_f32 v[208:209], v[22:23], v[54:55], v[208:209]
	ds_read_b128 v[36:39], v232 offset:8720
	ds_read_b128 v[52:55], v232 offset:6160
	v_pk_fma_f32 v[196:197], v[8:9], v[40:41], v[196:197]
	v_pk_fma_f32 v[200:201], v[24:25], v[40:41], v[200:201]
	v_pk_fma_f32 v[204:205], v[8:9], v[56:57], v[204:205]
	v_pk_fma_f32 v[208:209], v[24:25], v[56:57], v[208:209]
	v_pk_fma_f32 v[196:197], v[10:11], v[42:43], v[196:197]
	v_pk_fma_f32 v[200:201], v[26:27], v[42:43], v[200:201]
	v_pk_fma_f32 v[204:205], v[10:11], v[58:59], v[204:205]
	v_pk_fma_f32 v[208:209], v[26:27], v[58:59], v[208:209]
	ds_read_b128 v[40:43], v232 offset:8736
	ds_read_b128 v[56:59], v232 offset:6176
	v_pk_fma_f32 v[196:197], v[12:13], v[44:45], v[196:197]
	v_pk_fma_f32 v[200:201], v[28:29], v[44:45], v[200:201]
	v_pk_fma_f32 v[204:205], v[12:13], v[60:61], v[204:205]
	v_pk_fma_f32 v[208:209], v[28:29], v[60:61], v[208:209]
	v_pk_fma_f32 v[196:197], v[14:15], v[46:47], v[196:197]
	v_pk_fma_f32 v[200:201], v[30:31], v[46:47], v[200:201]
	v_pk_fma_f32 v[204:205], v[14:15], v[62:63], v[204:205]
	v_pk_fma_f32 v[208:209], v[30:31], v[62:63], v[208:209]
	ds_read_b128 v[44:47], v232 offset:8752
	ds_read_b128 v[60:63], v232 offset:6192
	v_add_f32_e32 v212, v196, v197
	v_add_f32_e32 v213, v200, v201
	v_add_f32_e32 v214, v204, v205
	v_add_f32_e32 v215, v208, v209
	v_add_f32_dpp v212, v212, v212 quad_perm:[1,0,3,2] row_mask:0xf bank_mask:0xf
	v_add_f32_dpp v213, v213, v213 quad_perm:[1,0,3,2] row_mask:0xf bank_mask:0xf
	v_add_f32_dpp v214, v214, v214 quad_perm:[1,0,3,2] row_mask:0xf bank_mask:0xf
	v_add_f32_dpp v215, v215, v215 quad_perm:[1,0,3,2] row_mask:0xf bank_mask:0xf
	v_add_f32_dpp v212, v212, v212 quad_perm:[2,3,0,1] row_mask:0xf bank_mask:0xf
	v_add_f32_dpp v213, v213, v213 quad_perm:[2,3,0,1] row_mask:0xf bank_mask:0xf
	v_add_f32_dpp v214, v214, v214 quad_perm:[2,3,0,1] row_mask:0xf bank_mask:0xf
	v_add_f32_dpp v215, v215, v215 quad_perm:[2,3,0,1] row_mask:0xf bank_mask:0xf
	ds_write_b64 v234, v[214:215] offset:768
	s_waitcnt lgkmcnt(8)
	ds_read_b64 v[122:123], v233 offset:8192
	v_pk_mul_f32 v[216:217], v[88:89], v[212:213] op_sel_hi:[1,0] neg_lo:[0,1] neg_hi:[0,1]
	v_pk_mul_f32 v[218:219], v[90:91], v[212:213] op_sel_hi:[1,0] neg_lo:[0,1] neg_hi:[0,1]
	v_pk_mul_f32 v[220:221], v[88:89], v[212:213] op_sel:[0,1] op_sel_hi:[1,1] neg_lo:[0,1] neg_hi:[0,1]
	v_pk_mul_f32 v[222:223], v[90:91], v[212:213] op_sel:[0,1] op_sel_hi:[1,1] neg_lo:[0,1] neg_hi:[0,1]
	v_pk_fma_f32 v[216:217], v[104:105], v[120:121], v[216:217] op_sel_hi:[1,0,1]
	v_pk_fma_f32 v[218:219], v[106:107], v[120:121], v[218:219] op_sel_hi:[1,0,1]
	v_pk_fma_f32 v[220:221], v[104:105], v[120:121], v[220:221] op_sel:[0,1,0] op_sel_hi:[1,1,1]
	v_pk_fma_f32 v[222:223], v[106:107], v[120:121], v[222:223] op_sel:[0,1,0] op_sel_hi:[1,1,1]
	v_pk_fma_f32 v[0:1], v[0:1], v[180:181], v[216:217]
	v_pk_fma_f32 v[2:3], v[2:3], v[182:183], v[218:219]
	v_pk_fma_f32 v[16:17], v[16:17], v[180:181], v[220:221]
	v_pk_fma_f32 v[18:19], v[18:19], v[182:183], v[222:223]
	ds_read_b128 v[88:91], v232 offset:8960
	ds_read_b128 v[104:107], v232 offset:7936
	ds_read_b128 v[180:183], v232 offset:8448
	v_pk_mul_f32 v[224:225], v[92:93], v[212:213] op_sel_hi:[1,0] neg_lo:[0,1] neg_hi:[0,1]
	v_pk_mul_f32 v[226:227], v[94:95], v[212:213] op_sel_hi:[1,0] neg_lo:[0,1] neg_hi:[0,1]
	v_pk_mul_f32 v[228:229], v[92:93], v[212:213] op_sel:[0,1] op_sel_hi:[1,1] neg_lo:[0,1] neg_hi:[0,1]
	v_pk_mul_f32 v[230:231], v[94:95], v[212:213] op_sel:[0,1] op_sel_hi:[1,1] neg_lo:[0,1] neg_hi:[0,1]
	v_pk_fma_f32 v[224:225], v[108:109], v[120:121], v[224:225] op_sel_hi:[1,0,1]
	v_pk_fma_f32 v[226:227], v[110:111], v[120:121], v[226:227] op_sel_hi:[1,0,1]
	v_pk_fma_f32 v[228:229], v[108:109], v[120:121], v[228:229] op_sel:[0,1,0] op_sel_hi:[1,1,1]
	v_pk_fma_f32 v[230:231], v[110:111], v[120:121], v[230:231] op_sel:[0,1,0] op_sel_hi:[1,1,1]
	v_pk_fma_f32 v[4:5], v[4:5], v[184:185], v[224:225]
	v_pk_fma_f32 v[6:7], v[6:7], v[186:187], v[226:227]
	v_pk_fma_f32 v[20:21], v[20:21], v[184:185], v[228:229]
	v_pk_fma_f32 v[22:23], v[22:23], v[186:187], v[230:231]
	ds_read_b128 v[92:95], v232 offset:8976
	ds_read_b128 v[108:111], v232 offset:7952
	ds_read_b128 v[184:187], v232 offset:8464
	v_pk_mul_f32 v[216:217], v[96:97], v[212:213] op_sel_hi:[1,0] neg_lo:[0,1] neg_hi:[0,1]
	v_pk_mul_f32 v[218:219], v[98:99], v[212:213] op_sel_hi:[1,0] neg_lo:[0,1] neg_hi:[0,1]
	v_pk_mul_f32 v[220:221], v[96:97], v[212:213] op_sel:[0,1] op_sel_hi:[1,1] neg_lo:[0,1] neg_hi:[0,1]
	v_pk_mul_f32 v[222:223], v[98:99], v[212:213] op_sel:[0,1] op_sel_hi:[1,1] neg_lo:[0,1] neg_hi:[0,1]
	v_pk_fma_f32 v[216:217], v[112:113], v[120:121], v[216:217] op_sel_hi:[1,0,1]
	v_pk_fma_f32 v[218:219], v[114:115], v[120:121], v[218:219] op_sel_hi:[1,0,1]
; #define SB __builtin_amdgcn_sched_barrier(0)
; #define CMP(G, c8) { CMP1(G, 0, 2 * (c8)) CMP1(G, 1, 2 * (c8) + 1) }
; __device__ __forceinline__ void phase_scan(const Args& a, unsigned char* lds) {
;     ...
;                     for (int s = 0; s < 16; ++s) {
;                         const float* vs = vb + s * 384;
;                         const float vi = vs[128 - cb + srow];
;                         f32x4 G0[8], G1[8], G2[8];
;                         LDG(G0, 0) SB;
;                         LDG(G1, 1) SB;
;                         f32x2 c0 = {0.f, 0.f}, c1 = {0.f, 0.f};
; #pragma unroll
;                         for (int j = 0; j < 8; ++j) { c0 += S2[2 * j] * (f32x2){KA[j][0], KA[j][1]}; c1 += S2[2 * j + 1] * (f32x2){KA[j][2], KA[j][3]}; }
;                         float cs = (c0.x + c0.y) + (c1.x + c1.y);
;                         cs += dpp_f(cs, 0);
;                         const float sa = -cs;
;                         const f32x2 sa2 = {sa, sa}, v2 = {vi, vi};
;                         f32x2 y0 = {0.f, 0.f}, y1 = {0.f, 0.f};
;                         SB; LDG(G2, 2) SB; CMP(G0, 0) SB;
;                         LDG(G0, 3) SB; CMP(G1, 1) SB;
;                         CMP(G2, 2) SB;
; #pragma unroll
;                         for (int j = 0; j < 8; ++j) KA[j] = *(const f32x4*)(vs + 384 + 256 + 4 * j);
;                         SB; CMP(G0, 3) SB;
;                         float ys = (y0.x + y0.y) + (y1.x + y1.y);
;                         ys += dpp_f(ys, 0);
;                         if ((lane & 1) == 0) yb[s * 64 + srow] = ys;
	v_pk_fma_f32 v[220:221], v[112:113], v[120:121], v[220:221] op_sel:[0,1,0] op_sel_hi:[1,1,1]
	v_pk_fma_f32 v[222:223], v[114:115], v[120:121], v[222:223] op_sel:[0,1,0] op_sel_hi:[1,1,1]
	v_pk_fma_f32 v[8:9], v[8:9], v[188:189], v[216:217]
	v_pk_fma_f32 v[10:11], v[10:11], v[190:191], v[218:219]
	v_pk_fma_f32 v[24:25], v[24:25], v[188:189], v[220:221]
	v_pk_fma_f32 v[26:27], v[26:27], v[190:191], v[222:223]
	ds_read_b128 v[96:99], v232 offset:8992
	ds_read_b128 v[112:115], v232 offset:7968
	ds_read_b128 v[188:191], v232 offset:8480
	v_pk_mul_f32 v[224:225], v[100:101], v[212:213] op_sel_hi:[1,0] neg_lo:[0,1] neg_hi:[0,1]
	v_pk_mul_f32 v[226:227], v[102:103], v[212:213] op_sel_hi:[1,0] neg_lo:[0,1] neg_hi:[0,1]
	v_pk_mul_f32 v[228:229], v[100:101], v[212:213] op_sel:[0,1] op_sel_hi:[1,1] neg_lo:[0,1] neg_hi:[0,1]
	v_pk_mul_f32 v[230:231], v[102:103], v[212:213] op_sel:[0,1] op_sel_hi:[1,1] neg_lo:[0,1] neg_hi:[0,1]
	v_pk_fma_f32 v[224:225], v[116:117], v[120:121], v[224:225] op_sel_hi:[1,0,1]
	v_pk_fma_f32 v[226:227], v[118:119], v[120:121], v[226:227] op_sel_hi:[1,0,1]
	v_pk_fma_f32 v[228:229], v[116:117], v[120:121], v[228:229] op_sel:[0,1,0] op_sel_hi:[1,1,1]
	v_pk_fma_f32 v[230:231], v[118:119], v[120:121], v[230:231] op_sel:[0,1,0] op_sel_hi:[1,1,1]
	v_pk_fma_f32 v[12:13], v[12:13], v[192:193], v[224:225]
	v_pk_fma_f32 v[14:15], v[14:15], v[194:195], v[226:227]
	v_pk_fma_f32 v[28:29], v[28:29], v[192:193], v[228:229]
	v_pk_fma_f32 v[30:31], v[30:31], v[194:195], v[230:231]
	ds_read_b128 v[100:103], v232 offset:9008
	ds_read_b128 v[116:119], v232 offset:7984
	ds_read_b128 v[192:195], v232 offset:8496
	s_waitcnt lgkmcnt(13)
	v_pk_mul_f32 v[196:197], v[0:1], v[32:33]
	v_pk_mul_f32 v[200:201], v[16:17], v[32:33]
	v_pk_mul_f32 v[204:205], v[0:1], v[48:49]
	v_pk_mul_f32 v[208:209], v[16:17], v[48:49]
	v_pk_fma_f32 v[196:197], v[2:3], v[34:35], v[196:197]
	v_pk_fma_f32 v[200:201], v[18:19], v[34:35], v[200:201]
	v_pk_fma_f32 v[204:205], v[2:3], v[50:51], v[204:205]
	v_pk_fma_f32 v[208:209], v[18:19], v[50:51], v[208:209]
	ds_read_b128 v[32:35], v232 offset:10240
	ds_read_b128 v[48:51], v232 offset:7680
	v_pk_fma_f32 v[196:197], v[4:5], v[36:37], v[196:197]
	v_pk_fma_f32 v[200:201], v[20:21], v[36:37], v[200:201]
	v_pk_fma_f32 v[204:205], v[4:5], v[52:53], v[204:205]
	v_pk_fma_f32 v[208:209], v[20:21], v[52:53], v[208:209]
	v_pk_fma_f32 v[196:197], v[6:7], v[38:39], v[196:197]
	v_pk_fma_f32 v[200:201], v[22:23], v[38:39], v[200:201]
	v_pk_fma_f32 v[204:205], v[6:7], v[54:55], v[204:205]
	v_pk_fma_f32 v[208:209], v[22:23], v[54:55], v[208:209]
	ds_read_b128 v[36:39], v232 offset:10256
	ds_read_b128 v[52:55], v232 offset:7696
	v_pk_fma_f32 v[196:197], v[8:9], v[40:41], v[196:197]
	v_pk_fma_f32 v[200:201], v[24:25], v[40:41], v[200:201]
	v_pk_fma_f32 v[204:205], v[8:9], v[56:57], v[204:205]
	v_pk_fma_f32 v[208:209], v[24:25], v[56:57], v[208:209]
	v_pk_fma_f32 v[196:197], v[10:11], v[42:43], v[196:197]
	v_pk_fma_f32 v[200:201], v[26:27], v[42:43], v[200:201]
	v_pk_fma_f32 v[204:205], v[10:11], v[58:59], v[204:205]
	v_pk_fma_f32 v[208:209], v[26:27], v[58:59], v[208:209]
	ds_read_b128 v[40:43], v232 offset:10272
	ds_read_b128 v[56:59], v232 offset:7712
	v_pk_fma_f32 v[196:197], v[12:13], v[44:45], v[196:197]
	v_pk_fma_f32 v[200:201], v[28:29], v[44:45], v[200:201]
	v_pk_fma_f32 v[204:205], v[12:13], v[60:61], v[204:205]
	v_pk_fma_f32 v[208:209], v[28:29], v[60:61], v[208:209]
	v_pk_fma_f32 v[196:197], v[14:15], v[46:47], v[196:197]
	v_pk_fma_f32 v[200:201], v[30:31], v[46:47], v[200:201]
	v_pk_fma_f32 v[204:205], v[14:15], v[62:63], v[204:205]
	v_pk_fma_f32 v[208:209], v[30:31], v[62:63], v[208:209]
	ds_read_b128 v[44:47], v232 offset:10288
	ds_read_b128 v[60:63], v232 offset:7728
	v_add_f32_e32 v212, v196, v197
	v_add_f32_e32 v213, v200, v201
	v_add_f32_e32 v214, v204, v205
	v_add_f32_e32 v215, v208, v209
	v_add_f32_dpp v212, v212, v212 quad_perm:[1,0,3,2] row_mask:0xf bank_mask:0xf
	v_add_f32_dpp v213, v213, v213 quad_perm:[1,0,3,2] row_mask:0xf bank_mask:0xf
	v_add_f32_dpp v214, v214, v214 quad_perm:[1,0,3,2] row_mask:0xf bank_mask:0xf
	v_add_f32_dpp v215, v215, v215 quad_perm:[1,0,3,2] row_mask:0xf bank_mask:0xf
	v_add_f32_dpp v212, v212, v212 quad_perm:[2,3,0,1] row_mask:0xf bank_mask:0xf
	v_add_f32_dpp v213, v213, v213 quad_perm:[2,3,0,1] row_mask:0xf bank_mask:0xf
	v_add_f32_dpp v214, v214, v214 quad_perm:[2,3,0,1] row_mask:0xf bank_mask:0xf
	v_add_f32_dpp v215, v215, v215 quad_perm:[2,3,0,1] row_mask:0xf bank_mask:0xf
	ds_write_b64 v234, v[214:215] offset:1024
	s_waitcnt lgkmcnt(8)
; #define SB __builtin_amdgcn_sched_barrier(0)
; #define CMP(G, c8) { CMP1(G, 0, 2 * (c8)) CMP1(G, 1, 2 * (c8) + 1) }
; __device__ __forceinline__ void phase_scan(const Args& a, unsigned char* lds) {
;     ...
;                     for (int s = 0; s < 16; ++s) {
;                         const float* vs = vb + s * 384;
;                         const float vi = vs[128 - cb + srow];
;                         f32x4 G0[8], G1[8], G2[8];
;                         LDG(G0, 0) SB;
;                         LDG(G1, 1) SB;
;                         f32x2 c0 = {0.f, 0.f}, c1 = {0.f, 0.f};
; #pragma unroll
;                         for (int j = 0; j < 8; ++j) { c0 += S2[2 * j] * (f32x2){KA[j][0], KA[j][1]}; c1 += S2[2 * j + 1] * (f32x2){KA[j][2], KA[j][3]}; }
;                         float cs = (c0.x + c0.y) + (c1.x + c1.y);
;                         cs += dpp_f(cs, 0);
;                         const float sa = -cs;
;                         const f32x2 sa2 = {sa, sa}, v2 = {vi, vi};
;                         f32x2 y0 = {0.f, 0.f}, y1 = {0.f, 0.f};
;                         SB; LDG(G2, 2) SB; CMP(G0, 0) SB;
;                         LDG(G0, 3) SB; CMP(G1, 1) SB;
;                         CMP(G2, 2) SB;
; #pragma unroll
;                         for (int j = 0; j < 8; ++j) KA[j] = *(const f32x4*)(vs + 384 + 256 + 4 * j);
;                         SB; CMP(G0, 3) SB;
;                         float ys = (y0.x + y0.y) + (y1.x + y1.y);
;                         ys += dpp_f(ys, 0);
;                         if ((lane & 1) == 0) yb[s * 64 + srow] = ys;
	ds_read_b64 v[120:121], v233 offset:9728
	v_pk_mul_f32 v[216:217], v[88:89], v[212:213] op_sel_hi:[1,0] neg_lo:[0,1] neg_hi:[0,1]
	v_pk_mul_f32 v[218:219], v[90:91], v[212:213] op_sel_hi:[1,0] neg_lo:[0,1] neg_hi:[0,1]
	v_pk_mul_f32 v[220:221], v[88:89], v[212:213] op_sel:[0,1] op_sel_hi:[1,1] neg_lo:[0,1] neg_hi:[0,1]
	v_pk_mul_f32 v[222:223], v[90:91], v[212:213] op_sel:[0,1] op_sel_hi:[1,1] neg_lo:[0,1] neg_hi:[0,1]
	v_pk_fma_f32 v[216:217], v[104:105], v[122:123], v[216:217] op_sel_hi:[1,0,1]
	v_pk_fma_f32 v[218:219], v[106:107], v[122:123], v[218:219] op_sel_hi:[1,0,1]
	v_pk_fma_f32 v[220:221], v[104:105], v[122:123], v[220:221] op_sel:[0,1,0] op_sel_hi:[1,1,1]
	v_pk_fma_f32 v[222:223], v[106:107], v[122:123], v[222:223] op_sel:[0,1,0] op_sel_hi:[1,1,1]
	v_pk_fma_f32 v[0:1], v[0:1], v[180:181], v[216:217]
	v_pk_fma_f32 v[2:3], v[2:3], v[182:183], v[218:219]
	v_pk_fma_f32 v[16:17], v[16:17], v[180:181], v[220:221]
	v_pk_fma_f32 v[18:19], v[18:19], v[182:183], v[222:223]
	ds_read_b128 v[88:91], v232 offset:10496
	ds_read_b128 v[104:107], v232 offset:9472
	ds_read_b128 v[180:183], v232 offset:9984
	v_pk_mul_f32 v[224:225], v[92:93], v[212:213] op_sel_hi:[1,0] neg_lo:[0,1] neg_hi:[0,1]
	v_pk_mul_f32 v[226:227], v[94:95], v[212:213] op_sel_hi:[1,0] neg_lo:[0,1] neg_hi:[0,1]
	v_pk_mul_f32 v[228:229], v[92:93], v[212:213] op_sel:[0,1] op_sel_hi:[1,1] neg_lo:[0,1] neg_hi:[0,1]
	v_pk_mul_f32 v[230:231], v[94:95], v[212:213] op_sel:[0,1] op_sel_hi:[1,1] neg_lo:[0,1] neg_hi:[0,1]
	v_pk_fma_f32 v[224:225], v[108:109], v[122:123], v[224:225] op_sel_hi:[1,0,1]
	v_pk_fma_f32 v[226:227], v[110:111], v[122:123], v[226:227] op_sel_hi:[1,0,1]
	v_pk_fma_f32 v[228:229], v[108:109], v[122:123], v[228:229] op_sel:[0,1,0] op_sel_hi:[1,1,1]
	v_pk_fma_f32 v[230:231], v[110:111], v[122:123], v[230:231] op_sel:[0,1,0] op_sel_hi:[1,1,1]
	v_pk_fma_f32 v[4:5], v[4:5], v[184:185], v[224:225]
	v_pk_fma_f32 v[6:7], v[6:7], v[186:187], v[226:227]
	v_pk_fma_f32 v[20:21], v[20:21], v[184:185], v[228:229]
	v_pk_fma_f32 v[22:23], v[22:23], v[186:187], v[230:231]
	ds_read_b128 v[92:95], v232 offset:10512
	ds_read_b128 v[108:111], v232 offset:9488
	ds_read_b128 v[184:187], v232 offset:10000
	v_pk_mul_f32 v[216:217], v[96:97], v[212:213] op_sel_hi:[1,0] neg_lo:[0,1] neg_hi:[0,1]
	v_pk_mul_f32 v[218:219], v[98:99], v[212:213] op_sel_hi:[1,0] neg_lo:[0,1] neg_hi:[0,1]
	v_pk_mul_f32 v[220:221], v[96:97], v[212:213] op_sel:[0,1] op_sel_hi:[1,1] neg_lo:[0,1] neg_hi:[0,1]
	v_pk_mul_f32 v[222:223], v[98:99], v[212:213] op_sel:[0,1] op_sel_hi:[1,1] neg_lo:[0,1] neg_hi:[0,1]
	v_pk_fma_f32 v[216:217], v[112:113], v[122:123], v[216:217] op_sel_hi:[1,0,1]
	v_pk_fma_f32 v[218:219], v[114:115], v[122:123], v[218:219] op_sel_hi:[1,0,1]
	v_pk_fma_f32 v[220:221], v[112:113], v[122:123], v[220:221] op_sel:[0,1,0] op_sel_hi:[1,1,1]
	v_pk_fma_f32 v[222:223], v[114:115], v[122:123], v[222:223] op_sel:[0,1,0] op_sel_hi:[1,1,1]
	v_pk_fma_f32 v[8:9], v[8:9], v[188:189], v[216:217]
	v_pk_fma_f32 v[10:11], v[10:11], v[190:191], v[218:219]
	v_pk_fma_f32 v[24:25], v[24:25], v[188:189], v[220:221]
	v_pk_fma_f32 v[26:27], v[26:27], v[190:191], v[222:223]
	ds_read_b128 v[96:99], v232 offset:10528
	ds_read_b128 v[112:115], v232 offset:9504
	ds_read_b128 v[188:191], v232 offset:10016
	v_pk_mul_f32 v[224:225], v[100:101], v[212:213] op_sel_hi:[1,0] neg_lo:[0,1] neg_hi:[0,1]
	v_pk_mul_f32 v[226:227], v[102:103], v[212:213] op_sel_hi:[1,0] neg_lo:[0,1] neg_hi:[0,1]
	v_pk_mul_f32 v[228:229], v[100:101], v[212:213] op_sel:[0,1] op_sel_hi:[1,1] neg_lo:[0,1] neg_hi:[0,1]
	v_pk_mul_f32 v[230:231], v[102:103], v[212:213] op_sel:[0,1] op_sel_hi:[1,1] neg_lo:[0,1] neg_hi:[0,1]
	v_pk_fma_f32 v[224:225], v[116:117], v[122:123], v[224:225] op_sel_hi:[1,0,1]
	v_pk_fma_f32 v[226:227], v[118:119], v[122:123], v[226:227] op_sel_hi:[1,0,1]
	v_pk_fma_f32 v[228:229], v[116:117], v[122:123], v[228:229] op_sel:[0,1,0] op_sel_hi:[1,1,1]
	v_pk_fma_f32 v[230:231], v[118:119], v[122:123], v[230:231] op_sel:[0,1,0] op_sel_hi:[1,1,1]
	v_pk_fma_f32 v[12:13], v[12:13], v[192:193], v[224:225]
	v_pk_fma_f32 v[14:15], v[14:15], v[194:195], v[226:227]
	v_pk_fma_f32 v[28:29], v[28:29], v[192:193], v[228:229]
	v_pk_fma_f32 v[30:31], v[30:31], v[194:195], v[230:231]
	ds_read_b128 v[100:103], v232 offset:10544
	ds_read_b128 v[116:119], v232 offset:9520
	ds_read_b128 v[192:195], v232 offset:10032
	s_waitcnt lgkmcnt(13)
; #define SB __builtin_amdgcn_sched_barrier(0)
; #define CMP(G, c8) { CMP1(G, 0, 2 * (c8)) CMP1(G, 1, 2 * (c8) + 1) }
; __device__ __forceinline__ void phase_scan(const Args& a, unsigned char* lds) {
;     ...
;                     for (int s = 0; s < 16; ++s) {
;                         const float* vs = vb + s * 384;
;                         const float vi = vs[128 - cb + srow];
;                         f32x4 G0[8], G1[8], G2[8];
;                         LDG(G0, 0) SB;
;                         LDG(G1, 1) SB;
;                         f32x2 c0 = {0.f, 0.f}, c1 = {0.f, 0.f};
; #pragma unroll
;                         for (int j = 0; j < 8; ++j) { c0 += S2[2 * j] * (f32x2){KA[j][0], KA[j][1]}; c1 += S2[2 * j + 1] * (f32x2){KA[j][2], KA[j][3]}; }
;                         float cs = (c0.x + c0.y) + (c1.x + c1.y);
;                         cs += dpp_f(cs, 0);
;                         const float sa = -cs;
;                         const f32x2 sa2 = {sa, sa}, v2 = {vi, vi};
;                         f32x2 y0 = {0.f, 0.f}, y1 = {0.f, 0.f};
;                         SB; LDG(G2, 2) SB; CMP(G0, 0) SB;
;                         LDG(G0, 3) SB; CMP(G1, 1) SB;
;                         CMP(G2, 2) SB;
; #pragma unroll
;                         for (int j = 0; j < 8; ++j) KA[j] = *(const f32x4*)(vs + 384 + 256 + 4 * j);
;                         SB; CMP(G0, 3) SB;
;                         float ys = (y0.x + y0.y) + (y1.x + y1.y);
;                         ys += dpp_f(ys, 0);
;                         if ((lane & 1) == 0) yb[s * 64 + srow] = ys;
	v_pk_mul_f32 v[196:197], v[0:1], v[32:33]
	v_pk_mul_f32 v[200:201], v[16:17], v[32:33]
	v_pk_mul_f32 v[204:205], v[0:1], v[48:49]
	v_pk_mul_f32 v[208:209], v[16:17], v[48:49]
	v_pk_fma_f32 v[196:197], v[2:3], v[34:35], v[196:197]
	v_pk_fma_f32 v[200:201], v[18:19], v[34:35], v[200:201]
	v_pk_fma_f32 v[204:205], v[2:3], v[50:51], v[204:205]
	v_pk_fma_f32 v[208:209], v[18:19], v[50:51], v[208:209]
	ds_read_b128 v[32:35], v232 offset:11776
	ds_read_b128 v[48:51], v232 offset:9216
	v_pk_fma_f32 v[196:197], v[4:5], v[36:37], v[196:197]
	v_pk_fma_f32 v[200:201], v[20:21], v[36:37], v[200:201]
	v_pk_fma_f32 v[204:205], v[4:5], v[52:53], v[204:205]
	v_pk_fma_f32 v[208:209], v[20:21], v[52:53], v[208:209]
	v_pk_fma_f32 v[196:197], v[6:7], v[38:39], v[196:197]
	v_pk_fma_f32 v[200:201], v[22:23], v[38:39], v[200:201]
	v_pk_fma_f32 v[204:205], v[6:7], v[54:55], v[204:205]
	v_pk_fma_f32 v[208:209], v[22:23], v[54:55], v[208:209]
	ds_read_b128 v[36:39], v232 offset:11792
	ds_read_b128 v[52:55], v232 offset:9232
	v_pk_fma_f32 v[196:197], v[8:9], v[40:41], v[196:197]
	v_pk_fma_f32 v[200:201], v[24:25], v[40:41], v[200:201]
	v_pk_fma_f32 v[204:205], v[8:9], v[56:57], v[204:205]
	v_pk_fma_f32 v[208:209], v[24:25], v[56:57], v[208:209]
	v_pk_fma_f32 v[196:197], v[10:11], v[42:43], v[196:197]
	v_pk_fma_f32 v[200:201], v[26:27], v[42:43], v[200:201]
	v_pk_fma_f32 v[204:205], v[10:11], v[58:59], v[204:205]
	v_pk_fma_f32 v[208:209], v[26:27], v[58:59], v[208:209]
	ds_read_b128 v[40:43], v232 offset:11808
	ds_read_b128 v[56:59], v232 offset:9248
	v_pk_fma_f32 v[196:197], v[12:13], v[44:45], v[196:197]
	v_pk_fma_f32 v[200:201], v[28:29], v[44:45], v[200:201]
	v_pk_fma_f32 v[204:205], v[12:13], v[60:61], v[204:205]
	v_pk_fma_f32 v[208:209], v[28:29], v[60:61], v[208:209]
	v_pk_fma_f32 v[196:197], v[14:15], v[46:47], v[196:197]
	v_pk_fma_f32 v[200:201], v[30:31], v[46:47], v[200:201]
	v_pk_fma_f32 v[204:205], v[14:15], v[62:63], v[204:205]
	v_pk_fma_f32 v[208:209], v[30:31], v[62:63], v[208:209]
	ds_read_b128 v[44:47], v232 offset:11824
	ds_read_b128 v[60:63], v232 offset:9264
	v_add_f32_e32 v212, v196, v197
	v_add_f32_e32 v213, v200, v201
	v_add_f32_e32 v214, v204, v205
	v_add_f32_e32 v215, v208, v209
	v_add_f32_dpp v212, v212, v212 quad_perm:[1,0,3,2] row_mask:0xf bank_mask:0xf
	v_add_f32_dpp v213, v213, v213 quad_perm:[1,0,3,2] row_mask:0xf bank_mask:0xf
	v_add_f32_dpp v214, v214, v214 quad_perm:[1,0,3,2] row_mask:0xf bank_mask:0xf
	v_add_f32_dpp v215, v215, v215 quad_perm:[1,0,3,2] row_mask:0xf bank_mask:0xf
	v_add_f32_dpp v212, v212, v212 quad_perm:[2,3,0,1] row_mask:0xf bank_mask:0xf
	v_add_f32_dpp v213, v213, v213 quad_perm:[2,3,0,1] row_mask:0xf bank_mask:0xf
	v_add_f32_dpp v214, v214, v214 quad_perm:[2,3,0,1] row_mask:0xf bank_mask:0xf
	v_add_f32_dpp v215, v215, v215 quad_perm:[2,3,0,1] row_mask:0xf bank_mask:0xf
	ds_write_b64 v234, v[214:215] offset:1280
	s_waitcnt lgkmcnt(8)
	ds_read_b64 v[122:123], v233 offset:11264
	v_pk_mul_f32 v[216:217], v[88:89], v[212:213] op_sel_hi:[1,0] neg_lo:[0,1] neg_hi:[0,1]
	v_pk_mul_f32 v[218:219], v[90:91], v[212:213] op_sel_hi:[1,0] neg_lo:[0,1] neg_hi:[0,1]
	v_pk_mul_f32 v[220:221], v[88:89], v[212:213] op_sel:[0,1] op_sel_hi:[1,1] neg_lo:[0,1] neg_hi:[0,1]
	v_pk_mul_f32 v[222:223], v[90:91], v[212:213] op_sel:[0,1] op_sel_hi:[1,1] neg_lo:[0,1] neg_hi:[0,1]
	v_pk_fma_f32 v[216:217], v[104:105], v[120:121], v[216:217] op_sel_hi:[1,0,1]
	v_pk_fma_f32 v[218:219], v[106:107], v[120:121], v[218:219] op_sel_hi:[1,0,1]
	v_pk_fma_f32 v[220:221], v[104:105], v[120:121], v[220:221] op_sel:[0,1,0] op_sel_hi:[1,1,1]
	v_pk_fma_f32 v[222:223], v[106:107], v[120:121], v[222:223] op_sel:[0,1,0] op_sel_hi:[1,1,1]
	v_pk_fma_f32 v[0:1], v[0:1], v[180:181], v[216:217]
	v_pk_fma_f32 v[2:3], v[2:3], v[182:183], v[218:219]
	v_pk_fma_f32 v[16:17], v[16:17], v[180:181], v[220:221]
	v_pk_fma_f32 v[18:19], v[18:19], v[182:183], v[222:223]
	ds_read_b128 v[88:91], v232 offset:12032
	ds_read_b128 v[104:107], v232 offset:11008
	ds_read_b128 v[180:183], v232 offset:11520
	v_pk_mul_f32 v[224:225], v[92:93], v[212:213] op_sel_hi:[1,0] neg_lo:[0,1] neg_hi:[0,1]
	v_pk_mul_f32 v[226:227], v[94:95], v[212:213] op_sel_hi:[1,0] neg_lo:[0,1] neg_hi:[0,1]
	v_pk_mul_f32 v[228:229], v[92:93], v[212:213] op_sel:[0,1] op_sel_hi:[1,1] neg_lo:[0,1] neg_hi:[0,1]
	v_pk_mul_f32 v[230:231], v[94:95], v[212:213] op_sel:[0,1] op_sel_hi:[1,1] neg_lo:[0,1] neg_hi:[0,1]
	v_pk_fma_f32 v[224:225], v[108:109], v[120:121], v[224:225] op_sel_hi:[1,0,1]
	v_pk_fma_f32 v[226:227], v[110:111], v[120:121], v[226:227] op_sel_hi:[1,0,1]
	v_pk_fma_f32 v[228:229], v[108:109], v[120:121], v[228:229] op_sel:[0,1,0] op_sel_hi:[1,1,1]
	v_pk_fma_f32 v[230:231], v[110:111], v[120:121], v[230:231] op_sel:[0,1,0] op_sel_hi:[1,1,1]
	v_pk_fma_f32 v[4:5], v[4:5], v[184:185], v[224:225]
	v_pk_fma_f32 v[6:7], v[6:7], v[186:187], v[226:227]
	v_pk_fma_f32 v[20:21], v[20:21], v[184:185], v[228:229]
	v_pk_fma_f32 v[22:23], v[22:23], v[186:187], v[230:231]
	ds_read_b128 v[92:95], v232 offset:12048
	ds_read_b128 v[108:111], v232 offset:11024
	ds_read_b128 v[184:187], v232 offset:11536
	v_pk_mul_f32 v[216:217], v[96:97], v[212:213] op_sel_hi:[1,0] neg_lo:[0,1] neg_hi:[0,1]
	v_pk_mul_f32 v[218:219], v[98:99], v[212:213] op_sel_hi:[1,0] neg_lo:[0,1] neg_hi:[0,1]
	v_pk_mul_f32 v[220:221], v[96:97], v[212:213] op_sel:[0,1] op_sel_hi:[1,1] neg_lo:[0,1] neg_hi:[0,1]
	v_pk_mul_f32 v[222:223], v[98:99], v[212:213] op_sel:[0,1] op_sel_hi:[1,1] neg_lo:[0,1] neg_hi:[0,1]
	v_pk_fma_f32 v[216:217], v[112:113], v[120:121], v[216:217] op_sel_hi:[1,0,1]
	v_pk_fma_f32 v[218:219], v[114:115], v[120:121], v[218:219] op_sel_hi:[1,0,1]
; #define SB __builtin_amdgcn_sched_barrier(0)
; #define CMP(G, c8) { CMP1(G, 0, 2 * (c8)) CMP1(G, 1, 2 * (c8) + 1) }
; __device__ __forceinline__ void phase_scan(const Args& a, unsigned char* lds) {
;     ...
;                     for (int s = 0; s < 16; ++s) {
;                         const float* vs = vb + s * 384;
;                         const float vi = vs[128 - cb + srow];
;                         f32x4 G0[8], G1[8], G2[8];
;                         LDG(G0, 0) SB;
;                         LDG(G1, 1) SB;
;                         f32x2 c0 = {0.f, 0.f}, c1 = {0.f, 0.f};
; #pragma unroll
;                         for (int j = 0; j < 8; ++j) { c0 += S2[2 * j] * (f32x2){KA[j][0], KA[j][1]}; c1 += S2[2 * j + 1] * (f32x2){KA[j][2], KA[j][3]}; }
;                         float cs = (c0.x + c0.y) + (c1.x + c1.y);
;                         cs += dpp_f(cs, 0);
;                         const float sa = -cs;
;                         const f32x2 sa2 = {sa, sa}, v2 = {vi, vi};
;                         f32x2 y0 = {0.f, 0.f}, y1 = {0.f, 0.f};
;                         SB; LDG(G2, 2) SB; CMP(G0, 0) SB;
;                         LDG(G0, 3) SB; CMP(G1, 1) SB;
;                         CMP(G2, 2) SB;
; #pragma unroll
;                         for (int j = 0; j < 8; ++j) KA[j] = *(const f32x4*)(vs + 384 + 256 + 4 * j);
;                         SB; CMP(G0, 3) SB;
;                         float ys = (y0.x + y0.y) + (y1.x + y1.y);
;                         ys += dpp_f(ys, 0);
;                         if ((lane & 1) == 0) yb[s * 64 + srow] = ys;
	v_pk_fma_f32 v[220:221], v[112:113], v[120:121], v[220:221] op_sel:[0,1,0] op_sel_hi:[1,1,1]
	v_pk_fma_f32 v[222:223], v[114:115], v[120:121], v[222:223] op_sel:[0,1,0] op_sel_hi:[1,1,1]
	v_pk_fma_f32 v[8:9], v[8:9], v[188:189], v[216:217]
	v_pk_fma_f32 v[10:11], v[10:11], v[190:191], v[218:219]
	v_pk_fma_f32 v[24:25], v[24:25], v[188:189], v[220:221]
	v_pk_fma_f32 v[26:27], v[26:27], v[190:191], v[222:223]
	ds_read_b128 v[96:99], v232 offset:12064
	ds_read_b128 v[112:115], v232 offset:11040
	ds_read_b128 v[188:191], v232 offset:11552
	v_pk_mul_f32 v[224:225], v[100:101], v[212:213] op_sel_hi:[1,0] neg_lo:[0,1] neg_hi:[0,1]
	v_pk_mul_f32 v[226:227], v[102:103], v[212:213] op_sel_hi:[1,0] neg_lo:[0,1] neg_hi:[0,1]
	v_pk_mul_f32 v[228:229], v[100:101], v[212:213] op_sel:[0,1] op_sel_hi:[1,1] neg_lo:[0,1] neg_hi:[0,1]
	v_pk_mul_f32 v[230:231], v[102:103], v[212:213] op_sel:[0,1] op_sel_hi:[1,1] neg_lo:[0,1] neg_hi:[0,1]
	v_pk_fma_f32 v[224:225], v[116:117], v[120:121], v[224:225] op_sel_hi:[1,0,1]
	v_pk_fma_f32 v[226:227], v[118:119], v[120:121], v[226:227] op_sel_hi:[1,0,1]
	v_pk_fma_f32 v[228:229], v[116:117], v[120:121], v[228:229] op_sel:[0,1,0] op_sel_hi:[1,1,1]
	v_pk_fma_f32 v[230:231], v[118:119], v[120:121], v[230:231] op_sel:[0,1,0] op_sel_hi:[1,1,1]
	v_pk_fma_f32 v[12:13], v[12:13], v[192:193], v[224:225]
	v_pk_fma_f32 v[14:15], v[14:15], v[194:195], v[226:227]
	v_pk_fma_f32 v[28:29], v[28:29], v[192:193], v[228:229]
	v_pk_fma_f32 v[30:31], v[30:31], v[194:195], v[230:231]
	ds_read_b128 v[100:103], v232 offset:12080
	ds_read_b128 v[116:119], v232 offset:11056
	ds_read_b128 v[192:195], v232 offset:11568
	s_waitcnt lgkmcnt(13)
	v_pk_mul_f32 v[196:197], v[0:1], v[32:33]
	v_pk_mul_f32 v[200:201], v[16:17], v[32:33]
	v_pk_mul_f32 v[204:205], v[0:1], v[48:49]
	v_pk_mul_f32 v[208:209], v[16:17], v[48:49]
	v_pk_fma_f32 v[196:197], v[2:3], v[34:35], v[196:197]
	v_pk_fma_f32 v[200:201], v[18:19], v[34:35], v[200:201]
	v_pk_fma_f32 v[204:205], v[2:3], v[50:51], v[204:205]
	v_pk_fma_f32 v[208:209], v[18:19], v[50:51], v[208:209]
	ds_read_b128 v[32:35], v232 offset:13312
	ds_read_b128 v[48:51], v232 offset:10752
	v_pk_fma_f32 v[196:197], v[4:5], v[36:37], v[196:197]
	v_pk_fma_f32 v[200:201], v[20:21], v[36:37], v[200:201]
	v_pk_fma_f32 v[204:205], v[4:5], v[52:53], v[204:205]
	v_pk_fma_f32 v[208:209], v[20:21], v[52:53], v[208:209]
	v_pk_fma_f32 v[196:197], v[6:7], v[38:39], v[196:197]
	v_pk_fma_f32 v[200:201], v[22:23], v[38:39], v[200:201]
	v_pk_fma_f32 v[204:205], v[6:7], v[54:55], v[204:205]
	v_pk_fma_f32 v[208:209], v[22:23], v[54:55], v[208:209]
	ds_read_b128 v[36:39], v232 offset:13328
	ds_read_b128 v[52:55], v232 offset:10768
	v_pk_fma_f32 v[196:197], v[8:9], v[40:41], v[196:197]
	v_pk_fma_f32 v[200:201], v[24:25], v[40:41], v[200:201]
	v_pk_fma_f32 v[204:205], v[8:9], v[56:57], v[204:205]
	v_pk_fma_f32 v[208:209], v[24:25], v[56:57], v[208:209]
	v_pk_fma_f32 v[196:197], v[10:11], v[42:43], v[196:197]
	v_pk_fma_f32 v[200:201], v[26:27], v[42:43], v[200:201]
	v_pk_fma_f32 v[204:205], v[10:11], v[58:59], v[204:205]
	v_pk_fma_f32 v[208:209], v[26:27], v[58:59], v[208:209]
	ds_read_b128 v[40:43], v232 offset:13344
	ds_read_b128 v[56:59], v232 offset:10784
	v_pk_fma_f32 v[196:197], v[12:13], v[44:45], v[196:197]
	v_pk_fma_f32 v[200:201], v[28:29], v[44:45], v[200:201]
	v_pk_fma_f32 v[204:205], v[12:13], v[60:61], v[204:205]
	v_pk_fma_f32 v[208:209], v[28:29], v[60:61], v[208:209]
	v_pk_fma_f32 v[196:197], v[14:15], v[46:47], v[196:197]
	v_pk_fma_f32 v[200:201], v[30:31], v[46:47], v[200:201]
	v_pk_fma_f32 v[204:205], v[14:15], v[62:63], v[204:205]
	v_pk_fma_f32 v[208:209], v[30:31], v[62:63], v[208:209]
	ds_read_b128 v[44:47], v232 offset:13360
	ds_read_b128 v[60:63], v232 offset:10800
	v_add_f32_e32 v212, v196, v197
	v_add_f32_e32 v213, v200, v201
	v_add_f32_e32 v214, v204, v205
	v_add_f32_e32 v215, v208, v209
	v_add_f32_dpp v212, v212, v212 quad_perm:[1,0,3,2] row_mask:0xf bank_mask:0xf
	v_add_f32_dpp v213, v213, v213 quad_perm:[1,0,3,2] row_mask:0xf bank_mask:0xf
	v_add_f32_dpp v214, v214, v214 quad_perm:[1,0,3,2] row_mask:0xf bank_mask:0xf
	v_add_f32_dpp v215, v215, v215 quad_perm:[1,0,3,2] row_mask:0xf bank_mask:0xf
	v_add_f32_dpp v212, v212, v212 quad_perm:[2,3,0,1] row_mask:0xf bank_mask:0xf
	v_add_f32_dpp v213, v213, v213 quad_perm:[2,3,0,1] row_mask:0xf bank_mask:0xf
	v_add_f32_dpp v214, v214, v214 quad_perm:[2,3,0,1] row_mask:0xf bank_mask:0xf
	v_add_f32_dpp v215, v215, v215 quad_perm:[2,3,0,1] row_mask:0xf bank_mask:0xf
	ds_write_b64 v234, v[214:215] offset:1536
	s_waitcnt lgkmcnt(8)
; #define SB __builtin_amdgcn_sched_barrier(0)
; #define CMP(G, c8) { CMP1(G, 0, 2 * (c8)) CMP1(G, 1, 2 * (c8) + 1) }
; __device__ __forceinline__ void phase_scan(const Args& a, unsigned char* lds) {
;     ...
;                     for (int s = 0; s < 16; ++s) {
;                         const float* vs = vb + s * 384;
;                         const float vi = vs[128 - cb + srow];
;                         f32x4 G0[8], G1[8], G2[8];
;                         LDG(G0, 0) SB;
;                         LDG(G1, 1) SB;
;                         f32x2 c0 = {0.f, 0.f}, c1 = {0.f, 0.f};
; #pragma unroll
;                         for (int j = 0; j < 8; ++j) { c0 += S2[2 * j] * (f32x2){KA[j][0], KA[j][1]}; c1 += S2[2 * j + 1] * (f32x2){KA[j][2], KA[j][3]}; }
;                         float cs = (c0.x + c0.y) + (c1.x + c1.y);
;                         cs += dpp_f(cs, 0);
;                         const float sa = -cs;
;                         const f32x2 sa2 = {sa, sa}, v2 = {vi, vi};
;                         f32x2 y0 = {0.f, 0.f}, y1 = {0.f, 0.f};
;                         SB; LDG(G2, 2) SB; CMP(G0, 0) SB;
;                         LDG(G0, 3) SB; CMP(G1, 1) SB;
;                         CMP(G2, 2) SB;
; #pragma unroll
;                         for (int j = 0; j < 8; ++j) KA[j] = *(const f32x4*)(vs + 384 + 256 + 4 * j);
;                         SB; CMP(G0, 3) SB;
;                         float ys = (y0.x + y0.y) + (y1.x + y1.y);
;                         ys += dpp_f(ys, 0);
;                         if ((lane & 1) == 0) yb[s * 64 + srow] = ys;
	ds_read_b64 v[120:121], v233 offset:12800
	v_pk_mul_f32 v[216:217], v[88:89], v[212:213] op_sel_hi:[1,0] neg_lo:[0,1] neg_hi:[0,1]
	v_pk_mul_f32 v[218:219], v[90:91], v[212:213] op_sel_hi:[1,0] neg_lo:[0,1] neg_hi:[0,1]
	v_pk_mul_f32 v[220:221], v[88:89], v[212:213] op_sel:[0,1] op_sel_hi:[1,1] neg_lo:[0,1] neg_hi:[0,1]
	v_pk_mul_f32 v[222:223], v[90:91], v[212:213] op_sel:[0,1] op_sel_hi:[1,1] neg_lo:[0,1] neg_hi:[0,1]
	v_pk_fma_f32 v[216:217], v[104:105], v[122:123], v[216:217] op_sel_hi:[1,0,1]
	v_pk_fma_f32 v[218:219], v[106:107], v[122:123], v[218:219] op_sel_hi:[1,0,1]
	v_pk_fma_f32 v[220:221], v[104:105], v[122:123], v[220:221] op_sel:[0,1,0] op_sel_hi:[1,1,1]
	v_pk_fma_f32 v[222:223], v[106:107], v[122:123], v[222:223] op_sel:[0,1,0] op_sel_hi:[1,1,1]
	v_pk_fma_f32 v[0:1], v[0:1], v[180:181], v[216:217]
	v_pk_fma_f32 v[2:3], v[2:3], v[182:183], v[218:219]
	v_pk_fma_f32 v[16:17], v[16:17], v[180:181], v[220:221]
	v_pk_fma_f32 v[18:19], v[18:19], v[182:183], v[222:223]
	ds_read_b128 v[88:91], v232 offset:13568
	ds_read_b128 v[104:107], v232 offset:12544
	ds_read_b128 v[180:183], v232 offset:13056
	v_pk_mul_f32 v[224:225], v[92:93], v[212:213] op_sel_hi:[1,0] neg_lo:[0,1] neg_hi:[0,1]
	v_pk_mul_f32 v[226:227], v[94:95], v[212:213] op_sel_hi:[1,0] neg_lo:[0,1] neg_hi:[0,1]
	v_pk_mul_f32 v[228:229], v[92:93], v[212:213] op_sel:[0,1] op_sel_hi:[1,1] neg_lo:[0,1] neg_hi:[0,1]
	v_pk_mul_f32 v[230:231], v[94:95], v[212:213] op_sel:[0,1] op_sel_hi:[1,1] neg_lo:[0,1] neg_hi:[0,1]
	v_pk_fma_f32 v[224:225], v[108:109], v[122:123], v[224:225] op_sel_hi:[1,0,1]
	v_pk_fma_f32 v[226:227], v[110:111], v[122:123], v[226:227] op_sel_hi:[1,0,1]
	v_pk_fma_f32 v[228:229], v[108:109], v[122:123], v[228:229] op_sel:[0,1,0] op_sel_hi:[1,1,1]
	v_pk_fma_f32 v[230:231], v[110:111], v[122:123], v[230:231] op_sel:[0,1,0] op_sel_hi:[1,1,1]
	v_pk_fma_f32 v[4:5], v[4:5], v[184:185], v[224:225]
	v_pk_fma_f32 v[6:7], v[6:7], v[186:187], v[226:227]
	v_pk_fma_f32 v[20:21], v[20:21], v[184:185], v[228:229]
	v_pk_fma_f32 v[22:23], v[22:23], v[186:187], v[230:231]
	ds_read_b128 v[92:95], v232 offset:13584
	ds_read_b128 v[108:111], v232 offset:12560
	ds_read_b128 v[184:187], v232 offset:13072
	v_pk_mul_f32 v[216:217], v[96:97], v[212:213] op_sel_hi:[1,0] neg_lo:[0,1] neg_hi:[0,1]
	v_pk_mul_f32 v[218:219], v[98:99], v[212:213] op_sel_hi:[1,0] neg_lo:[0,1] neg_hi:[0,1]
	v_pk_mul_f32 v[220:221], v[96:97], v[212:213] op_sel:[0,1] op_sel_hi:[1,1] neg_lo:[0,1] neg_hi:[0,1]
	v_pk_mul_f32 v[222:223], v[98:99], v[212:213] op_sel:[0,1] op_sel_hi:[1,1] neg_lo:[0,1] neg_hi:[0,1]
	v_pk_fma_f32 v[216:217], v[112:113], v[122:123], v[216:217] op_sel_hi:[1,0,1]
	v_pk_fma_f32 v[218:219], v[114:115], v[122:123], v[218:219] op_sel_hi:[1,0,1]
	v_pk_fma_f32 v[220:221], v[112:113], v[122:123], v[220:221] op_sel:[0,1,0] op_sel_hi:[1,1,1]
	v_pk_fma_f32 v[222:223], v[114:115], v[122:123], v[222:223] op_sel:[0,1,0] op_sel_hi:[1,1,1]
	v_pk_fma_f32 v[8:9], v[8:9], v[188:189], v[216:217]
	v_pk_fma_f32 v[10:11], v[10:11], v[190:191], v[218:219]
	v_pk_fma_f32 v[24:25], v[24:25], v[188:189], v[220:221]
	v_pk_fma_f32 v[26:27], v[26:27], v[190:191], v[222:223]
	ds_read_b128 v[96:99], v232 offset:13600
	ds_read_b128 v[112:115], v232 offset:12576
	ds_read_b128 v[188:191], v232 offset:13088
	v_pk_mul_f32 v[224:225], v[100:101], v[212:213] op_sel_hi:[1,0] neg_lo:[0,1] neg_hi:[0,1]
	v_pk_mul_f32 v[226:227], v[102:103], v[212:213] op_sel_hi:[1,0] neg_lo:[0,1] neg_hi:[0,1]
	v_pk_mul_f32 v[228:229], v[100:101], v[212:213] op_sel:[0,1] op_sel_hi:[1,1] neg_lo:[0,1] neg_hi:[0,1]
	v_pk_mul_f32 v[230:231], v[102:103], v[212:213] op_sel:[0,1] op_sel_hi:[1,1] neg_lo:[0,1] neg_hi:[0,1]
	v_pk_fma_f32 v[224:225], v[116:117], v[122:123], v[224:225] op_sel_hi:[1,0,1]
	v_pk_fma_f32 v[226:227], v[118:119], v[122:123], v[226:227] op_sel_hi:[1,0,1]
	v_pk_fma_f32 v[228:229], v[116:117], v[122:123], v[228:229] op_sel:[0,1,0] op_sel_hi:[1,1,1]
	v_pk_fma_f32 v[230:231], v[118:119], v[122:123], v[230:231] op_sel:[0,1,0] op_sel_hi:[1,1,1]
	v_pk_fma_f32 v[12:13], v[12:13], v[192:193], v[224:225]
	v_pk_fma_f32 v[14:15], v[14:15], v[194:195], v[226:227]
	v_pk_fma_f32 v[28:29], v[28:29], v[192:193], v[228:229]
	v_pk_fma_f32 v[30:31], v[30:31], v[194:195], v[230:231]
	ds_read_b128 v[100:103], v232 offset:13616
	ds_read_b128 v[116:119], v232 offset:12592
	ds_read_b128 v[192:195], v232 offset:13104
	s_waitcnt lgkmcnt(13)
; #define SB __builtin_amdgcn_sched_barrier(0)
; #define CMP(G, c8) { CMP1(G, 0, 2 * (c8)) CMP1(G, 1, 2 * (c8) + 1) }
; __device__ __forceinline__ void phase_scan(const Args& a, unsigned char* lds) {
;     ...
;                     for (int s = 0; s < 16; ++s) {
;                         const float* vs = vb + s * 384;
;                         const float vi = vs[128 - cb + srow];
;                         f32x4 G0[8], G1[8], G2[8];
;                         LDG(G0, 0) SB;
;                         LDG(G1, 1) SB;
;                         f32x2 c0 = {0.f, 0.f}, c1 = {0.f, 0.f};
; #pragma unroll
;                         for (int j = 0; j < 8; ++j) { c0 += S2[2 * j] * (f32x2){KA[j][0], KA[j][1]}; c1 += S2[2 * j + 1] * (f32x2){KA[j][2], KA[j][3]}; }
;                         float cs = (c0.x + c0.y) + (c1.x + c1.y);
;                         cs += dpp_f(cs, 0);
;                         const float sa = -cs;
;                         const f32x2 sa2 = {sa, sa}, v2 = {vi, vi};
;                         f32x2 y0 = {0.f, 0.f}, y1 = {0.f, 0.f};
;                         SB; LDG(G2, 2) SB; CMP(G0, 0) SB;
;                         LDG(G0, 3) SB; CMP(G1, 1) SB;
;                         CMP(G2, 2) SB;
; #pragma unroll
;                         for (int j = 0; j < 8; ++j) KA[j] = *(const f32x4*)(vs + 384 + 256 + 4 * j);
;                         SB; CMP(G0, 3) SB;
;                         float ys = (y0.x + y0.y) + (y1.x + y1.y);
;                         ys += dpp_f(ys, 0);
;                         if ((lane & 1) == 0) yb[s * 64 + srow] = ys;
	v_pk_mul_f32 v[196:197], v[0:1], v[32:33]
	v_pk_mul_f32 v[200:201], v[16:17], v[32:33]
	v_pk_mul_f32 v[204:205], v[0:1], v[48:49]
	v_pk_mul_f32 v[208:209], v[16:17], v[48:49]
	v_pk_fma_f32 v[196:197], v[2:3], v[34:35], v[196:197]
	v_pk_fma_f32 v[200:201], v[18:19], v[34:35], v[200:201]
	v_pk_fma_f32 v[204:205], v[2:3], v[50:51], v[204:205]
	v_pk_fma_f32 v[208:209], v[18:19], v[50:51], v[208:209]
	ds_read_b128 v[32:35], v232 offset:14848
	ds_read_b128 v[48:51], v232 offset:12288
	v_pk_fma_f32 v[196:197], v[4:5], v[36:37], v[196:197]
	v_pk_fma_f32 v[200:201], v[20:21], v[36:37], v[200:201]
	v_pk_fma_f32 v[204:205], v[4:5], v[52:53], v[204:205]
	v_pk_fma_f32 v[208:209], v[20:21], v[52:53], v[208:209]
	v_pk_fma_f32 v[196:197], v[6:7], v[38:39], v[196:197]
	v_pk_fma_f32 v[200:201], v[22:23], v[38:39], v[200:201]
	v_pk_fma_f32 v[204:205], v[6:7], v[54:55], v[204:205]
	v_pk_fma_f32 v[208:209], v[22:23], v[54:55], v[208:209]
	ds_read_b128 v[36:39], v232 offset:14864
	ds_read_b128 v[52:55], v232 offset:12304
	v_pk_fma_f32 v[196:197], v[8:9], v[40:41], v[196:197]
	v_pk_fma_f32 v[200:201], v[24:25], v[40:41], v[200:201]
	v_pk_fma_f32 v[204:205], v[8:9], v[56:57], v[204:205]
	v_pk_fma_f32 v[208:209], v[24:25], v[56:57], v[208:209]
	v_pk_fma_f32 v[196:197], v[10:11], v[42:43], v[196:197]
	v_pk_fma_f32 v[200:201], v[26:27], v[42:43], v[200:201]
	v_pk_fma_f32 v[204:205], v[10:11], v[58:59], v[204:205]
	v_pk_fma_f32 v[208:209], v[26:27], v[58:59], v[208:209]
	ds_read_b128 v[40:43], v232 offset:14880
	ds_read_b128 v[56:59], v232 offset:12320
	v_pk_fma_f32 v[196:197], v[12:13], v[44:45], v[196:197]
	v_pk_fma_f32 v[200:201], v[28:29], v[44:45], v[200:201]
	v_pk_fma_f32 v[204:205], v[12:13], v[60:61], v[204:205]
	v_pk_fma_f32 v[208:209], v[28:29], v[60:61], v[208:209]
	v_pk_fma_f32 v[196:197], v[14:15], v[46:47], v[196:197]
	v_pk_fma_f32 v[200:201], v[30:31], v[46:47], v[200:201]
	v_pk_fma_f32 v[204:205], v[14:15], v[62:63], v[204:205]
	v_pk_fma_f32 v[208:209], v[30:31], v[62:63], v[208:209]
	ds_read_b128 v[44:47], v232 offset:14896
	ds_read_b128 v[60:63], v232 offset:12336
	v_add_f32_e32 v212, v196, v197
	v_add_f32_e32 v213, v200, v201
	v_add_f32_e32 v214, v204, v205
	v_add_f32_e32 v215, v208, v209
	v_add_f32_dpp v212, v212, v212 quad_perm:[1,0,3,2] row_mask:0xf bank_mask:0xf
	v_add_f32_dpp v213, v213, v213 quad_perm:[1,0,3,2] row_mask:0xf bank_mask:0xf
	v_add_f32_dpp v214, v214, v214 quad_perm:[1,0,3,2] row_mask:0xf bank_mask:0xf
	v_add_f32_dpp v215, v215, v215 quad_perm:[1,0,3,2] row_mask:0xf bank_mask:0xf
	v_add_f32_dpp v212, v212, v212 quad_perm:[2,3,0,1] row_mask:0xf bank_mask:0xf
	v_add_f32_dpp v213, v213, v213 quad_perm:[2,3,0,1] row_mask:0xf bank_mask:0xf
	v_add_f32_dpp v214, v214, v214 quad_perm:[2,3,0,1] row_mask:0xf bank_mask:0xf
	v_add_f32_dpp v215, v215, v215 quad_perm:[2,3,0,1] row_mask:0xf bank_mask:0xf
	ds_write_b64 v234, v[214:215] offset:1792
	s_waitcnt lgkmcnt(8)
	ds_read_b64 v[122:123], v233 offset:14336
	v_pk_mul_f32 v[216:217], v[88:89], v[212:213] op_sel_hi:[1,0] neg_lo:[0,1] neg_hi:[0,1]
	v_pk_mul_f32 v[218:219], v[90:91], v[212:213] op_sel_hi:[1,0] neg_lo:[0,1] neg_hi:[0,1]
	v_pk_mul_f32 v[220:221], v[88:89], v[212:213] op_sel:[0,1] op_sel_hi:[1,1] neg_lo:[0,1] neg_hi:[0,1]
	v_pk_mul_f32 v[222:223], v[90:91], v[212:213] op_sel:[0,1] op_sel_hi:[1,1] neg_lo:[0,1] neg_hi:[0,1]
	v_pk_fma_f32 v[216:217], v[104:105], v[120:121], v[216:217] op_sel_hi:[1,0,1]
	v_pk_fma_f32 v[218:219], v[106:107], v[120:121], v[218:219] op_sel_hi:[1,0,1]
	v_pk_fma_f32 v[220:221], v[104:105], v[120:121], v[220:221] op_sel:[0,1,0] op_sel_hi:[1,1,1]
	v_pk_fma_f32 v[222:223], v[106:107], v[120:121], v[222:223] op_sel:[0,1,0] op_sel_hi:[1,1,1]
	v_pk_fma_f32 v[0:1], v[0:1], v[180:181], v[216:217]
	v_pk_fma_f32 v[2:3], v[2:3], v[182:183], v[218:219]
	v_pk_fma_f32 v[16:17], v[16:17], v[180:181], v[220:221]
	v_pk_fma_f32 v[18:19], v[18:19], v[182:183], v[222:223]
	ds_read_b128 v[88:91], v232 offset:15104
	ds_read_b128 v[104:107], v232 offset:14080
	ds_read_b128 v[180:183], v232 offset:14592
	v_pk_mul_f32 v[224:225], v[92:93], v[212:213] op_sel_hi:[1,0] neg_lo:[0,1] neg_hi:[0,1]
	v_pk_mul_f32 v[226:227], v[94:95], v[212:213] op_sel_hi:[1,0] neg_lo:[0,1] neg_hi:[0,1]
	v_pk_mul_f32 v[228:229], v[92:93], v[212:213] op_sel:[0,1] op_sel_hi:[1,1] neg_lo:[0,1] neg_hi:[0,1]
	v_pk_mul_f32 v[230:231], v[94:95], v[212:213] op_sel:[0,1] op_sel_hi:[1,1] neg_lo:[0,1] neg_hi:[0,1]
	v_pk_fma_f32 v[224:225], v[108:109], v[120:121], v[224:225] op_sel_hi:[1,0,1]
	v_pk_fma_f32 v[226:227], v[110:111], v[120:121], v[226:227] op_sel_hi:[1,0,1]
	v_pk_fma_f32 v[228:229], v[108:109], v[120:121], v[228:229] op_sel:[0,1,0] op_sel_hi:[1,1,1]
	v_pk_fma_f32 v[230:231], v[110:111], v[120:121], v[230:231] op_sel:[0,1,0] op_sel_hi:[1,1,1]
	v_pk_fma_f32 v[4:5], v[4:5], v[184:185], v[224:225]
	v_pk_fma_f32 v[6:7], v[6:7], v[186:187], v[226:227]
	v_pk_fma_f32 v[20:21], v[20:21], v[184:185], v[228:229]
	v_pk_fma_f32 v[22:23], v[22:23], v[186:187], v[230:231]
	ds_read_b128 v[92:95], v232 offset:15120
	ds_read_b128 v[108:111], v232 offset:14096
	ds_read_b128 v[184:187], v232 offset:14608
	v_pk_mul_f32 v[216:217], v[96:97], v[212:213] op_sel_hi:[1,0] neg_lo:[0,1] neg_hi:[0,1]
	v_pk_mul_f32 v[218:219], v[98:99], v[212:213] op_sel_hi:[1,0] neg_lo:[0,1] neg_hi:[0,1]
	v_pk_mul_f32 v[220:221], v[96:97], v[212:213] op_sel:[0,1] op_sel_hi:[1,1] neg_lo:[0,1] neg_hi:[0,1]
	v_pk_mul_f32 v[222:223], v[98:99], v[212:213] op_sel:[0,1] op_sel_hi:[1,1] neg_lo:[0,1] neg_hi:[0,1]
	v_pk_fma_f32 v[216:217], v[112:113], v[120:121], v[216:217] op_sel_hi:[1,0,1]
	v_pk_fma_f32 v[218:219], v[114:115], v[120:121], v[218:219] op_sel_hi:[1,0,1]
; #define SB __builtin_amdgcn_sched_barrier(0)
; #define CMP(G, c8) { CMP1(G, 0, 2 * (c8)) CMP1(G, 1, 2 * (c8) + 1) }
; __device__ __forceinline__ void phase_scan(const Args& a, unsigned char* lds) {
;     ...
;                     for (int s = 0; s < 16; ++s) {
;                         const float* vs = vb + s * 384;
;                         const float vi = vs[128 - cb + srow];
;                         f32x4 G0[8], G1[8], G2[8];
;                         LDG(G0, 0) SB;
;                         LDG(G1, 1) SB;
;                         f32x2 c0 = {0.f, 0.f}, c1 = {0.f, 0.f};
; #pragma unroll
;                         for (int j = 0; j < 8; ++j) { c0 += S2[2 * j] * (f32x2){KA[j][0], KA[j][1]}; c1 += S2[2 * j + 1] * (f32x2){KA[j][2], KA[j][3]}; }
;                         float cs = (c0.x + c0.y) + (c1.x + c1.y);
;                         cs += dpp_f(cs, 0);
;                         const float sa = -cs;
;                         const f32x2 sa2 = {sa, sa}, v2 = {vi, vi};
;                         f32x2 y0 = {0.f, 0.f}, y1 = {0.f, 0.f};
;                         SB; LDG(G2, 2) SB; CMP(G0, 0) SB;
;                         LDG(G0, 3) SB; CMP(G1, 1) SB;
;                         CMP(G2, 2) SB;
; #pragma unroll
;                         for (int j = 0; j < 8; ++j) KA[j] = *(const f32x4*)(vs + 384 + 256 + 4 * j);
;                         SB; CMP(G0, 3) SB;
;                         float ys = (y0.x + y0.y) + (y1.x + y1.y);
;                         ys += dpp_f(ys, 0);
;                         if ((lane & 1) == 0) yb[s * 64 + srow] = ys;
	v_pk_fma_f32 v[220:221], v[112:113], v[120:121], v[220:221] op_sel:[0,1,0] op_sel_hi:[1,1,1]
	v_pk_fma_f32 v[222:223], v[114:115], v[120:121], v[222:223] op_sel:[0,1,0] op_sel_hi:[1,1,1]
	v_pk_fma_f32 v[8:9], v[8:9], v[188:189], v[216:217]
	v_pk_fma_f32 v[10:11], v[10:11], v[190:191], v[218:219]
	v_pk_fma_f32 v[24:25], v[24:25], v[188:189], v[220:221]
	v_pk_fma_f32 v[26:27], v[26:27], v[190:191], v[222:223]
	ds_read_b128 v[96:99], v232 offset:15136
	ds_read_b128 v[112:115], v232 offset:14112
	ds_read_b128 v[188:191], v232 offset:14624
	v_pk_mul_f32 v[224:225], v[100:101], v[212:213] op_sel_hi:[1,0] neg_lo:[0,1] neg_hi:[0,1]
	v_pk_mul_f32 v[226:227], v[102:103], v[212:213] op_sel_hi:[1,0] neg_lo:[0,1] neg_hi:[0,1]
	v_pk_mul_f32 v[228:229], v[100:101], v[212:213] op_sel:[0,1] op_sel_hi:[1,1] neg_lo:[0,1] neg_hi:[0,1]
	v_pk_mul_f32 v[230:231], v[102:103], v[212:213] op_sel:[0,1] op_sel_hi:[1,1] neg_lo:[0,1] neg_hi:[0,1]
	v_pk_fma_f32 v[224:225], v[116:117], v[120:121], v[224:225] op_sel_hi:[1,0,1]
	v_pk_fma_f32 v[226:227], v[118:119], v[120:121], v[226:227] op_sel_hi:[1,0,1]
	v_pk_fma_f32 v[228:229], v[116:117], v[120:121], v[228:229] op_sel:[0,1,0] op_sel_hi:[1,1,1]
	v_pk_fma_f32 v[230:231], v[118:119], v[120:121], v[230:231] op_sel:[0,1,0] op_sel_hi:[1,1,1]
	v_pk_fma_f32 v[12:13], v[12:13], v[192:193], v[224:225]
	v_pk_fma_f32 v[14:15], v[14:15], v[194:195], v[226:227]
	v_pk_fma_f32 v[28:29], v[28:29], v[192:193], v[228:229]
	v_pk_fma_f32 v[30:31], v[30:31], v[194:195], v[230:231]
	ds_read_b128 v[100:103], v232 offset:15152
	ds_read_b128 v[116:119], v232 offset:14128
	ds_read_b128 v[192:195], v232 offset:14640
	s_waitcnt lgkmcnt(13)
	v_pk_mul_f32 v[196:197], v[0:1], v[32:33]
	v_pk_mul_f32 v[200:201], v[16:17], v[32:33]
	v_pk_mul_f32 v[204:205], v[0:1], v[48:49]
	v_pk_mul_f32 v[208:209], v[16:17], v[48:49]
	v_pk_fma_f32 v[196:197], v[2:3], v[34:35], v[196:197]
	v_pk_fma_f32 v[200:201], v[18:19], v[34:35], v[200:201]
	v_pk_fma_f32 v[204:205], v[2:3], v[50:51], v[204:205]
	v_pk_fma_f32 v[208:209], v[18:19], v[50:51], v[208:209]
	ds_read_b128 v[32:35], v232 offset:16384
	ds_read_b128 v[48:51], v232 offset:13824
	v_pk_fma_f32 v[196:197], v[4:5], v[36:37], v[196:197]
	v_pk_fma_f32 v[200:201], v[20:21], v[36:37], v[200:201]
	v_pk_fma_f32 v[204:205], v[4:5], v[52:53], v[204:205]
	v_pk_fma_f32 v[208:209], v[20:21], v[52:53], v[208:209]
	v_pk_fma_f32 v[196:197], v[6:7], v[38:39], v[196:197]
	v_pk_fma_f32 v[200:201], v[22:23], v[38:39], v[200:201]
	v_pk_fma_f32 v[204:205], v[6:7], v[54:55], v[204:205]
	v_pk_fma_f32 v[208:209], v[22:23], v[54:55], v[208:209]
	ds_read_b128 v[36:39], v232 offset:16400
	ds_read_b128 v[52:55], v232 offset:13840
	v_pk_fma_f32 v[196:197], v[8:9], v[40:41], v[196:197]
	v_pk_fma_f32 v[200:201], v[24:25], v[40:41], v[200:201]
	v_pk_fma_f32 v[204:205], v[8:9], v[56:57], v[204:205]
	v_pk_fma_f32 v[208:209], v[24:25], v[56:57], v[208:209]
	v_pk_fma_f32 v[196:197], v[10:11], v[42:43], v[196:197]
	v_pk_fma_f32 v[200:201], v[26:27], v[42:43], v[200:201]
	v_pk_fma_f32 v[204:205], v[10:11], v[58:59], v[204:205]
	v_pk_fma_f32 v[208:209], v[26:27], v[58:59], v[208:209]
	ds_read_b128 v[40:43], v232 offset:16416
	ds_read_b128 v[56:59], v232 offset:13856
	v_pk_fma_f32 v[196:197], v[12:13], v[44:45], v[196:197]
	v_pk_fma_f32 v[200:201], v[28:29], v[44:45], v[200:201]
	v_pk_fma_f32 v[204:205], v[12:13], v[60:61], v[204:205]
	v_pk_fma_f32 v[208:209], v[28:29], v[60:61], v[208:209]
	v_pk_fma_f32 v[196:197], v[14:15], v[46:47], v[196:197]
	v_pk_fma_f32 v[200:201], v[30:31], v[46:47], v[200:201]
	v_pk_fma_f32 v[204:205], v[14:15], v[62:63], v[204:205]
	v_pk_fma_f32 v[208:209], v[30:31], v[62:63], v[208:209]
	ds_read_b128 v[44:47], v232 offset:16432
	ds_read_b128 v[60:63], v232 offset:13872
	v_add_f32_e32 v212, v196, v197
	v_add_f32_e32 v213, v200, v201
	v_add_f32_e32 v214, v204, v205
	v_add_f32_e32 v215, v208, v209
	v_add_f32_dpp v212, v212, v212 quad_perm:[1,0,3,2] row_mask:0xf bank_mask:0xf
	v_add_f32_dpp v213, v213, v213 quad_perm:[1,0,3,2] row_mask:0xf bank_mask:0xf
	v_add_f32_dpp v214, v214, v214 quad_perm:[1,0,3,2] row_mask:0xf bank_mask:0xf
	v_add_f32_dpp v215, v215, v215 quad_perm:[1,0,3,2] row_mask:0xf bank_mask:0xf
	v_add_f32_dpp v212, v212, v212 quad_perm:[2,3,0,1] row_mask:0xf bank_mask:0xf
	v_add_f32_dpp v213, v213, v213 quad_perm:[2,3,0,1] row_mask:0xf bank_mask:0xf
	v_add_f32_dpp v214, v214, v214 quad_perm:[2,3,0,1] row_mask:0xf bank_mask:0xf
	v_add_f32_dpp v215, v215, v215 quad_perm:[2,3,0,1] row_mask:0xf bank_mask:0xf
	ds_write_b64 v234, v[214:215] offset:2048
	s_waitcnt lgkmcnt(8)
; #define SB __builtin_amdgcn_sched_barrier(0)
; #define CMP(G, c8) { CMP1(G, 0, 2 * (c8)) CMP1(G, 1, 2 * (c8) + 1) }
; __device__ __forceinline__ void phase_scan(const Args& a, unsigned char* lds) {
;     ...
;                     for (int s = 0; s < 16; ++s) {
;                         const float* vs = vb + s * 384;
;                         const float vi = vs[128 - cb + srow];
;                         f32x4 G0[8], G1[8], G2[8];
;                         LDG(G0, 0) SB;
;                         LDG(G1, 1) SB;
;                         f32x2 c0 = {0.f, 0.f}, c1 = {0.f, 0.f};
; #pragma unroll
;                         for (int j = 0; j < 8; ++j) { c0 += S2[2 * j] * (f32x2){KA[j][0], KA[j][1]}; c1 += S2[2 * j + 1] * (f32x2){KA[j][2], KA[j][3]}; }
;                         float cs = (c0.x + c0.y) + (c1.x + c1.y);
;                         cs += dpp_f(cs, 0);
;                         const float sa = -cs;
;                         const f32x2 sa2 = {sa, sa}, v2 = {vi, vi};
;                         f32x2 y0 = {0.f, 0.f}, y1 = {0.f, 0.f};
;                         SB; LDG(G2, 2) SB; CMP(G0, 0) SB;
;                         LDG(G0, 3) SB; CMP(G1, 1) SB;
;                         CMP(G2, 2) SB;
; #pragma unroll
;                         for (int j = 0; j < 8; ++j) KA[j] = *(const f32x4*)(vs + 384 + 256 + 4 * j);
;                         SB; CMP(G0, 3) SB;
;                         float ys = (y0.x + y0.y) + (y1.x + y1.y);
;                         ys += dpp_f(ys, 0);
;                         if ((lane & 1) == 0) yb[s * 64 + srow] = ys;
	ds_read_b64 v[120:121], v233 offset:15872
	v_pk_mul_f32 v[216:217], v[88:89], v[212:213] op_sel_hi:[1,0] neg_lo:[0,1] neg_hi:[0,1]
	v_pk_mul_f32 v[218:219], v[90:91], v[212:213] op_sel_hi:[1,0] neg_lo:[0,1] neg_hi:[0,1]
	v_pk_mul_f32 v[220:221], v[88:89], v[212:213] op_sel:[0,1] op_sel_hi:[1,1] neg_lo:[0,1] neg_hi:[0,1]
	v_pk_mul_f32 v[222:223], v[90:91], v[212:213] op_sel:[0,1] op_sel_hi:[1,1] neg_lo:[0,1] neg_hi:[0,1]
	v_pk_fma_f32 v[216:217], v[104:105], v[122:123], v[216:217] op_sel_hi:[1,0,1]
	v_pk_fma_f32 v[218:219], v[106:107], v[122:123], v[218:219] op_sel_hi:[1,0,1]
	v_pk_fma_f32 v[220:221], v[104:105], v[122:123], v[220:221] op_sel:[0,1,0] op_sel_hi:[1,1,1]
	v_pk_fma_f32 v[222:223], v[106:107], v[122:123], v[222:223] op_sel:[0,1,0] op_sel_hi:[1,1,1]
	v_pk_fma_f32 v[0:1], v[0:1], v[180:181], v[216:217]
	v_pk_fma_f32 v[2:3], v[2:3], v[182:183], v[218:219]
	v_pk_fma_f32 v[16:17], v[16:17], v[180:181], v[220:221]
	v_pk_fma_f32 v[18:19], v[18:19], v[182:183], v[222:223]
	ds_read_b128 v[88:91], v232 offset:16640
	ds_read_b128 v[104:107], v232 offset:15616
	ds_read_b128 v[180:183], v232 offset:16128
	v_pk_mul_f32 v[224:225], v[92:93], v[212:213] op_sel_hi:[1,0] neg_lo:[0,1] neg_hi:[0,1]
	v_pk_mul_f32 v[226:227], v[94:95], v[212:213] op_sel_hi:[1,0] neg_lo:[0,1] neg_hi:[0,1]
	v_pk_mul_f32 v[228:229], v[92:93], v[212:213] op_sel:[0,1] op_sel_hi:[1,1] neg_lo:[0,1] neg_hi:[0,1]
	v_pk_mul_f32 v[230:231], v[94:95], v[212:213] op_sel:[0,1] op_sel_hi:[1,1] neg_lo:[0,1] neg_hi:[0,1]
	v_pk_fma_f32 v[224:225], v[108:109], v[122:123], v[224:225] op_sel_hi:[1,0,1]
	v_pk_fma_f32 v[226:227], v[110:111], v[122:123], v[226:227] op_sel_hi:[1,0,1]
	v_pk_fma_f32 v[228:229], v[108:109], v[122:123], v[228:229] op_sel:[0,1,0] op_sel_hi:[1,1,1]
	v_pk_fma_f32 v[230:231], v[110:111], v[122:123], v[230:231] op_sel:[0,1,0] op_sel_hi:[1,1,1]
	v_pk_fma_f32 v[4:5], v[4:5], v[184:185], v[224:225]
	v_pk_fma_f32 v[6:7], v[6:7], v[186:187], v[226:227]
	v_pk_fma_f32 v[20:21], v[20:21], v[184:185], v[228:229]
	v_pk_fma_f32 v[22:23], v[22:23], v[186:187], v[230:231]
	ds_read_b128 v[92:95], v232 offset:16656
	ds_read_b128 v[108:111], v232 offset:15632
	ds_read_b128 v[184:187], v232 offset:16144
	v_pk_mul_f32 v[216:217], v[96:97], v[212:213] op_sel_hi:[1,0] neg_lo:[0,1] neg_hi:[0,1]
	v_pk_mul_f32 v[218:219], v[98:99], v[212:213] op_sel_hi:[1,0] neg_lo:[0,1] neg_hi:[0,1]
	v_pk_mul_f32 v[220:221], v[96:97], v[212:213] op_sel:[0,1] op_sel_hi:[1,1] neg_lo:[0,1] neg_hi:[0,1]
	v_pk_mul_f32 v[222:223], v[98:99], v[212:213] op_sel:[0,1] op_sel_hi:[1,1] neg_lo:[0,1] neg_hi:[0,1]
	v_pk_fma_f32 v[216:217], v[112:113], v[122:123], v[216:217] op_sel_hi:[1,0,1]
	v_pk_fma_f32 v[218:219], v[114:115], v[122:123], v[218:219] op_sel_hi:[1,0,1]
	v_pk_fma_f32 v[220:221], v[112:113], v[122:123], v[220:221] op_sel:[0,1,0] op_sel_hi:[1,1,1]
	v_pk_fma_f32 v[222:223], v[114:115], v[122:123], v[222:223] op_sel:[0,1,0] op_sel_hi:[1,1,1]
	v_pk_fma_f32 v[8:9], v[8:9], v[188:189], v[216:217]
	v_pk_fma_f32 v[10:11], v[10:11], v[190:191], v[218:219]
	v_pk_fma_f32 v[24:25], v[24:25], v[188:189], v[220:221]
	v_pk_fma_f32 v[26:27], v[26:27], v[190:191], v[222:223]
	ds_read_b128 v[96:99], v232 offset:16672
	ds_read_b128 v[112:115], v232 offset:15648
	ds_read_b128 v[188:191], v232 offset:16160
	v_pk_mul_f32 v[224:225], v[100:101], v[212:213] op_sel_hi:[1,0] neg_lo:[0,1] neg_hi:[0,1]
	v_pk_mul_f32 v[226:227], v[102:103], v[212:213] op_sel_hi:[1,0] neg_lo:[0,1] neg_hi:[0,1]
	v_pk_mul_f32 v[228:229], v[100:101], v[212:213] op_sel:[0,1] op_sel_hi:[1,1] neg_lo:[0,1] neg_hi:[0,1]
	v_pk_mul_f32 v[230:231], v[102:103], v[212:213] op_sel:[0,1] op_sel_hi:[1,1] neg_lo:[0,1] neg_hi:[0,1]
	v_pk_fma_f32 v[224:225], v[116:117], v[122:123], v[224:225] op_sel_hi:[1,0,1]
	v_pk_fma_f32 v[226:227], v[118:119], v[122:123], v[226:227] op_sel_hi:[1,0,1]
	v_pk_fma_f32 v[228:229], v[116:117], v[122:123], v[228:229] op_sel:[0,1,0] op_sel_hi:[1,1,1]
	v_pk_fma_f32 v[230:231], v[118:119], v[122:123], v[230:231] op_sel:[0,1,0] op_sel_hi:[1,1,1]
	v_pk_fma_f32 v[12:13], v[12:13], v[192:193], v[224:225]
	v_pk_fma_f32 v[14:15], v[14:15], v[194:195], v[226:227]
	v_pk_fma_f32 v[28:29], v[28:29], v[192:193], v[228:229]
	v_pk_fma_f32 v[30:31], v[30:31], v[194:195], v[230:231]
	ds_read_b128 v[100:103], v232 offset:16688
	ds_read_b128 v[116:119], v232 offset:15664
	ds_read_b128 v[192:195], v232 offset:16176
	s_waitcnt lgkmcnt(13)
; #define SB __builtin_amdgcn_sched_barrier(0)
; #define CMP(G, c8) { CMP1(G, 0, 2 * (c8)) CMP1(G, 1, 2 * (c8) + 1) }
; __device__ __forceinline__ void phase_scan(const Args& a, unsigned char* lds) {
;     ...
;                     for (int s = 0; s < 16; ++s) {
;                         const float* vs = vb + s * 384;
;                         const float vi = vs[128 - cb + srow];
;                         f32x4 G0[8], G1[8], G2[8];
;                         LDG(G0, 0) SB;
;                         LDG(G1, 1) SB;
;                         f32x2 c0 = {0.f, 0.f}, c1 = {0.f, 0.f};
; #pragma unroll
;                         for (int j = 0; j < 8; ++j) { c0 += S2[2 * j] * (f32x2){KA[j][0], KA[j][1]}; c1 += S2[2 * j + 1] * (f32x2){KA[j][2], KA[j][3]}; }
;                         float cs = (c0.x + c0.y) + (c1.x + c1.y);
;                         cs += dpp_f(cs, 0);
;                         const float sa = -cs;
;                         const f32x2 sa2 = {sa, sa}, v2 = {vi, vi};
;                         f32x2 y0 = {0.f, 0.f}, y1 = {0.f, 0.f};
;                         SB; LDG(G2, 2) SB; CMP(G0, 0) SB;
;                         LDG(G0, 3) SB; CMP(G1, 1) SB;
;                         CMP(G2, 2) SB;
; #pragma unroll
;                         for (int j = 0; j < 8; ++j) KA[j] = *(const f32x4*)(vs + 384 + 256 + 4 * j);
;                         SB; CMP(G0, 3) SB;
;                         float ys = (y0.x + y0.y) + (y1.x + y1.y);
;                         ys += dpp_f(ys, 0);
;                         if ((lane & 1) == 0) yb[s * 64 + srow] = ys;
	v_pk_mul_f32 v[196:197], v[0:1], v[32:33]
	v_pk_mul_f32 v[200:201], v[16:17], v[32:33]
	v_pk_mul_f32 v[204:205], v[0:1], v[48:49]
	v_pk_mul_f32 v[208:209], v[16:17], v[48:49]
	v_pk_fma_f32 v[196:197], v[2:3], v[34:35], v[196:197]
	v_pk_fma_f32 v[200:201], v[18:19], v[34:35], v[200:201]
	v_pk_fma_f32 v[204:205], v[2:3], v[50:51], v[204:205]
	v_pk_fma_f32 v[208:209], v[18:19], v[50:51], v[208:209]
	ds_read_b128 v[32:35], v232 offset:17920
	ds_read_b128 v[48:51], v232 offset:15360
	v_pk_fma_f32 v[196:197], v[4:5], v[36:37], v[196:197]
	v_pk_fma_f32 v[200:201], v[20:21], v[36:37], v[200:201]
	v_pk_fma_f32 v[204:205], v[4:5], v[52:53], v[204:205]
	v_pk_fma_f32 v[208:209], v[20:21], v[52:53], v[208:209]
	v_pk_fma_f32 v[196:197], v[6:7], v[38:39], v[196:197]
	v_pk_fma_f32 v[200:201], v[22:23], v[38:39], v[200:201]
	v_pk_fma_f32 v[204:205], v[6:7], v[54:55], v[204:205]
	v_pk_fma_f32 v[208:209], v[22:23], v[54:55], v[208:209]
	ds_read_b128 v[36:39], v232 offset:17936
	ds_read_b128 v[52:55], v232 offset:15376
	v_pk_fma_f32 v[196:197], v[8:9], v[40:41], v[196:197]
	v_pk_fma_f32 v[200:201], v[24:25], v[40:41], v[200:201]
	v_pk_fma_f32 v[204:205], v[8:9], v[56:57], v[204:205]
	v_pk_fma_f32 v[208:209], v[24:25], v[56:57], v[208:209]
	v_pk_fma_f32 v[196:197], v[10:11], v[42:43], v[196:197]
	v_pk_fma_f32 v[200:201], v[26:27], v[42:43], v[200:201]
	v_pk_fma_f32 v[204:205], v[10:11], v[58:59], v[204:205]
	v_pk_fma_f32 v[208:209], v[26:27], v[58:59], v[208:209]
	ds_read_b128 v[40:43], v232 offset:17952
	ds_read_b128 v[56:59], v232 offset:15392
	v_pk_fma_f32 v[196:197], v[12:13], v[44:45], v[196:197]
	v_pk_fma_f32 v[200:201], v[28:29], v[44:45], v[200:201]
	v_pk_fma_f32 v[204:205], v[12:13], v[60:61], v[204:205]
	v_pk_fma_f32 v[208:209], v[28:29], v[60:61], v[208:209]
	v_pk_fma_f32 v[196:197], v[14:15], v[46:47], v[196:197]
	v_pk_fma_f32 v[200:201], v[30:31], v[46:47], v[200:201]
	v_pk_fma_f32 v[204:205], v[14:15], v[62:63], v[204:205]
	v_pk_fma_f32 v[208:209], v[30:31], v[62:63], v[208:209]
	ds_read_b128 v[44:47], v232 offset:17968
	ds_read_b128 v[60:63], v232 offset:15408
	v_add_f32_e32 v212, v196, v197
	v_add_f32_e32 v213, v200, v201
	v_add_f32_e32 v214, v204, v205
	v_add_f32_e32 v215, v208, v209
	v_add_f32_dpp v212, v212, v212 quad_perm:[1,0,3,2] row_mask:0xf bank_mask:0xf
	v_add_f32_dpp v213, v213, v213 quad_perm:[1,0,3,2] row_mask:0xf bank_mask:0xf
	v_add_f32_dpp v214, v214, v214 quad_perm:[1,0,3,2] row_mask:0xf bank_mask:0xf
	v_add_f32_dpp v215, v215, v215 quad_perm:[1,0,3,2] row_mask:0xf bank_mask:0xf
	v_add_f32_dpp v212, v212, v212 quad_perm:[2,3,0,1] row_mask:0xf bank_mask:0xf
	v_add_f32_dpp v213, v213, v213 quad_perm:[2,3,0,1] row_mask:0xf bank_mask:0xf
	v_add_f32_dpp v214, v214, v214 quad_perm:[2,3,0,1] row_mask:0xf bank_mask:0xf
	v_add_f32_dpp v215, v215, v215 quad_perm:[2,3,0,1] row_mask:0xf bank_mask:0xf
	ds_write_b64 v234, v[214:215] offset:2304
	s_waitcnt lgkmcnt(8)
	ds_read_b64 v[122:123], v233 offset:17408
	v_pk_mul_f32 v[216:217], v[88:89], v[212:213] op_sel_hi:[1,0] neg_lo:[0,1] neg_hi:[0,1]
	v_pk_mul_f32 v[218:219], v[90:91], v[212:213] op_sel_hi:[1,0] neg_lo:[0,1] neg_hi:[0,1]
	v_pk_mul_f32 v[220:221], v[88:89], v[212:213] op_sel:[0,1] op_sel_hi:[1,1] neg_lo:[0,1] neg_hi:[0,1]
	v_pk_mul_f32 v[222:223], v[90:91], v[212:213] op_sel:[0,1] op_sel_hi:[1,1] neg_lo:[0,1] neg_hi:[0,1]
	v_pk_fma_f32 v[216:217], v[104:105], v[120:121], v[216:217] op_sel_hi:[1,0,1]
	v_pk_fma_f32 v[218:219], v[106:107], v[120:121], v[218:219] op_sel_hi:[1,0,1]
	v_pk_fma_f32 v[220:221], v[104:105], v[120:121], v[220:221] op_sel:[0,1,0] op_sel_hi:[1,1,1]
	v_pk_fma_f32 v[222:223], v[106:107], v[120:121], v[222:223] op_sel:[0,1,0] op_sel_hi:[1,1,1]
	v_pk_fma_f32 v[0:1], v[0:1], v[180:181], v[216:217]
	v_pk_fma_f32 v[2:3], v[2:3], v[182:183], v[218:219]
	v_pk_fma_f32 v[16:17], v[16:17], v[180:181], v[220:221]
	v_pk_fma_f32 v[18:19], v[18:19], v[182:183], v[222:223]
	ds_read_b128 v[88:91], v232 offset:18176
	ds_read_b128 v[104:107], v232 offset:17152
	ds_read_b128 v[180:183], v232 offset:17664
	v_pk_mul_f32 v[224:225], v[92:93], v[212:213] op_sel_hi:[1,0] neg_lo:[0,1] neg_hi:[0,1]
	v_pk_mul_f32 v[226:227], v[94:95], v[212:213] op_sel_hi:[1,0] neg_lo:[0,1] neg_hi:[0,1]
	v_pk_mul_f32 v[228:229], v[92:93], v[212:213] op_sel:[0,1] op_sel_hi:[1,1] neg_lo:[0,1] neg_hi:[0,1]
	v_pk_mul_f32 v[230:231], v[94:95], v[212:213] op_sel:[0,1] op_sel_hi:[1,1] neg_lo:[0,1] neg_hi:[0,1]
	v_pk_fma_f32 v[224:225], v[108:109], v[120:121], v[224:225] op_sel_hi:[1,0,1]
	v_pk_fma_f32 v[226:227], v[110:111], v[120:121], v[226:227] op_sel_hi:[1,0,1]
	v_pk_fma_f32 v[228:229], v[108:109], v[120:121], v[228:229] op_sel:[0,1,0] op_sel_hi:[1,1,1]
	v_pk_fma_f32 v[230:231], v[110:111], v[120:121], v[230:231] op_sel:[0,1,0] op_sel_hi:[1,1,1]
	v_pk_fma_f32 v[4:5], v[4:5], v[184:185], v[224:225]
	v_pk_fma_f32 v[6:7], v[6:7], v[186:187], v[226:227]
	v_pk_fma_f32 v[20:21], v[20:21], v[184:185], v[228:229]
	v_pk_fma_f32 v[22:23], v[22:23], v[186:187], v[230:231]
	ds_read_b128 v[92:95], v232 offset:18192
	ds_read_b128 v[108:111], v232 offset:17168
	ds_read_b128 v[184:187], v232 offset:17680
	v_pk_mul_f32 v[216:217], v[96:97], v[212:213] op_sel_hi:[1,0] neg_lo:[0,1] neg_hi:[0,1]
	v_pk_mul_f32 v[218:219], v[98:99], v[212:213] op_sel_hi:[1,0] neg_lo:[0,1] neg_hi:[0,1]
	v_pk_mul_f32 v[220:221], v[96:97], v[212:213] op_sel:[0,1] op_sel_hi:[1,1] neg_lo:[0,1] neg_hi:[0,1]
	v_pk_mul_f32 v[222:223], v[98:99], v[212:213] op_sel:[0,1] op_sel_hi:[1,1] neg_lo:[0,1] neg_hi:[0,1]
	v_pk_fma_f32 v[216:217], v[112:113], v[120:121], v[216:217] op_sel_hi:[1,0,1]
	v_pk_fma_f32 v[218:219], v[114:115], v[120:121], v[218:219] op_sel_hi:[1,0,1]
; #define SB __builtin_amdgcn_sched_barrier(0)
; #define CMP(G, c8) { CMP1(G, 0, 2 * (c8)) CMP1(G, 1, 2 * (c8) + 1) }
; __device__ __forceinline__ void phase_scan(const Args& a, unsigned char* lds) {
;     ...
;                     for (int s = 0; s < 16; ++s) {
;                         const float* vs = vb + s * 384;
;                         const float vi = vs[128 - cb + srow];
;                         f32x4 G0[8], G1[8], G2[8];
;                         LDG(G0, 0) SB;
;                         LDG(G1, 1) SB;
;                         f32x2 c0 = {0.f, 0.f}, c1 = {0.f, 0.f};
; #pragma unroll
;                         for (int j = 0; j < 8; ++j) { c0 += S2[2 * j] * (f32x2){KA[j][0], KA[j][1]}; c1 += S2[2 * j + 1] * (f32x2){KA[j][2], KA[j][3]}; }
;                         float cs = (c0.x + c0.y) + (c1.x + c1.y);
;                         cs += dpp_f(cs, 0);
;                         const float sa = -cs;
;                         const f32x2 sa2 = {sa, sa}, v2 = {vi, vi};
;                         f32x2 y0 = {0.f, 0.f}, y1 = {0.f, 0.f};
;                         SB; LDG(G2, 2) SB; CMP(G0, 0) SB;
;                         LDG(G0, 3) SB; CMP(G1, 1) SB;
;                         CMP(G2, 2) SB;
; #pragma unroll
;                         for (int j = 0; j < 8; ++j) KA[j] = *(const f32x4*)(vs + 384 + 256 + 4 * j);
;                         SB; CMP(G0, 3) SB;
;                         float ys = (y0.x + y0.y) + (y1.x + y1.y);
;                         ys += dpp_f(ys, 0);
;                         if ((lane & 1) == 0) yb[s * 64 + srow] = ys;
	v_pk_fma_f32 v[220:221], v[112:113], v[120:121], v[220:221] op_sel:[0,1,0] op_sel_hi:[1,1,1]
	v_pk_fma_f32 v[222:223], v[114:115], v[120:121], v[222:223] op_sel:[0,1,0] op_sel_hi:[1,1,1]
	v_pk_fma_f32 v[8:9], v[8:9], v[188:189], v[216:217]
	v_pk_fma_f32 v[10:11], v[10:11], v[190:191], v[218:219]
	v_pk_fma_f32 v[24:25], v[24:25], v[188:189], v[220:221]
	v_pk_fma_f32 v[26:27], v[26:27], v[190:191], v[222:223]
	ds_read_b128 v[96:99], v232 offset:18208
	ds_read_b128 v[112:115], v232 offset:17184
	ds_read_b128 v[188:191], v232 offset:17696
	v_pk_mul_f32 v[224:225], v[100:101], v[212:213] op_sel_hi:[1,0] neg_lo:[0,1] neg_hi:[0,1]
	v_pk_mul_f32 v[226:227], v[102:103], v[212:213] op_sel_hi:[1,0] neg_lo:[0,1] neg_hi:[0,1]
	v_pk_mul_f32 v[228:229], v[100:101], v[212:213] op_sel:[0,1] op_sel_hi:[1,1] neg_lo:[0,1] neg_hi:[0,1]
	v_pk_mul_f32 v[230:231], v[102:103], v[212:213] op_sel:[0,1] op_sel_hi:[1,1] neg_lo:[0,1] neg_hi:[0,1]
	v_pk_fma_f32 v[224:225], v[116:117], v[120:121], v[224:225] op_sel_hi:[1,0,1]
	v_pk_fma_f32 v[226:227], v[118:119], v[120:121], v[226:227] op_sel_hi:[1,0,1]
	v_pk_fma_f32 v[228:229], v[116:117], v[120:121], v[228:229] op_sel:[0,1,0] op_sel_hi:[1,1,1]
	v_pk_fma_f32 v[230:231], v[118:119], v[120:121], v[230:231] op_sel:[0,1,0] op_sel_hi:[1,1,1]
	v_pk_fma_f32 v[12:13], v[12:13], v[192:193], v[224:225]
	v_pk_fma_f32 v[14:15], v[14:15], v[194:195], v[226:227]
	v_pk_fma_f32 v[28:29], v[28:29], v[192:193], v[228:229]
	v_pk_fma_f32 v[30:31], v[30:31], v[194:195], v[230:231]
	ds_read_b128 v[100:103], v232 offset:18224
	ds_read_b128 v[116:119], v232 offset:17200
	ds_read_b128 v[192:195], v232 offset:17712
	s_waitcnt lgkmcnt(13)
	v_pk_mul_f32 v[196:197], v[0:1], v[32:33]
	v_pk_mul_f32 v[200:201], v[16:17], v[32:33]
	v_pk_mul_f32 v[204:205], v[0:1], v[48:49]
	v_pk_mul_f32 v[208:209], v[16:17], v[48:49]
	v_pk_fma_f32 v[196:197], v[2:3], v[34:35], v[196:197]
	v_pk_fma_f32 v[200:201], v[18:19], v[34:35], v[200:201]
	v_pk_fma_f32 v[204:205], v[2:3], v[50:51], v[204:205]
	v_pk_fma_f32 v[208:209], v[18:19], v[50:51], v[208:209]
	ds_read_b128 v[32:35], v232 offset:19456
	ds_read_b128 v[48:51], v232 offset:16896
	v_pk_fma_f32 v[196:197], v[4:5], v[36:37], v[196:197]
	v_pk_fma_f32 v[200:201], v[20:21], v[36:37], v[200:201]
	v_pk_fma_f32 v[204:205], v[4:5], v[52:53], v[204:205]
	v_pk_fma_f32 v[208:209], v[20:21], v[52:53], v[208:209]
	v_pk_fma_f32 v[196:197], v[6:7], v[38:39], v[196:197]
	v_pk_fma_f32 v[200:201], v[22:23], v[38:39], v[200:201]
	v_pk_fma_f32 v[204:205], v[6:7], v[54:55], v[204:205]
	v_pk_fma_f32 v[208:209], v[22:23], v[54:55], v[208:209]
	ds_read_b128 v[36:39], v232 offset:19472
	ds_read_b128 v[52:55], v232 offset:16912
	v_pk_fma_f32 v[196:197], v[8:9], v[40:41], v[196:197]
	v_pk_fma_f32 v[200:201], v[24:25], v[40:41], v[200:201]
	v_pk_fma_f32 v[204:205], v[8:9], v[56:57], v[204:205]
	v_pk_fma_f32 v[208:209], v[24:25], v[56:57], v[208:209]
	v_pk_fma_f32 v[196:197], v[10:11], v[42:43], v[196:197]
	v_pk_fma_f32 v[200:201], v[26:27], v[42:43], v[200:201]
	v_pk_fma_f32 v[204:205], v[10:11], v[58:59], v[204:205]
	v_pk_fma_f32 v[208:209], v[26:27], v[58:59], v[208:209]
	ds_read_b128 v[40:43], v232 offset:19488
	ds_read_b128 v[56:59], v232 offset:16928
	v_pk_fma_f32 v[196:197], v[12:13], v[44:45], v[196:197]
	v_pk_fma_f32 v[200:201], v[28:29], v[44:45], v[200:201]
	v_pk_fma_f32 v[204:205], v[12:13], v[60:61], v[204:205]
	v_pk_fma_f32 v[208:209], v[28:29], v[60:61], v[208:209]
	v_pk_fma_f32 v[196:197], v[14:15], v[46:47], v[196:197]
	v_pk_fma_f32 v[200:201], v[30:31], v[46:47], v[200:201]
	v_pk_fma_f32 v[204:205], v[14:15], v[62:63], v[204:205]
	v_pk_fma_f32 v[208:209], v[30:31], v[62:63], v[208:209]
	ds_read_b128 v[44:47], v232 offset:19504
	ds_read_b128 v[60:63], v232 offset:16944
	v_add_f32_e32 v212, v196, v197
	v_add_f32_e32 v213, v200, v201
	v_add_f32_e32 v214, v204, v205
	v_add_f32_e32 v215, v208, v209
	v_add_f32_dpp v212, v212, v212 quad_perm:[1,0,3,2] row_mask:0xf bank_mask:0xf
	v_add_f32_dpp v213, v213, v213 quad_perm:[1,0,3,2] row_mask:0xf bank_mask:0xf
	v_add_f32_dpp v214, v214, v214 quad_perm:[1,0,3,2] row_mask:0xf bank_mask:0xf
	v_add_f32_dpp v215, v215, v215 quad_perm:[1,0,3,2] row_mask:0xf bank_mask:0xf
	v_add_f32_dpp v212, v212, v212 quad_perm:[2,3,0,1] row_mask:0xf bank_mask:0xf
	v_add_f32_dpp v213, v213, v213 quad_perm:[2,3,0,1] row_mask:0xf bank_mask:0xf
	v_add_f32_dpp v214, v214, v214 quad_perm:[2,3,0,1] row_mask:0xf bank_mask:0xf
	v_add_f32_dpp v215, v215, v215 quad_perm:[2,3,0,1] row_mask:0xf bank_mask:0xf
	ds_write_b64 v234, v[214:215] offset:2560
	s_waitcnt lgkmcnt(8)
; #define SB __builtin_amdgcn_sched_barrier(0)
; #define CMP(G, c8) { CMP1(G, 0, 2 * (c8)) CMP1(G, 1, 2 * (c8) + 1) }
; __device__ __forceinline__ void phase_scan(const Args& a, unsigned char* lds) {
;     ...
;                     for (int s = 0; s < 16; ++s) {
;                         const float* vs = vb + s * 384;
;                         const float vi = vs[128 - cb + srow];
;                         f32x4 G0[8], G1[8], G2[8];
;                         LDG(G0, 0) SB;
;                         LDG(G1, 1) SB;
;                         f32x2 c0 = {0.f, 0.f}, c1 = {0.f, 0.f};
; #pragma unroll
;                         for (int j = 0; j < 8; ++j) { c0 += S2[2 * j] * (f32x2){KA[j][0], KA[j][1]}; c1 += S2[2 * j + 1] * (f32x2){KA[j][2], KA[j][3]}; }
;                         float cs = (c0.x + c0.y) + (c1.x + c1.y);
;                         cs += dpp_f(cs, 0);
;                         const float sa = -cs;
;                         const f32x2 sa2 = {sa, sa}, v2 = {vi, vi};
;                         f32x2 y0 = {0.f, 0.f}, y1 = {0.f, 0.f};
;                         SB; LDG(G2, 2) SB; CMP(G0, 0) SB;
;                         LDG(G0, 3) SB; CMP(G1, 1) SB;
;                         CMP(G2, 2) SB;
; #pragma unroll
;                         for (int j = 0; j < 8; ++j) KA[j] = *(const f32x4*)(vs + 384 + 256 + 4 * j);
;                         SB; CMP(G0, 3) SB;
;                         float ys = (y0.x + y0.y) + (y1.x + y1.y);
;                         ys += dpp_f(ys, 0);
;                         if ((lane & 1) == 0) yb[s * 64 + srow] = ys;
	ds_read_b64 v[120:121], v233 offset:18944
	v_pk_mul_f32 v[216:217], v[88:89], v[212:213] op_sel_hi:[1,0] neg_lo:[0,1] neg_hi:[0,1]
	v_pk_mul_f32 v[218:219], v[90:91], v[212:213] op_sel_hi:[1,0] neg_lo:[0,1] neg_hi:[0,1]
	v_pk_mul_f32 v[220:221], v[88:89], v[212:213] op_sel:[0,1] op_sel_hi:[1,1] neg_lo:[0,1] neg_hi:[0,1]
	v_pk_mul_f32 v[222:223], v[90:91], v[212:213] op_sel:[0,1] op_sel_hi:[1,1] neg_lo:[0,1] neg_hi:[0,1]
	v_pk_fma_f32 v[216:217], v[104:105], v[122:123], v[216:217] op_sel_hi:[1,0,1]
	v_pk_fma_f32 v[218:219], v[106:107], v[122:123], v[218:219] op_sel_hi:[1,0,1]
	v_pk_fma_f32 v[220:221], v[104:105], v[122:123], v[220:221] op_sel:[0,1,0] op_sel_hi:[1,1,1]
	v_pk_fma_f32 v[222:223], v[106:107], v[122:123], v[222:223] op_sel:[0,1,0] op_sel_hi:[1,1,1]
	v_pk_fma_f32 v[0:1], v[0:1], v[180:181], v[216:217]
	v_pk_fma_f32 v[2:3], v[2:3], v[182:183], v[218:219]
	v_pk_fma_f32 v[16:17], v[16:17], v[180:181], v[220:221]
	v_pk_fma_f32 v[18:19], v[18:19], v[182:183], v[222:223]
	ds_read_b128 v[88:91], v232 offset:19712
	ds_read_b128 v[104:107], v232 offset:18688
	ds_read_b128 v[180:183], v232 offset:19200
	v_pk_mul_f32 v[224:225], v[92:93], v[212:213] op_sel_hi:[1,0] neg_lo:[0,1] neg_hi:[0,1]
	v_pk_mul_f32 v[226:227], v[94:95], v[212:213] op_sel_hi:[1,0] neg_lo:[0,1] neg_hi:[0,1]
	v_pk_mul_f32 v[228:229], v[92:93], v[212:213] op_sel:[0,1] op_sel_hi:[1,1] neg_lo:[0,1] neg_hi:[0,1]
	v_pk_mul_f32 v[230:231], v[94:95], v[212:213] op_sel:[0,1] op_sel_hi:[1,1] neg_lo:[0,1] neg_hi:[0,1]
	v_pk_fma_f32 v[224:225], v[108:109], v[122:123], v[224:225] op_sel_hi:[1,0,1]
	v_pk_fma_f32 v[226:227], v[110:111], v[122:123], v[226:227] op_sel_hi:[1,0,1]
	v_pk_fma_f32 v[228:229], v[108:109], v[122:123], v[228:229] op_sel:[0,1,0] op_sel_hi:[1,1,1]
	v_pk_fma_f32 v[230:231], v[110:111], v[122:123], v[230:231] op_sel:[0,1,0] op_sel_hi:[1,1,1]
	v_pk_fma_f32 v[4:5], v[4:5], v[184:185], v[224:225]
	v_pk_fma_f32 v[6:7], v[6:7], v[186:187], v[226:227]
	v_pk_fma_f32 v[20:21], v[20:21], v[184:185], v[228:229]
	v_pk_fma_f32 v[22:23], v[22:23], v[186:187], v[230:231]
	ds_read_b128 v[92:95], v232 offset:19728
	ds_read_b128 v[108:111], v232 offset:18704
	ds_read_b128 v[184:187], v232 offset:19216
	v_pk_mul_f32 v[216:217], v[96:97], v[212:213] op_sel_hi:[1,0] neg_lo:[0,1] neg_hi:[0,1]
	v_pk_mul_f32 v[218:219], v[98:99], v[212:213] op_sel_hi:[1,0] neg_lo:[0,1] neg_hi:[0,1]
	v_pk_mul_f32 v[220:221], v[96:97], v[212:213] op_sel:[0,1] op_sel_hi:[1,1] neg_lo:[0,1] neg_hi:[0,1]
	v_pk_mul_f32 v[222:223], v[98:99], v[212:213] op_sel:[0,1] op_sel_hi:[1,1] neg_lo:[0,1] neg_hi:[0,1]
	v_pk_fma_f32 v[216:217], v[112:113], v[122:123], v[216:217] op_sel_hi:[1,0,1]
	v_pk_fma_f32 v[218:219], v[114:115], v[122:123], v[218:219] op_sel_hi:[1,0,1]
	v_pk_fma_f32 v[220:221], v[112:113], v[122:123], v[220:221] op_sel:[0,1,0] op_sel_hi:[1,1,1]
	v_pk_fma_f32 v[222:223], v[114:115], v[122:123], v[222:223] op_sel:[0,1,0] op_sel_hi:[1,1,1]
	v_pk_fma_f32 v[8:9], v[8:9], v[188:189], v[216:217]
	v_pk_fma_f32 v[10:11], v[10:11], v[190:191], v[218:219]
	v_pk_fma_f32 v[24:25], v[24:25], v[188:189], v[220:221]
	v_pk_fma_f32 v[26:27], v[26:27], v[190:191], v[222:223]
	ds_read_b128 v[96:99], v232 offset:19744
	ds_read_b128 v[112:115], v232 offset:18720
	ds_read_b128 v[188:191], v232 offset:19232
	v_pk_mul_f32 v[224:225], v[100:101], v[212:213] op_sel_hi:[1,0] neg_lo:[0,1] neg_hi:[0,1]
	v_pk_mul_f32 v[226:227], v[102:103], v[212:213] op_sel_hi:[1,0] neg_lo:[0,1] neg_hi:[0,1]
	v_pk_mul_f32 v[228:229], v[100:101], v[212:213] op_sel:[0,1] op_sel_hi:[1,1] neg_lo:[0,1] neg_hi:[0,1]
	v_pk_mul_f32 v[230:231], v[102:103], v[212:213] op_sel:[0,1] op_sel_hi:[1,1] neg_lo:[0,1] neg_hi:[0,1]
	v_pk_fma_f32 v[224:225], v[116:117], v[122:123], v[224:225] op_sel_hi:[1,0,1]
	v_pk_fma_f32 v[226:227], v[118:119], v[122:123], v[226:227] op_sel_hi:[1,0,1]
	v_pk_fma_f32 v[228:229], v[116:117], v[122:123], v[228:229] op_sel:[0,1,0] op_sel_hi:[1,1,1]
	v_pk_fma_f32 v[230:231], v[118:119], v[122:123], v[230:231] op_sel:[0,1,0] op_sel_hi:[1,1,1]
	v_pk_fma_f32 v[12:13], v[12:13], v[192:193], v[224:225]
	v_pk_fma_f32 v[14:15], v[14:15], v[194:195], v[226:227]
	v_pk_fma_f32 v[28:29], v[28:29], v[192:193], v[228:229]
	v_pk_fma_f32 v[30:31], v[30:31], v[194:195], v[230:231]
	ds_read_b128 v[100:103], v232 offset:19760
	ds_read_b128 v[116:119], v232 offset:18736
	ds_read_b128 v[192:195], v232 offset:19248
	s_waitcnt lgkmcnt(13)
; #define SB __builtin_amdgcn_sched_barrier(0)
; #define CMP(G, c8) { CMP1(G, 0, 2 * (c8)) CMP1(G, 1, 2 * (c8) + 1) }
; __device__ __forceinline__ void phase_scan(const Args& a, unsigned char* lds) {
;     ...
;                     for (int s = 0; s < 16; ++s) {
;                         const float* vs = vb + s * 384;
;                         const float vi = vs[128 - cb + srow];
;                         f32x4 G0[8], G1[8], G2[8];
;                         LDG(G0, 0) SB;
;                         LDG(G1, 1) SB;
;                         f32x2 c0 = {0.f, 0.f}, c1 = {0.f, 0.f};
; #pragma unroll
;                         for (int j = 0; j < 8; ++j) { c0 += S2[2 * j] * (f32x2){KA[j][0], KA[j][1]}; c1 += S2[2 * j + 1] * (f32x2){KA[j][2], KA[j][3]}; }
;                         float cs = (c0.x + c0.y) + (c1.x + c1.y);
;                         cs += dpp_f(cs, 0);
;                         const float sa = -cs;
;                         const f32x2 sa2 = {sa, sa}, v2 = {vi, vi};
;                         f32x2 y0 = {0.f, 0.f}, y1 = {0.f, 0.f};
;                         SB; LDG(G2, 2) SB; CMP(G0, 0) SB;
;                         LDG(G0, 3) SB; CMP(G1, 1) SB;
;                         CMP(G2, 2) SB;
; #pragma unroll
;                         for (int j = 0; j < 8; ++j) KA[j] = *(const f32x4*)(vs + 384 + 256 + 4 * j);
;                         SB; CMP(G0, 3) SB;
;                         float ys = (y0.x + y0.y) + (y1.x + y1.y);
;                         ys += dpp_f(ys, 0);
;                         if ((lane & 1) == 0) yb[s * 64 + srow] = ys;
	v_pk_mul_f32 v[196:197], v[0:1], v[32:33]
	v_pk_mul_f32 v[200:201], v[16:17], v[32:33]
	v_pk_mul_f32 v[204:205], v[0:1], v[48:49]
	v_pk_mul_f32 v[208:209], v[16:17], v[48:49]
	v_pk_fma_f32 v[196:197], v[2:3], v[34:35], v[196:197]
	v_pk_fma_f32 v[200:201], v[18:19], v[34:35], v[200:201]
	v_pk_fma_f32 v[204:205], v[2:3], v[50:51], v[204:205]
	v_pk_fma_f32 v[208:209], v[18:19], v[50:51], v[208:209]
	ds_read_b128 v[32:35], v232 offset:20992
	ds_read_b128 v[48:51], v232 offset:18432
	v_pk_fma_f32 v[196:197], v[4:5], v[36:37], v[196:197]
	v_pk_fma_f32 v[200:201], v[20:21], v[36:37], v[200:201]
	v_pk_fma_f32 v[204:205], v[4:5], v[52:53], v[204:205]
	v_pk_fma_f32 v[208:209], v[20:21], v[52:53], v[208:209]
	v_pk_fma_f32 v[196:197], v[6:7], v[38:39], v[196:197]
	v_pk_fma_f32 v[200:201], v[22:23], v[38:39], v[200:201]
	v_pk_fma_f32 v[204:205], v[6:7], v[54:55], v[204:205]
	v_pk_fma_f32 v[208:209], v[22:23], v[54:55], v[208:209]
	ds_read_b128 v[36:39], v232 offset:21008
	ds_read_b128 v[52:55], v232 offset:18448
	v_pk_fma_f32 v[196:197], v[8:9], v[40:41], v[196:197]
	v_pk_fma_f32 v[200:201], v[24:25], v[40:41], v[200:201]
	v_pk_fma_f32 v[204:205], v[8:9], v[56:57], v[204:205]
	v_pk_fma_f32 v[208:209], v[24:25], v[56:57], v[208:209]
	v_pk_fma_f32 v[196:197], v[10:11], v[42:43], v[196:197]
	v_pk_fma_f32 v[200:201], v[26:27], v[42:43], v[200:201]
	v_pk_fma_f32 v[204:205], v[10:11], v[58:59], v[204:205]
	v_pk_fma_f32 v[208:209], v[26:27], v[58:59], v[208:209]
	ds_read_b128 v[40:43], v232 offset:21024
	ds_read_b128 v[56:59], v232 offset:18464
	v_pk_fma_f32 v[196:197], v[12:13], v[44:45], v[196:197]
	v_pk_fma_f32 v[200:201], v[28:29], v[44:45], v[200:201]
	v_pk_fma_f32 v[204:205], v[12:13], v[60:61], v[204:205]
	v_pk_fma_f32 v[208:209], v[28:29], v[60:61], v[208:209]
	v_pk_fma_f32 v[196:197], v[14:15], v[46:47], v[196:197]
	v_pk_fma_f32 v[200:201], v[30:31], v[46:47], v[200:201]
	v_pk_fma_f32 v[204:205], v[14:15], v[62:63], v[204:205]
	v_pk_fma_f32 v[208:209], v[30:31], v[62:63], v[208:209]
	ds_read_b128 v[44:47], v232 offset:21040
	ds_read_b128 v[60:63], v232 offset:18480
	v_add_f32_e32 v212, v196, v197
	v_add_f32_e32 v213, v200, v201
	v_add_f32_e32 v214, v204, v205
	v_add_f32_e32 v215, v208, v209
	v_add_f32_dpp v212, v212, v212 quad_perm:[1,0,3,2] row_mask:0xf bank_mask:0xf
	v_add_f32_dpp v213, v213, v213 quad_perm:[1,0,3,2] row_mask:0xf bank_mask:0xf
	v_add_f32_dpp v214, v214, v214 quad_perm:[1,0,3,2] row_mask:0xf bank_mask:0xf
	v_add_f32_dpp v215, v215, v215 quad_perm:[1,0,3,2] row_mask:0xf bank_mask:0xf
	v_add_f32_dpp v212, v212, v212 quad_perm:[2,3,0,1] row_mask:0xf bank_mask:0xf
	v_add_f32_dpp v213, v213, v213 quad_perm:[2,3,0,1] row_mask:0xf bank_mask:0xf
	v_add_f32_dpp v214, v214, v214 quad_perm:[2,3,0,1] row_mask:0xf bank_mask:0xf
	v_add_f32_dpp v215, v215, v215 quad_perm:[2,3,0,1] row_mask:0xf bank_mask:0xf
	ds_write_b64 v234, v[214:215] offset:2816
	s_waitcnt lgkmcnt(8)
	ds_read_b64 v[122:123], v233 offset:20480
	v_pk_mul_f32 v[216:217], v[88:89], v[212:213] op_sel_hi:[1,0] neg_lo:[0,1] neg_hi:[0,1]
	v_pk_mul_f32 v[218:219], v[90:91], v[212:213] op_sel_hi:[1,0] neg_lo:[0,1] neg_hi:[0,1]
	v_pk_mul_f32 v[220:221], v[88:89], v[212:213] op_sel:[0,1] op_sel_hi:[1,1] neg_lo:[0,1] neg_hi:[0,1]
	v_pk_mul_f32 v[222:223], v[90:91], v[212:213] op_sel:[0,1] op_sel_hi:[1,1] neg_lo:[0,1] neg_hi:[0,1]
	v_pk_fma_f32 v[216:217], v[104:105], v[120:121], v[216:217] op_sel_hi:[1,0,1]
	v_pk_fma_f32 v[218:219], v[106:107], v[120:121], v[218:219] op_sel_hi:[1,0,1]
	v_pk_fma_f32 v[220:221], v[104:105], v[120:121], v[220:221] op_sel:[0,1,0] op_sel_hi:[1,1,1]
	v_pk_fma_f32 v[222:223], v[106:107], v[120:121], v[222:223] op_sel:[0,1,0] op_sel_hi:[1,1,1]
	v_pk_fma_f32 v[0:1], v[0:1], v[180:181], v[216:217]
	v_pk_fma_f32 v[2:3], v[2:3], v[182:183], v[218:219]
	v_pk_fma_f32 v[16:17], v[16:17], v[180:181], v[220:221]
	v_pk_fma_f32 v[18:19], v[18:19], v[182:183], v[222:223]
	ds_read_b128 v[88:91], v232 offset:21248
	ds_read_b128 v[104:107], v232 offset:20224
	ds_read_b128 v[180:183], v232 offset:20736
	v_pk_mul_f32 v[224:225], v[92:93], v[212:213] op_sel_hi:[1,0] neg_lo:[0,1] neg_hi:[0,1]
	v_pk_mul_f32 v[226:227], v[94:95], v[212:213] op_sel_hi:[1,0] neg_lo:[0,1] neg_hi:[0,1]
	v_pk_mul_f32 v[228:229], v[92:93], v[212:213] op_sel:[0,1] op_sel_hi:[1,1] neg_lo:[0,1] neg_hi:[0,1]
	v_pk_mul_f32 v[230:231], v[94:95], v[212:213] op_sel:[0,1] op_sel_hi:[1,1] neg_lo:[0,1] neg_hi:[0,1]
	v_pk_fma_f32 v[224:225], v[108:109], v[120:121], v[224:225] op_sel_hi:[1,0,1]
	v_pk_fma_f32 v[226:227], v[110:111], v[120:121], v[226:227] op_sel_hi:[1,0,1]
	v_pk_fma_f32 v[228:229], v[108:109], v[120:121], v[228:229] op_sel:[0,1,0] op_sel_hi:[1,1,1]
	v_pk_fma_f32 v[230:231], v[110:111], v[120:121], v[230:231] op_sel:[0,1,0] op_sel_hi:[1,1,1]
	v_pk_fma_f32 v[4:5], v[4:5], v[184:185], v[224:225]
	v_pk_fma_f32 v[6:7], v[6:7], v[186:187], v[226:227]
	v_pk_fma_f32 v[20:21], v[20:21], v[184:185], v[228:229]
	v_pk_fma_f32 v[22:23], v[22:23], v[186:187], v[230:231]
	ds_read_b128 v[92:95], v232 offset:21264
	ds_read_b128 v[108:111], v232 offset:20240
	ds_read_b128 v[184:187], v232 offset:20752
	v_pk_mul_f32 v[216:217], v[96:97], v[212:213] op_sel_hi:[1,0] neg_lo:[0,1] neg_hi:[0,1]
	v_pk_mul_f32 v[218:219], v[98:99], v[212:213] op_sel_hi:[1,0] neg_lo:[0,1] neg_hi:[0,1]
	v_pk_mul_f32 v[220:221], v[96:97], v[212:213] op_sel:[0,1] op_sel_hi:[1,1] neg_lo:[0,1] neg_hi:[0,1]
	v_pk_mul_f32 v[222:223], v[98:99], v[212:213] op_sel:[0,1] op_sel_hi:[1,1] neg_lo:[0,1] neg_hi:[0,1]
	v_pk_fma_f32 v[216:217], v[112:113], v[120:121], v[216:217] op_sel_hi:[1,0,1]
	v_pk_fma_f32 v[218:219], v[114:115], v[120:121], v[218:219] op_sel_hi:[1,0,1]
; #define SB __builtin_amdgcn_sched_barrier(0)
; #define CMP(G, c8) { CMP1(G, 0, 2 * (c8)) CMP1(G, 1, 2 * (c8) + 1) }
; __device__ __forceinline__ void phase_scan(const Args& a, unsigned char* lds) {
;     ...
;                     for (int s = 0; s < 16; ++s) {
;                         const float* vs = vb + s * 384;
;                         const float vi = vs[128 - cb + srow];
;                         f32x4 G0[8], G1[8], G2[8];
;                         LDG(G0, 0) SB;
;                         LDG(G1, 1) SB;
;                         f32x2 c0 = {0.f, 0.f}, c1 = {0.f, 0.f};
; #pragma unroll
;                         for (int j = 0; j < 8; ++j) { c0 += S2[2 * j] * (f32x2){KA[j][0], KA[j][1]}; c1 += S2[2 * j + 1] * (f32x2){KA[j][2], KA[j][3]}; }
;                         float cs = (c0.x + c0.y) + (c1.x + c1.y);
;                         cs += dpp_f(cs, 0);
;                         const float sa = -cs;
;                         const f32x2 sa2 = {sa, sa}, v2 = {vi, vi};
;                         f32x2 y0 = {0.f, 0.f}, y1 = {0.f, 0.f};
;                         SB; LDG(G2, 2) SB; CMP(G0, 0) SB;
;                         LDG(G0, 3) SB; CMP(G1, 1) SB;
;                         CMP(G2, 2) SB;
; #pragma unroll
;                         for (int j = 0; j < 8; ++j) KA[j] = *(const f32x4*)(vs + 384 + 256 + 4 * j);
;                         SB; CMP(G0, 3) SB;
;                         float ys = (y0.x + y0.y) + (y1.x + y1.y);
;                         ys += dpp_f(ys, 0);
;                         if ((lane & 1) == 0) yb[s * 64 + srow] = ys;
	v_pk_fma_f32 v[220:221], v[112:113], v[120:121], v[220:221] op_sel:[0,1,0] op_sel_hi:[1,1,1]
	v_pk_fma_f32 v[222:223], v[114:115], v[120:121], v[222:223] op_sel:[0,1,0] op_sel_hi:[1,1,1]
	v_pk_fma_f32 v[8:9], v[8:9], v[188:189], v[216:217]
	v_pk_fma_f32 v[10:11], v[10:11], v[190:191], v[218:219]
	v_pk_fma_f32 v[24:25], v[24:25], v[188:189], v[220:221]
	v_pk_fma_f32 v[26:27], v[26:27], v[190:191], v[222:223]
	ds_read_b128 v[96:99], v232 offset:21280
	ds_read_b128 v[112:115], v232 offset:20256
	ds_read_b128 v[188:191], v232 offset:20768
	v_pk_mul_f32 v[224:225], v[100:101], v[212:213] op_sel_hi:[1,0] neg_lo:[0,1] neg_hi:[0,1]
	v_pk_mul_f32 v[226:227], v[102:103], v[212:213] op_sel_hi:[1,0] neg_lo:[0,1] neg_hi:[0,1]
	v_pk_mul_f32 v[228:229], v[100:101], v[212:213] op_sel:[0,1] op_sel_hi:[1,1] neg_lo:[0,1] neg_hi:[0,1]
	v_pk_mul_f32 v[230:231], v[102:103], v[212:213] op_sel:[0,1] op_sel_hi:[1,1] neg_lo:[0,1] neg_hi:[0,1]
	v_pk_fma_f32 v[224:225], v[116:117], v[120:121], v[224:225] op_sel_hi:[1,0,1]
	v_pk_fma_f32 v[226:227], v[118:119], v[120:121], v[226:227] op_sel_hi:[1,0,1]
	v_pk_fma_f32 v[228:229], v[116:117], v[120:121], v[228:229] op_sel:[0,1,0] op_sel_hi:[1,1,1]
	v_pk_fma_f32 v[230:231], v[118:119], v[120:121], v[230:231] op_sel:[0,1,0] op_sel_hi:[1,1,1]
	v_pk_fma_f32 v[12:13], v[12:13], v[192:193], v[224:225]
	v_pk_fma_f32 v[14:15], v[14:15], v[194:195], v[226:227]
	v_pk_fma_f32 v[28:29], v[28:29], v[192:193], v[228:229]
	v_pk_fma_f32 v[30:31], v[30:31], v[194:195], v[230:231]
	ds_read_b128 v[100:103], v232 offset:21296
	ds_read_b128 v[116:119], v232 offset:20272
	ds_read_b128 v[192:195], v232 offset:20784
	s_waitcnt lgkmcnt(13)
	v_pk_mul_f32 v[196:197], v[0:1], v[32:33]
	v_pk_mul_f32 v[200:201], v[16:17], v[32:33]
	v_pk_mul_f32 v[204:205], v[0:1], v[48:49]
	v_pk_mul_f32 v[208:209], v[16:17], v[48:49]
	v_pk_fma_f32 v[196:197], v[2:3], v[34:35], v[196:197]
	v_pk_fma_f32 v[200:201], v[18:19], v[34:35], v[200:201]
	v_pk_fma_f32 v[204:205], v[2:3], v[50:51], v[204:205]
	v_pk_fma_f32 v[208:209], v[18:19], v[50:51], v[208:209]
	ds_read_b128 v[32:35], v232 offset:22528
	ds_read_b128 v[48:51], v232 offset:19968
	v_pk_fma_f32 v[196:197], v[4:5], v[36:37], v[196:197]
	v_pk_fma_f32 v[200:201], v[20:21], v[36:37], v[200:201]
	v_pk_fma_f32 v[204:205], v[4:5], v[52:53], v[204:205]
	v_pk_fma_f32 v[208:209], v[20:21], v[52:53], v[208:209]
	v_pk_fma_f32 v[196:197], v[6:7], v[38:39], v[196:197]
	v_pk_fma_f32 v[200:201], v[22:23], v[38:39], v[200:201]
	v_pk_fma_f32 v[204:205], v[6:7], v[54:55], v[204:205]
	v_pk_fma_f32 v[208:209], v[22:23], v[54:55], v[208:209]
	ds_read_b128 v[36:39], v232 offset:22544
	ds_read_b128 v[52:55], v232 offset:19984
	v_pk_fma_f32 v[196:197], v[8:9], v[40:41], v[196:197]
	v_pk_fma_f32 v[200:201], v[24:25], v[40:41], v[200:201]
	v_pk_fma_f32 v[204:205], v[8:9], v[56:57], v[204:205]
	v_pk_fma_f32 v[208:209], v[24:25], v[56:57], v[208:209]
	v_pk_fma_f32 v[196:197], v[10:11], v[42:43], v[196:197]
	v_pk_fma_f32 v[200:201], v[26:27], v[42:43], v[200:201]
	v_pk_fma_f32 v[204:205], v[10:11], v[58:59], v[204:205]
	v_pk_fma_f32 v[208:209], v[26:27], v[58:59], v[208:209]
	ds_read_b128 v[40:43], v232 offset:22560
	ds_read_b128 v[56:59], v232 offset:20000
	v_pk_fma_f32 v[196:197], v[12:13], v[44:45], v[196:197]
	v_pk_fma_f32 v[200:201], v[28:29], v[44:45], v[200:201]
	v_pk_fma_f32 v[204:205], v[12:13], v[60:61], v[204:205]
	v_pk_fma_f32 v[208:209], v[28:29], v[60:61], v[208:209]
	v_pk_fma_f32 v[196:197], v[14:15], v[46:47], v[196:197]
	v_pk_fma_f32 v[200:201], v[30:31], v[46:47], v[200:201]
	v_pk_fma_f32 v[204:205], v[14:15], v[62:63], v[204:205]
	v_pk_fma_f32 v[208:209], v[30:31], v[62:63], v[208:209]
	ds_read_b128 v[44:47], v232 offset:22576
	ds_read_b128 v[60:63], v232 offset:20016
	v_add_f32_e32 v212, v196, v197
	v_add_f32_e32 v213, v200, v201
	v_add_f32_e32 v214, v204, v205
	v_add_f32_e32 v215, v208, v209
	v_add_f32_dpp v212, v212, v212 quad_perm:[1,0,3,2] row_mask:0xf bank_mask:0xf
	v_add_f32_dpp v213, v213, v213 quad_perm:[1,0,3,2] row_mask:0xf bank_mask:0xf
	v_add_f32_dpp v214, v214, v214 quad_perm:[1,0,3,2] row_mask:0xf bank_mask:0xf
	v_add_f32_dpp v215, v215, v215 quad_perm:[1,0,3,2] row_mask:0xf bank_mask:0xf
	v_add_f32_dpp v212, v212, v212 quad_perm:[2,3,0,1] row_mask:0xf bank_mask:0xf
	v_add_f32_dpp v213, v213, v213 quad_perm:[2,3,0,1] row_mask:0xf bank_mask:0xf
	v_add_f32_dpp v214, v214, v214 quad_perm:[2,3,0,1] row_mask:0xf bank_mask:0xf
	v_add_f32_dpp v215, v215, v215 quad_perm:[2,3,0,1] row_mask:0xf bank_mask:0xf
	ds_write_b64 v234, v[214:215] offset:3072
	s_waitcnt lgkmcnt(8)
; #define SB __builtin_amdgcn_sched_barrier(0)
; #define CMP(G, c8) { CMP1(G, 0, 2 * (c8)) CMP1(G, 1, 2 * (c8) + 1) }
; __device__ __forceinline__ void phase_scan(const Args& a, unsigned char* lds) {
;     ...
;                     for (int s = 0; s < 16; ++s) {
;                         const float* vs = vb + s * 384;
;                         const float vi = vs[128 - cb + srow];
;                         f32x4 G0[8], G1[8], G2[8];
;                         LDG(G0, 0) SB;
;                         LDG(G1, 1) SB;
;                         f32x2 c0 = {0.f, 0.f}, c1 = {0.f, 0.f};
; #pragma unroll
;                         for (int j = 0; j < 8; ++j) { c0 += S2[2 * j] * (f32x2){KA[j][0], KA[j][1]}; c1 += S2[2 * j + 1] * (f32x2){KA[j][2], KA[j][3]}; }
;                         float cs = (c0.x + c0.y) + (c1.x + c1.y);
;                         cs += dpp_f(cs, 0);
;                         const float sa = -cs;
;                         const f32x2 sa2 = {sa, sa}, v2 = {vi, vi};
;                         f32x2 y0 = {0.f, 0.f}, y1 = {0.f, 0.f};
;                         SB; LDG(G2, 2) SB; CMP(G0, 0) SB;
;                         LDG(G0, 3) SB; CMP(G1, 1) SB;
;                         CMP(G2, 2) SB;
; #pragma unroll
;                         for (int j = 0; j < 8; ++j) KA[j] = *(const f32x4*)(vs + 384 + 256 + 4 * j);
;                         SB; CMP(G0, 3) SB;
;                         float ys = (y0.x + y0.y) + (y1.x + y1.y);
;                         ys += dpp_f(ys, 0);
;                         if ((lane & 1) == 0) yb[s * 64 + srow] = ys;
	ds_read_b64 v[120:121], v233 offset:22016
	v_pk_mul_f32 v[216:217], v[88:89], v[212:213] op_sel_hi:[1,0] neg_lo:[0,1] neg_hi:[0,1]
	v_pk_mul_f32 v[218:219], v[90:91], v[212:213] op_sel_hi:[1,0] neg_lo:[0,1] neg_hi:[0,1]
	v_pk_mul_f32 v[220:221], v[88:89], v[212:213] op_sel:[0,1] op_sel_hi:[1,1] neg_lo:[0,1] neg_hi:[0,1]
	v_pk_mul_f32 v[222:223], v[90:91], v[212:213] op_sel:[0,1] op_sel_hi:[1,1] neg_lo:[0,1] neg_hi:[0,1]
	v_pk_fma_f32 v[216:217], v[104:105], v[122:123], v[216:217] op_sel_hi:[1,0,1]
	v_pk_fma_f32 v[218:219], v[106:107], v[122:123], v[218:219] op_sel_hi:[1,0,1]
	v_pk_fma_f32 v[220:221], v[104:105], v[122:123], v[220:221] op_sel:[0,1,0] op_sel_hi:[1,1,1]
	v_pk_fma_f32 v[222:223], v[106:107], v[122:123], v[222:223] op_sel:[0,1,0] op_sel_hi:[1,1,1]
	v_pk_fma_f32 v[0:1], v[0:1], v[180:181], v[216:217]
	v_pk_fma_f32 v[2:3], v[2:3], v[182:183], v[218:219]
	v_pk_fma_f32 v[16:17], v[16:17], v[180:181], v[220:221]
	v_pk_fma_f32 v[18:19], v[18:19], v[182:183], v[222:223]
	ds_read_b128 v[88:91], v232 offset:22784
	ds_read_b128 v[104:107], v232 offset:21760
	ds_read_b128 v[180:183], v232 offset:22272
	v_pk_mul_f32 v[224:225], v[92:93], v[212:213] op_sel_hi:[1,0] neg_lo:[0,1] neg_hi:[0,1]
	v_pk_mul_f32 v[226:227], v[94:95], v[212:213] op_sel_hi:[1,0] neg_lo:[0,1] neg_hi:[0,1]
	v_pk_mul_f32 v[228:229], v[92:93], v[212:213] op_sel:[0,1] op_sel_hi:[1,1] neg_lo:[0,1] neg_hi:[0,1]
	v_pk_mul_f32 v[230:231], v[94:95], v[212:213] op_sel:[0,1] op_sel_hi:[1,1] neg_lo:[0,1] neg_hi:[0,1]
	v_pk_fma_f32 v[224:225], v[108:109], v[122:123], v[224:225] op_sel_hi:[1,0,1]
	v_pk_fma_f32 v[226:227], v[110:111], v[122:123], v[226:227] op_sel_hi:[1,0,1]
	v_pk_fma_f32 v[228:229], v[108:109], v[122:123], v[228:229] op_sel:[0,1,0] op_sel_hi:[1,1,1]
	v_pk_fma_f32 v[230:231], v[110:111], v[122:123], v[230:231] op_sel:[0,1,0] op_sel_hi:[1,1,1]
	v_pk_fma_f32 v[4:5], v[4:5], v[184:185], v[224:225]
	v_pk_fma_f32 v[6:7], v[6:7], v[186:187], v[226:227]
	v_pk_fma_f32 v[20:21], v[20:21], v[184:185], v[228:229]
	v_pk_fma_f32 v[22:23], v[22:23], v[186:187], v[230:231]
	ds_read_b128 v[92:95], v232 offset:22800
	ds_read_b128 v[108:111], v232 offset:21776
	ds_read_b128 v[184:187], v232 offset:22288
	v_pk_mul_f32 v[216:217], v[96:97], v[212:213] op_sel_hi:[1,0] neg_lo:[0,1] neg_hi:[0,1]
	v_pk_mul_f32 v[218:219], v[98:99], v[212:213] op_sel_hi:[1,0] neg_lo:[0,1] neg_hi:[0,1]
	v_pk_mul_f32 v[220:221], v[96:97], v[212:213] op_sel:[0,1] op_sel_hi:[1,1] neg_lo:[0,1] neg_hi:[0,1]
	v_pk_mul_f32 v[222:223], v[98:99], v[212:213] op_sel:[0,1] op_sel_hi:[1,1] neg_lo:[0,1] neg_hi:[0,1]
	v_pk_fma_f32 v[216:217], v[112:113], v[122:123], v[216:217] op_sel_hi:[1,0,1]
	v_pk_fma_f32 v[218:219], v[114:115], v[122:123], v[218:219] op_sel_hi:[1,0,1]
	v_pk_fma_f32 v[220:221], v[112:113], v[122:123], v[220:221] op_sel:[0,1,0] op_sel_hi:[1,1,1]
	v_pk_fma_f32 v[222:223], v[114:115], v[122:123], v[222:223] op_sel:[0,1,0] op_sel_hi:[1,1,1]
	v_pk_fma_f32 v[8:9], v[8:9], v[188:189], v[216:217]
	v_pk_fma_f32 v[10:11], v[10:11], v[190:191], v[218:219]
	v_pk_fma_f32 v[24:25], v[24:25], v[188:189], v[220:221]
	v_pk_fma_f32 v[26:27], v[26:27], v[190:191], v[222:223]
	ds_read_b128 v[96:99], v232 offset:22816
	ds_read_b128 v[112:115], v232 offset:21792
	ds_read_b128 v[188:191], v232 offset:22304
	v_pk_mul_f32 v[224:225], v[100:101], v[212:213] op_sel_hi:[1,0] neg_lo:[0,1] neg_hi:[0,1]
	v_pk_mul_f32 v[226:227], v[102:103], v[212:213] op_sel_hi:[1,0] neg_lo:[0,1] neg_hi:[0,1]
	v_pk_mul_f32 v[228:229], v[100:101], v[212:213] op_sel:[0,1] op_sel_hi:[1,1] neg_lo:[0,1] neg_hi:[0,1]
	v_pk_mul_f32 v[230:231], v[102:103], v[212:213] op_sel:[0,1] op_sel_hi:[1,1] neg_lo:[0,1] neg_hi:[0,1]
	v_pk_fma_f32 v[224:225], v[116:117], v[122:123], v[224:225] op_sel_hi:[1,0,1]
	v_pk_fma_f32 v[226:227], v[118:119], v[122:123], v[226:227] op_sel_hi:[1,0,1]
	v_pk_fma_f32 v[228:229], v[116:117], v[122:123], v[228:229] op_sel:[0,1,0] op_sel_hi:[1,1,1]
	v_pk_fma_f32 v[230:231], v[118:119], v[122:123], v[230:231] op_sel:[0,1,0] op_sel_hi:[1,1,1]
	v_pk_fma_f32 v[12:13], v[12:13], v[192:193], v[224:225]
	v_pk_fma_f32 v[14:15], v[14:15], v[194:195], v[226:227]
	v_pk_fma_f32 v[28:29], v[28:29], v[192:193], v[228:229]
	v_pk_fma_f32 v[30:31], v[30:31], v[194:195], v[230:231]
	ds_read_b128 v[100:103], v232 offset:22832
	ds_read_b128 v[116:119], v232 offset:21808
	ds_read_b128 v[192:195], v232 offset:22320
	s_waitcnt lgkmcnt(13)
; #define SB __builtin_amdgcn_sched_barrier(0)
; #define CMP(G, c8) { CMP1(G, 0, 2 * (c8)) CMP1(G, 1, 2 * (c8) + 1) }
; __device__ __forceinline__ void phase_scan(const Args& a, unsigned char* lds) {
;     ...
;                     for (int s = 0; s < 16; ++s) {
;                         const float* vs = vb + s * 384;
;                         const float vi = vs[128 - cb + srow];
;                         f32x4 G0[8], G1[8], G2[8];
;                         LDG(G0, 0) SB;
;                         LDG(G1, 1) SB;
;                         f32x2 c0 = {0.f, 0.f}, c1 = {0.f, 0.f};
; #pragma unroll
;                         for (int j = 0; j < 8; ++j) { c0 += S2[2 * j] * (f32x2){KA[j][0], KA[j][1]}; c1 += S2[2 * j + 1] * (f32x2){KA[j][2], KA[j][3]}; }
;                         float cs = (c0.x + c0.y) + (c1.x + c1.y);
;                         cs += dpp_f(cs, 0);
;                         const float sa = -cs;
;                         const f32x2 sa2 = {sa, sa}, v2 = {vi, vi};
;                         f32x2 y0 = {0.f, 0.f}, y1 = {0.f, 0.f};
;                         SB; LDG(G2, 2) SB; CMP(G0, 0) SB;
;                         LDG(G0, 3) SB; CMP(G1, 1) SB;
;                         CMP(G2, 2) SB;
; #pragma unroll
;                         for (int j = 0; j < 8; ++j) KA[j] = *(const f32x4*)(vs + 384 + 256 + 4 * j);
;                         SB; CMP(G0, 3) SB;
;                         float ys = (y0.x + y0.y) + (y1.x + y1.y);
;                         ys += dpp_f(ys, 0);
;                         if ((lane & 1) == 0) yb[s * 64 + srow] = ys;
	v_pk_mul_f32 v[196:197], v[0:1], v[32:33]
	v_pk_mul_f32 v[200:201], v[16:17], v[32:33]
	v_pk_mul_f32 v[204:205], v[0:1], v[48:49]
	v_pk_mul_f32 v[208:209], v[16:17], v[48:49]
	v_pk_fma_f32 v[196:197], v[2:3], v[34:35], v[196:197]
	v_pk_fma_f32 v[200:201], v[18:19], v[34:35], v[200:201]
	v_pk_fma_f32 v[204:205], v[2:3], v[50:51], v[204:205]
	v_pk_fma_f32 v[208:209], v[18:19], v[50:51], v[208:209]
	ds_read_b128 v[32:35], v232 offset:24064
	ds_read_b128 v[48:51], v232 offset:21504
	v_pk_fma_f32 v[196:197], v[4:5], v[36:37], v[196:197]
	v_pk_fma_f32 v[200:201], v[20:21], v[36:37], v[200:201]
	v_pk_fma_f32 v[204:205], v[4:5], v[52:53], v[204:205]
	v_pk_fma_f32 v[208:209], v[20:21], v[52:53], v[208:209]
	v_pk_fma_f32 v[196:197], v[6:7], v[38:39], v[196:197]
	v_pk_fma_f32 v[200:201], v[22:23], v[38:39], v[200:201]
	v_pk_fma_f32 v[204:205], v[6:7], v[54:55], v[204:205]
	v_pk_fma_f32 v[208:209], v[22:23], v[54:55], v[208:209]
	ds_read_b128 v[36:39], v232 offset:24080
	ds_read_b128 v[52:55], v232 offset:21520
	v_pk_fma_f32 v[196:197], v[8:9], v[40:41], v[196:197]
	v_pk_fma_f32 v[200:201], v[24:25], v[40:41], v[200:201]
	v_pk_fma_f32 v[204:205], v[8:9], v[56:57], v[204:205]
	v_pk_fma_f32 v[208:209], v[24:25], v[56:57], v[208:209]
	v_pk_fma_f32 v[196:197], v[10:11], v[42:43], v[196:197]
	v_pk_fma_f32 v[200:201], v[26:27], v[42:43], v[200:201]
	v_pk_fma_f32 v[204:205], v[10:11], v[58:59], v[204:205]
	v_pk_fma_f32 v[208:209], v[26:27], v[58:59], v[208:209]
	ds_read_b128 v[40:43], v232 offset:24096
	ds_read_b128 v[56:59], v232 offset:21536
	v_pk_fma_f32 v[196:197], v[12:13], v[44:45], v[196:197]
	v_pk_fma_f32 v[200:201], v[28:29], v[44:45], v[200:201]
	v_pk_fma_f32 v[204:205], v[12:13], v[60:61], v[204:205]
	v_pk_fma_f32 v[208:209], v[28:29], v[60:61], v[208:209]
	v_pk_fma_f32 v[196:197], v[14:15], v[46:47], v[196:197]
	v_pk_fma_f32 v[200:201], v[30:31], v[46:47], v[200:201]
	v_pk_fma_f32 v[204:205], v[14:15], v[62:63], v[204:205]
	v_pk_fma_f32 v[208:209], v[30:31], v[62:63], v[208:209]
	ds_read_b128 v[44:47], v232 offset:24112
	ds_read_b128 v[60:63], v232 offset:21552
	v_add_f32_e32 v212, v196, v197
	v_add_f32_e32 v213, v200, v201
	v_add_f32_e32 v214, v204, v205
	v_add_f32_e32 v215, v208, v209
	v_add_f32_dpp v212, v212, v212 quad_perm:[1,0,3,2] row_mask:0xf bank_mask:0xf
	v_add_f32_dpp v213, v213, v213 quad_perm:[1,0,3,2] row_mask:0xf bank_mask:0xf
	v_add_f32_dpp v214, v214, v214 quad_perm:[1,0,3,2] row_mask:0xf bank_mask:0xf
	v_add_f32_dpp v215, v215, v215 quad_perm:[1,0,3,2] row_mask:0xf bank_mask:0xf
	v_add_f32_dpp v212, v212, v212 quad_perm:[2,3,0,1] row_mask:0xf bank_mask:0xf
	v_add_f32_dpp v213, v213, v213 quad_perm:[2,3,0,1] row_mask:0xf bank_mask:0xf
	v_add_f32_dpp v214, v214, v214 quad_perm:[2,3,0,1] row_mask:0xf bank_mask:0xf
	v_add_f32_dpp v215, v215, v215 quad_perm:[2,3,0,1] row_mask:0xf bank_mask:0xf
	ds_write_b64 v234, v[214:215] offset:3328
	s_waitcnt lgkmcnt(8)
	ds_read_b64 v[122:123], v233 offset:23552
	v_pk_mul_f32 v[216:217], v[88:89], v[212:213] op_sel_hi:[1,0] neg_lo:[0,1] neg_hi:[0,1]
	v_pk_mul_f32 v[218:219], v[90:91], v[212:213] op_sel_hi:[1,0] neg_lo:[0,1] neg_hi:[0,1]
	v_pk_mul_f32 v[220:221], v[88:89], v[212:213] op_sel:[0,1] op_sel_hi:[1,1] neg_lo:[0,1] neg_hi:[0,1]
	v_pk_mul_f32 v[222:223], v[90:91], v[212:213] op_sel:[0,1] op_sel_hi:[1,1] neg_lo:[0,1] neg_hi:[0,1]
	v_pk_fma_f32 v[216:217], v[104:105], v[120:121], v[216:217] op_sel_hi:[1,0,1]
	v_pk_fma_f32 v[218:219], v[106:107], v[120:121], v[218:219] op_sel_hi:[1,0,1]
	v_pk_fma_f32 v[220:221], v[104:105], v[120:121], v[220:221] op_sel:[0,1,0] op_sel_hi:[1,1,1]
	v_pk_fma_f32 v[222:223], v[106:107], v[120:121], v[222:223] op_sel:[0,1,0] op_sel_hi:[1,1,1]
	v_pk_fma_f32 v[0:1], v[0:1], v[180:181], v[216:217]
	v_pk_fma_f32 v[2:3], v[2:3], v[182:183], v[218:219]
	v_pk_fma_f32 v[16:17], v[16:17], v[180:181], v[220:221]
	v_pk_fma_f32 v[18:19], v[18:19], v[182:183], v[222:223]
	ds_read_b128 v[88:91], v232 offset:24320
	ds_read_b128 v[104:107], v232 offset:23296
	ds_read_b128 v[180:183], v232 offset:23808
	v_pk_mul_f32 v[224:225], v[92:93], v[212:213] op_sel_hi:[1,0] neg_lo:[0,1] neg_hi:[0,1]
	v_pk_mul_f32 v[226:227], v[94:95], v[212:213] op_sel_hi:[1,0] neg_lo:[0,1] neg_hi:[0,1]
	v_pk_mul_f32 v[228:229], v[92:93], v[212:213] op_sel:[0,1] op_sel_hi:[1,1] neg_lo:[0,1] neg_hi:[0,1]
	v_pk_mul_f32 v[230:231], v[94:95], v[212:213] op_sel:[0,1] op_sel_hi:[1,1] neg_lo:[0,1] neg_hi:[0,1]
	v_pk_fma_f32 v[224:225], v[108:109], v[120:121], v[224:225] op_sel_hi:[1,0,1]
	v_pk_fma_f32 v[226:227], v[110:111], v[120:121], v[226:227] op_sel_hi:[1,0,1]
	v_pk_fma_f32 v[228:229], v[108:109], v[120:121], v[228:229] op_sel:[0,1,0] op_sel_hi:[1,1,1]
	v_pk_fma_f32 v[230:231], v[110:111], v[120:121], v[230:231] op_sel:[0,1,0] op_sel_hi:[1,1,1]
	v_pk_fma_f32 v[4:5], v[4:5], v[184:185], v[224:225]
	v_pk_fma_f32 v[6:7], v[6:7], v[186:187], v[226:227]
	v_pk_fma_f32 v[20:21], v[20:21], v[184:185], v[228:229]
	v_pk_fma_f32 v[22:23], v[22:23], v[186:187], v[230:231]
	ds_read_b128 v[92:95], v232 offset:24336
	ds_read_b128 v[108:111], v232 offset:23312
	ds_read_b128 v[184:187], v232 offset:23824
	v_pk_mul_f32 v[216:217], v[96:97], v[212:213] op_sel_hi:[1,0] neg_lo:[0,1] neg_hi:[0,1]
	v_pk_mul_f32 v[218:219], v[98:99], v[212:213] op_sel_hi:[1,0] neg_lo:[0,1] neg_hi:[0,1]
	v_pk_mul_f32 v[220:221], v[96:97], v[212:213] op_sel:[0,1] op_sel_hi:[1,1] neg_lo:[0,1] neg_hi:[0,1]
	v_pk_mul_f32 v[222:223], v[98:99], v[212:213] op_sel:[0,1] op_sel_hi:[1,1] neg_lo:[0,1] neg_hi:[0,1]
	v_pk_fma_f32 v[216:217], v[112:113], v[120:121], v[216:217] op_sel_hi:[1,0,1]
	v_pk_fma_f32 v[218:219], v[114:115], v[120:121], v[218:219] op_sel_hi:[1,0,1]
; #define SB __builtin_amdgcn_sched_barrier(0)
; #define CMP(G, c8) { CMP1(G, 0, 2 * (c8)) CMP1(G, 1, 2 * (c8) + 1) }
; __device__ __forceinline__ void phase_scan(const Args& a, unsigned char* lds) {
;     ...
;                     for (int s = 0; s < 16; ++s) {
;                         const float* vs = vb + s * 384;
;                         const float vi = vs[128 - cb + srow];
;                         f32x4 G0[8], G1[8], G2[8];
;                         LDG(G0, 0) SB;
;                         LDG(G1, 1) SB;
;                         f32x2 c0 = {0.f, 0.f}, c1 = {0.f, 0.f};
; #pragma unroll
;                         for (int j = 0; j < 8; ++j) { c0 += S2[2 * j] * (f32x2){KA[j][0], KA[j][1]}; c1 += S2[2 * j + 1] * (f32x2){KA[j][2], KA[j][3]}; }
;                         float cs = (c0.x + c0.y) + (c1.x + c1.y);
;                         cs += dpp_f(cs, 0);
;                         const float sa = -cs;
;                         const f32x2 sa2 = {sa, sa}, v2 = {vi, vi};
;                         f32x2 y0 = {0.f, 0.f}, y1 = {0.f, 0.f};
;                         SB; LDG(G2, 2) SB; CMP(G0, 0) SB;
;                         LDG(G0, 3) SB; CMP(G1, 1) SB;
;                         CMP(G2, 2) SB;
; #pragma unroll
;                         for (int j = 0; j < 8; ++j) KA[j] = *(const f32x4*)(vs + 384 + 256 + 4 * j);
;                         SB; CMP(G0, 3) SB;
;                         float ys = (y0.x + y0.y) + (y1.x + y1.y);
;                         ys += dpp_f(ys, 0);
;                         if ((lane & 1) == 0) yb[s * 64 + srow] = ys;
	v_pk_fma_f32 v[220:221], v[112:113], v[120:121], v[220:221] op_sel:[0,1,0] op_sel_hi:[1,1,1]
	v_pk_fma_f32 v[222:223], v[114:115], v[120:121], v[222:223] op_sel:[0,1,0] op_sel_hi:[1,1,1]
	v_pk_fma_f32 v[8:9], v[8:9], v[188:189], v[216:217]
	v_pk_fma_f32 v[10:11], v[10:11], v[190:191], v[218:219]
	v_pk_fma_f32 v[24:25], v[24:25], v[188:189], v[220:221]
	v_pk_fma_f32 v[26:27], v[26:27], v[190:191], v[222:223]
	ds_read_b128 v[96:99], v232 offset:24352
	ds_read_b128 v[112:115], v232 offset:23328
	ds_read_b128 v[188:191], v232 offset:23840
	v_pk_mul_f32 v[224:225], v[100:101], v[212:213] op_sel_hi:[1,0] neg_lo:[0,1] neg_hi:[0,1]
	v_pk_mul_f32 v[226:227], v[102:103], v[212:213] op_sel_hi:[1,0] neg_lo:[0,1] neg_hi:[0,1]
	v_pk_mul_f32 v[228:229], v[100:101], v[212:213] op_sel:[0,1] op_sel_hi:[1,1] neg_lo:[0,1] neg_hi:[0,1]
	v_pk_mul_f32 v[230:231], v[102:103], v[212:213] op_sel:[0,1] op_sel_hi:[1,1] neg_lo:[0,1] neg_hi:[0,1]
	v_pk_fma_f32 v[224:225], v[116:117], v[120:121], v[224:225] op_sel_hi:[1,0,1]
	v_pk_fma_f32 v[226:227], v[118:119], v[120:121], v[226:227] op_sel_hi:[1,0,1]
	v_pk_fma_f32 v[228:229], v[116:117], v[120:121], v[228:229] op_sel:[0,1,0] op_sel_hi:[1,1,1]
	v_pk_fma_f32 v[230:231], v[118:119], v[120:121], v[230:231] op_sel:[0,1,0] op_sel_hi:[1,1,1]
	v_pk_fma_f32 v[12:13], v[12:13], v[192:193], v[224:225]
	v_pk_fma_f32 v[14:15], v[14:15], v[194:195], v[226:227]
	v_pk_fma_f32 v[28:29], v[28:29], v[192:193], v[228:229]
	v_pk_fma_f32 v[30:31], v[30:31], v[194:195], v[230:231]
	ds_read_b128 v[100:103], v232 offset:24368
	ds_read_b128 v[116:119], v232 offset:23344
	ds_read_b128 v[192:195], v232 offset:23856
	s_waitcnt lgkmcnt(13)
	v_pk_mul_f32 v[196:197], v[0:1], v[32:33]
	v_pk_mul_f32 v[200:201], v[16:17], v[32:33]
	v_pk_mul_f32 v[204:205], v[0:1], v[48:49]
	v_pk_mul_f32 v[208:209], v[16:17], v[48:49]
	v_pk_fma_f32 v[196:197], v[2:3], v[34:35], v[196:197]
	v_pk_fma_f32 v[200:201], v[18:19], v[34:35], v[200:201]
	v_pk_fma_f32 v[204:205], v[2:3], v[50:51], v[204:205]
	v_pk_fma_f32 v[208:209], v[18:19], v[50:51], v[208:209]
	ds_read_b128 v[32:35], v232 offset:25600
	ds_read_b128 v[48:51], v232 offset:23040
	v_pk_fma_f32 v[196:197], v[4:5], v[36:37], v[196:197]
	v_pk_fma_f32 v[200:201], v[20:21], v[36:37], v[200:201]
	v_pk_fma_f32 v[204:205], v[4:5], v[52:53], v[204:205]
	v_pk_fma_f32 v[208:209], v[20:21], v[52:53], v[208:209]
	v_pk_fma_f32 v[196:197], v[6:7], v[38:39], v[196:197]
	v_pk_fma_f32 v[200:201], v[22:23], v[38:39], v[200:201]
	v_pk_fma_f32 v[204:205], v[6:7], v[54:55], v[204:205]
	v_pk_fma_f32 v[208:209], v[22:23], v[54:55], v[208:209]
	ds_read_b128 v[36:39], v232 offset:25616
	ds_read_b128 v[52:55], v232 offset:23056
	v_pk_fma_f32 v[196:197], v[8:9], v[40:41], v[196:197]
	v_pk_fma_f32 v[200:201], v[24:25], v[40:41], v[200:201]
	v_pk_fma_f32 v[204:205], v[8:9], v[56:57], v[204:205]
	v_pk_fma_f32 v[208:209], v[24:25], v[56:57], v[208:209]
	v_pk_fma_f32 v[196:197], v[10:11], v[42:43], v[196:197]
	v_pk_fma_f32 v[200:201], v[26:27], v[42:43], v[200:201]
	v_pk_fma_f32 v[204:205], v[10:11], v[58:59], v[204:205]
	v_pk_fma_f32 v[208:209], v[26:27], v[58:59], v[208:209]
	ds_read_b128 v[40:43], v232 offset:25632
	ds_read_b128 v[56:59], v232 offset:23072
	v_pk_fma_f32 v[196:197], v[12:13], v[44:45], v[196:197]
	v_pk_fma_f32 v[200:201], v[28:29], v[44:45], v[200:201]
	v_pk_fma_f32 v[204:205], v[12:13], v[60:61], v[204:205]
	v_pk_fma_f32 v[208:209], v[28:29], v[60:61], v[208:209]
	v_pk_fma_f32 v[196:197], v[14:15], v[46:47], v[196:197]
	v_pk_fma_f32 v[200:201], v[30:31], v[46:47], v[200:201]
	v_pk_fma_f32 v[204:205], v[14:15], v[62:63], v[204:205]
	v_pk_fma_f32 v[208:209], v[30:31], v[62:63], v[208:209]
	ds_read_b128 v[44:47], v232 offset:25648
	ds_read_b128 v[60:63], v232 offset:23088
	v_add_f32_e32 v212, v196, v197
	v_add_f32_e32 v213, v200, v201
	v_add_f32_e32 v214, v204, v205
	v_add_f32_e32 v215, v208, v209
	v_add_f32_dpp v212, v212, v212 quad_perm:[1,0,3,2] row_mask:0xf bank_mask:0xf
	v_add_f32_dpp v213, v213, v213 quad_perm:[1,0,3,2] row_mask:0xf bank_mask:0xf
	v_add_f32_dpp v214, v214, v214 quad_perm:[1,0,3,2] row_mask:0xf bank_mask:0xf
	v_add_f32_dpp v215, v215, v215 quad_perm:[1,0,3,2] row_mask:0xf bank_mask:0xf
	v_add_f32_dpp v212, v212, v212 quad_perm:[2,3,0,1] row_mask:0xf bank_mask:0xf
	v_add_f32_dpp v213, v213, v213 quad_perm:[2,3,0,1] row_mask:0xf bank_mask:0xf
	v_add_f32_dpp v214, v214, v214 quad_perm:[2,3,0,1] row_mask:0xf bank_mask:0xf
	v_add_f32_dpp v215, v215, v215 quad_perm:[2,3,0,1] row_mask:0xf bank_mask:0xf
	ds_write_b64 v234, v[214:215] offset:3584
	s_waitcnt lgkmcnt(8)
; #define SB __builtin_amdgcn_sched_barrier(0)
; #define CMP(G, c8) { CMP1(G, 0, 2 * (c8)) CMP1(G, 1, 2 * (c8) + 1) }
; __device__ __forceinline__ void phase_scan(const Args& a, unsigned char* lds) {
;     ...
;                     for (int s = 0; s < 16; ++s) {
;                         const float* vs = vb + s * 384;
;                         const float vi = vs[128 - cb + srow];
;                         f32x4 G0[8], G1[8], G2[8];
;                         LDG(G0, 0) SB;
;                         LDG(G1, 1) SB;
;                         f32x2 c0 = {0.f, 0.f}, c1 = {0.f, 0.f};
; #pragma unroll
;                         for (int j = 0; j < 8; ++j) { c0 += S2[2 * j] * (f32x2){KA[j][0], KA[j][1]}; c1 += S2[2 * j + 1] * (f32x2){KA[j][2], KA[j][3]}; }
;                         float cs = (c0.x + c0.y) + (c1.x + c1.y);
;                         cs += dpp_f(cs, 0);
;                         const float sa = -cs;
;                         const f32x2 sa2 = {sa, sa}, v2 = {vi, vi};
;                         f32x2 y0 = {0.f, 0.f}, y1 = {0.f, 0.f};
;                         SB; LDG(G2, 2) SB; CMP(G0, 0) SB;
;                         LDG(G0, 3) SB; CMP(G1, 1) SB;
;                         CMP(G2, 2) SB;
; #pragma unroll
;                         for (int j = 0; j < 8; ++j) KA[j] = *(const f32x4*)(vs + 384 + 256 + 4 * j);
;                         SB; CMP(G0, 3) SB;
;                         float ys = (y0.x + y0.y) + (y1.x + y1.y);
;                         ys += dpp_f(ys, 0);
;                         if ((lane & 1) == 0) yb[s * 64 + srow] = ys;
	ds_read_b64 v[120:121], v233 offset:25088
	v_pk_mul_f32 v[216:217], v[88:89], v[212:213] op_sel_hi:[1,0] neg_lo:[0,1] neg_hi:[0,1]
	v_pk_mul_f32 v[218:219], v[90:91], v[212:213] op_sel_hi:[1,0] neg_lo:[0,1] neg_hi:[0,1]
	v_pk_mul_f32 v[220:221], v[88:89], v[212:213] op_sel:[0,1] op_sel_hi:[1,1] neg_lo:[0,1] neg_hi:[0,1]
	v_pk_mul_f32 v[222:223], v[90:91], v[212:213] op_sel:[0,1] op_sel_hi:[1,1] neg_lo:[0,1] neg_hi:[0,1]
	v_pk_fma_f32 v[216:217], v[104:105], v[122:123], v[216:217] op_sel_hi:[1,0,1]
	v_pk_fma_f32 v[218:219], v[106:107], v[122:123], v[218:219] op_sel_hi:[1,0,1]
	v_pk_fma_f32 v[220:221], v[104:105], v[122:123], v[220:221] op_sel:[0,1,0] op_sel_hi:[1,1,1]
	v_pk_fma_f32 v[222:223], v[106:107], v[122:123], v[222:223] op_sel:[0,1,0] op_sel_hi:[1,1,1]
	v_pk_fma_f32 v[0:1], v[0:1], v[180:181], v[216:217]
	v_pk_fma_f32 v[2:3], v[2:3], v[182:183], v[218:219]
	v_pk_fma_f32 v[16:17], v[16:17], v[180:181], v[220:221]
	v_pk_fma_f32 v[18:19], v[18:19], v[182:183], v[222:223]
	ds_read_b128 v[88:91], v232 offset:25856
	ds_read_b128 v[104:107], v232 offset:24832
	ds_read_b128 v[180:183], v232 offset:25344
	v_pk_mul_f32 v[224:225], v[92:93], v[212:213] op_sel_hi:[1,0] neg_lo:[0,1] neg_hi:[0,1]
	v_pk_mul_f32 v[226:227], v[94:95], v[212:213] op_sel_hi:[1,0] neg_lo:[0,1] neg_hi:[0,1]
	v_pk_mul_f32 v[228:229], v[92:93], v[212:213] op_sel:[0,1] op_sel_hi:[1,1] neg_lo:[0,1] neg_hi:[0,1]
	v_pk_mul_f32 v[230:231], v[94:95], v[212:213] op_sel:[0,1] op_sel_hi:[1,1] neg_lo:[0,1] neg_hi:[0,1]
	v_pk_fma_f32 v[224:225], v[108:109], v[122:123], v[224:225] op_sel_hi:[1,0,1]
	v_pk_fma_f32 v[226:227], v[110:111], v[122:123], v[226:227] op_sel_hi:[1,0,1]
	v_pk_fma_f32 v[228:229], v[108:109], v[122:123], v[228:229] op_sel:[0,1,0] op_sel_hi:[1,1,1]
	v_pk_fma_f32 v[230:231], v[110:111], v[122:123], v[230:231] op_sel:[0,1,0] op_sel_hi:[1,1,1]
	v_pk_fma_f32 v[4:5], v[4:5], v[184:185], v[224:225]
	v_pk_fma_f32 v[6:7], v[6:7], v[186:187], v[226:227]
	v_pk_fma_f32 v[20:21], v[20:21], v[184:185], v[228:229]
	v_pk_fma_f32 v[22:23], v[22:23], v[186:187], v[230:231]
	ds_read_b128 v[92:95], v232 offset:25872
	ds_read_b128 v[108:111], v232 offset:24848
	ds_read_b128 v[184:187], v232 offset:25360
	v_pk_mul_f32 v[216:217], v[96:97], v[212:213] op_sel_hi:[1,0] neg_lo:[0,1] neg_hi:[0,1]
	v_pk_mul_f32 v[218:219], v[98:99], v[212:213] op_sel_hi:[1,0] neg_lo:[0,1] neg_hi:[0,1]
	v_pk_mul_f32 v[220:221], v[96:97], v[212:213] op_sel:[0,1] op_sel_hi:[1,1] neg_lo:[0,1] neg_hi:[0,1]
	v_pk_mul_f32 v[222:223], v[98:99], v[212:213] op_sel:[0,1] op_sel_hi:[1,1] neg_lo:[0,1] neg_hi:[0,1]
	v_pk_fma_f32 v[216:217], v[112:113], v[122:123], v[216:217] op_sel_hi:[1,0,1]
	v_pk_fma_f32 v[218:219], v[114:115], v[122:123], v[218:219] op_sel_hi:[1,0,1]
	v_pk_fma_f32 v[220:221], v[112:113], v[122:123], v[220:221] op_sel:[0,1,0] op_sel_hi:[1,1,1]
	v_pk_fma_f32 v[222:223], v[114:115], v[122:123], v[222:223] op_sel:[0,1,0] op_sel_hi:[1,1,1]
	v_pk_fma_f32 v[8:9], v[8:9], v[188:189], v[216:217]
	v_pk_fma_f32 v[10:11], v[10:11], v[190:191], v[218:219]
	v_pk_fma_f32 v[24:25], v[24:25], v[188:189], v[220:221]
	v_pk_fma_f32 v[26:27], v[26:27], v[190:191], v[222:223]
	ds_read_b128 v[96:99], v232 offset:25888
	ds_read_b128 v[112:115], v232 offset:24864
	ds_read_b128 v[188:191], v232 offset:25376
	v_pk_mul_f32 v[224:225], v[100:101], v[212:213] op_sel_hi:[1,0] neg_lo:[0,1] neg_hi:[0,1]
	v_pk_mul_f32 v[226:227], v[102:103], v[212:213] op_sel_hi:[1,0] neg_lo:[0,1] neg_hi:[0,1]
	v_pk_mul_f32 v[228:229], v[100:101], v[212:213] op_sel:[0,1] op_sel_hi:[1,1] neg_lo:[0,1] neg_hi:[0,1]
	v_pk_mul_f32 v[230:231], v[102:103], v[212:213] op_sel:[0,1] op_sel_hi:[1,1] neg_lo:[0,1] neg_hi:[0,1]
	v_pk_fma_f32 v[224:225], v[116:117], v[122:123], v[224:225] op_sel_hi:[1,0,1]
	v_pk_fma_f32 v[226:227], v[118:119], v[122:123], v[226:227] op_sel_hi:[1,0,1]
	v_pk_fma_f32 v[228:229], v[116:117], v[122:123], v[228:229] op_sel:[0,1,0] op_sel_hi:[1,1,1]
	v_pk_fma_f32 v[230:231], v[118:119], v[122:123], v[230:231] op_sel:[0,1,0] op_sel_hi:[1,1,1]
	v_pk_fma_f32 v[12:13], v[12:13], v[192:193], v[224:225]
	v_pk_fma_f32 v[14:15], v[14:15], v[194:195], v[226:227]
	v_pk_fma_f32 v[28:29], v[28:29], v[192:193], v[228:229]
	v_pk_fma_f32 v[30:31], v[30:31], v[194:195], v[230:231]
	ds_read_b128 v[100:103], v232 offset:25904
	ds_read_b128 v[116:119], v232 offset:24880
	ds_read_b128 v[192:195], v232 offset:25392
	s_waitcnt lgkmcnt(13)
	v_pk_mul_f32 v[204:205], v[0:1], v[48:49]
	v_pk_mul_f32 v[208:209], v[16:17], v[48:49]
	s_nop 1
	v_pk_fma_f32 v[204:205], v[2:3], v[50:51], v[204:205]
	v_pk_fma_f32 v[208:209], v[18:19], v[50:51], v[208:209]
	s_nop 1
	v_pk_fma_f32 v[204:205], v[4:5], v[52:53], v[204:205]
	v_pk_fma_f32 v[208:209], v[20:21], v[52:53], v[208:209]
	s_nop 1
	v_pk_fma_f32 v[204:205], v[6:7], v[54:55], v[204:205]
	v_pk_fma_f32 v[208:209], v[22:23], v[54:55], v[208:209]
	s_nop 1
	v_pk_fma_f32 v[204:205], v[8:9], v[56:57], v[204:205]
	v_pk_fma_f32 v[208:209], v[24:25], v[56:57], v[208:209]
	s_nop 1
	v_pk_fma_f32 v[204:205], v[10:11], v[58:59], v[204:205]
	v_pk_fma_f32 v[208:209], v[26:27], v[58:59], v[208:209]
	s_nop 1
	v_pk_fma_f32 v[204:205], v[12:13], v[60:61], v[204:205]
	v_pk_fma_f32 v[208:209], v[28:29], v[60:61], v[208:209]
	s_nop 1
	v_pk_fma_f32 v[204:205], v[14:15], v[62:63], v[204:205]
	v_pk_fma_f32 v[208:209], v[30:31], v[62:63], v[208:209]
	s_nop 1
	s_nop 0
	v_add_f32_e32 v214, v204, v205
	v_add_f32_e32 v215, v208, v209
	s_nop 1
	v_add_f32_dpp v214, v214, v214 quad_perm:[1,0,3,2] row_mask:0xf bank_mask:0xf
	v_add_f32_dpp v215, v215, v215 quad_perm:[1,0,3,2] row_mask:0xf bank_mask:0xf
	s_nop 1
	v_add_f32_dpp v214, v214, v214 quad_perm:[2,3,0,1] row_mask:0xf bank_mask:0xf
	v_add_f32_dpp v215, v215, v215 quad_perm:[2,3,0,1] row_mask:0xf bank_mask:0xf
	s_nop 0
	ds_write_b64 v234, v[214:215] offset:3840
